# attnC: conversion and row sums of the second key block deferred into the next S phase; LDS fragment prefetch extended to mixer-A / GLA MFMA segments (on top of v49)
# speedup vs baseline: 1.0030x; 1.0030x over previous
.LBB0_435:
	s_cmp_lt_i32 s8, s74
	s_cselect_b64 vcc, -1, 0
	s_and_b64 s[12:13], vcc, exec
	s_cselect_b32 s2, s2, s3
	s_and_b32 s69, s8, 1
	s_mul_i32 s33, s69, 0x1200
	v_lshl_add_u32 v8, s33, 1, v133
	ds_read_b128 a[80:83], v8
	ds_read_b128 a[84:87], v8 offset:32
	ds_read_b128 a[88:91], v8 offset:4704
	ds_read_b128 a[92:95], v8 offset:64
	s_and_b64 s[12:13], s[62:63], vcc
	s_lshl_b32 s2, s2, 6
	s_waitcnt vmcnt(7)
	s_waitcnt lgkmcnt(3)
	v_mfma_f32_32x32x16_bf16 a[32:47], a[80:83], v[64:67], a[64:79]
	s_andn2_b64 vcc, exec, s[12:13]
	v_subrev_u32_e32 v153, s2, v131
	s_waitcnt vmcnt(3)
	v_mfma_f32_32x32x16_bf16 a[0:15], a[80:83], v[80:83], a[64:79]
	ds_read_b128 a[80:83], v8 offset:96
	s_waitcnt lgkmcnt(3)
	v_mfma_f32_32x32x16_bf16 a[32:47], a[84:87], v[68:71], a[32:47]
	s_waitcnt vmcnt(2)
	v_mfma_f32_32x32x16_bf16 a[0:15], a[84:87], v[84:87], a[0:15]
	ds_read_b128 a[84:87], v8 offset:4608
	s_waitcnt lgkmcnt(2)
	v_mfma_f32_32x32x16_bf16 a[32:47], a[92:95], v[72:75], a[32:47]
	s_waitcnt vmcnt(1)
	v_mfma_f32_32x32x16_bf16 a[0:15], a[92:95], v[88:91], a[0:15]
	ds_read_b128 a[92:95], v8 offset:4640
	s_waitcnt lgkmcnt(2)
	v_mfma_f32_32x32x16_bf16 a[32:47], a[80:83], v[76:79], a[32:47]
	s_waitcnt vmcnt(0)
	v_mfma_f32_32x32x16_bf16 a[0:15], a[80:83], v[92:95], a[0:15]
	ds_read_b128 a[80:83], v8 offset:4672
	s_waitcnt lgkmcnt(2)
	v_mfma_f32_32x32x16_bf16 a[48:63], a[84:87], v[64:67], a[64:79]
	v_mfma_f32_32x32x16_bf16 a[16:31], a[84:87], v[80:83], a[64:79]
	s_waitcnt lgkmcnt(1)
	v_mfma_f32_32x32x16_bf16 a[48:63], a[92:95], v[68:71], a[48:63]
	v_mfma_f32_32x32x16_bf16 a[16:31], a[92:95], v[84:87], a[16:31]
	s_waitcnt lgkmcnt(0)
	v_mfma_f32_32x32x16_bf16 a[48:63], a[80:83], v[72:75], a[48:63]
	v_mfma_f32_32x32x16_bf16 a[16:31], a[80:83], v[88:91], a[16:31]
	s_waitcnt lgkmcnt(5)
	v_mfma_f32_32x32x16_bf16 a[48:63], a[88:91], v[76:79], a[48:63]
	v_mfma_f32_32x32x16_bf16 a[16:31], a[88:91], v[92:95], a[16:31]
	v_cndmask_b32_e64 v32, 0, 1, s[12:13]
	v_cmp_ne_u32_e64 s[8:9], 1, v32
	s_cbranch_vccnz .LBB0_437
	v_add_u32_e32 v32, v153, v159
	v_accvgpr_read_b32 v16, a32
	v_cmp_lt_u32_e32 vcc, s83, v32
	v_add_u32_e32 v32, v153, v161
	v_accvgpr_read_b32 v17, a33
	v_cndmask_b32_e32 v16, v184, v16, vcc
	v_cmp_lt_u32_e32 vcc, s83, v32
	v_add_u32_e32 v32, v153, v163
	v_accvgpr_read_b32 v18, a34
	v_cndmask_b32_e32 v17, v184, v17, vcc
	v_cmp_lt_u32_e32 vcc, s83, v32
	v_add_u32_e32 v32, v153, v187
	v_accvgpr_read_b32 v19, a35
	v_cndmask_b32_e32 v18, v184, v18, vcc
	v_cmp_lt_u32_e32 vcc, s83, v32
	v_add_u32_e32 v32, v153, v188
	v_accvgpr_read_b32 v20, a36
	v_cndmask_b32_e32 v19, v184, v19, vcc
	v_cmp_lt_u32_e32 vcc, s83, v32
	v_add_u32_e32 v32, v153, v189
	v_accvgpr_read_b32 v21, a37
	v_cndmask_b32_e32 v20, v184, v20, vcc
	v_cmp_lt_u32_e32 vcc, s83, v32
	v_add_u32_e32 v32, v153, v190
	v_accvgpr_read_b32 v22, a38
	v_cndmask_b32_e32 v21, v184, v21, vcc
	v_cmp_lt_u32_e32 vcc, s83, v32
	v_add_u32_e32 v32, v153, v191
	s_or_b32 s3, s2, 16
	v_cndmask_b32_e32 v22, v184, v22, vcc
	v_cmp_lt_u32_e32 vcc, s83, v32
	v_subrev_u32_e32 v32, s3, v131
	v_accvgpr_read_b32 v23, a39
	v_add_u32_e32 v33, v32, v159
	v_accvgpr_read_b32 v24, a40
	v_cndmask_b32_e32 v23, v184, v23, vcc
	v_cmp_lt_u32_e32 vcc, s83, v33
	v_add_u32_e32 v33, v32, v161
	v_accvgpr_read_b32 v25, a41
	v_cndmask_b32_e32 v24, v184, v24, vcc
	v_cmp_lt_u32_e32 vcc, s83, v33
	v_add_u32_e32 v33, v32, v163
	v_accvgpr_read_b32 v26, a42
	v_cndmask_b32_e32 v25, v184, v25, vcc
	v_cmp_lt_u32_e32 vcc, s83, v33
	v_add_u32_e32 v33, v32, v187
	v_accvgpr_read_b32 v27, a43
	v_cndmask_b32_e32 v26, v184, v26, vcc
	v_cmp_lt_u32_e32 vcc, s83, v33
	v_add_u32_e32 v33, v32, v188
	v_accvgpr_read_b32 v28, a44
	v_cndmask_b32_e32 v27, v184, v27, vcc
	v_cmp_lt_u32_e32 vcc, s83, v33
	v_add_u32_e32 v33, v32, v189
	v_accvgpr_read_b32 v29, a45
	v_cndmask_b32_e32 v28, v184, v28, vcc
	v_cmp_lt_u32_e32 vcc, s83, v33
	v_add_u32_e32 v33, v32, v190
	s_or_b32 s3, s2, 32
	v_accvgpr_read_b32 v30, a46
	v_accvgpr_read_b32 v31, a47
	v_cndmask_b32_e32 v29, v184, v29, vcc
	v_cmp_lt_u32_e32 vcc, s83, v33
	v_add_u32_e32 v32, v32, v191
	v_accvgpr_write_b32 a32, v16
	v_subrev_u32_e32 v16, s3, v131
	v_cndmask_b32_e32 v30, v184, v30, vcc
	v_cmp_lt_u32_e32 vcc, s83, v32
	v_accvgpr_write_b32 a33, v17
	v_add_u32_e32 v17, v16, v159
	v_accvgpr_read_b32 v0, a48
	v_cndmask_b32_e32 v31, v184, v31, vcc
	v_cmp_lt_u32_e32 vcc, s83, v17
	v_add_u32_e32 v17, v16, v161
	v_accvgpr_read_b32 v1, a49
	v_cndmask_b32_e32 v0, v184, v0, vcc
	v_cmp_lt_u32_e32 vcc, s83, v17
	v_add_u32_e32 v17, v16, v163
	v_accvgpr_read_b32 v2, a50
	v_cndmask_b32_e32 v1, v184, v1, vcc
	v_cmp_lt_u32_e32 vcc, s83, v17
	v_add_u32_e32 v17, v16, v187
	v_accvgpr_read_b32 v3, a51
	v_cndmask_b32_e32 v2, v184, v2, vcc
	v_cmp_lt_u32_e32 vcc, s83, v17
	v_add_u32_e32 v17, v16, v188
	v_accvgpr_read_b32 v4, a52
	v_cndmask_b32_e32 v3, v184, v3, vcc
	v_cmp_lt_u32_e32 vcc, s83, v17
	v_add_u32_e32 v17, v16, v189
	v_accvgpr_read_b32 v5, a53
	v_cndmask_b32_e32 v4, v184, v4, vcc
	v_cmp_lt_u32_e32 vcc, s83, v17
	v_add_u32_e32 v17, v16, v190
	v_accvgpr_read_b32 v6, a54
	v_cndmask_b32_e32 v5, v184, v5, vcc
	v_cmp_lt_u32_e32 vcc, s83, v17
	v_add_u32_e32 v16, v16, v191
	s_or_b32 s3, s2, 48
	v_cndmask_b32_e32 v6, v184, v6, vcc
	v_cmp_lt_u32_e32 vcc, s83, v16
	v_subrev_u32_e32 v16, s3, v131
	v_accvgpr_read_b32 v7, a55
	v_add_u32_e32 v17, v16, v159
	v_accvgpr_read_b32 v8, a56
	v_cndmask_b32_e32 v7, v184, v7, vcc
	v_cmp_lt_u32_e32 vcc, s83, v17
	v_add_u32_e32 v17, v16, v161
	v_accvgpr_read_b32 v9, a57
	v_cndmask_b32_e32 v8, v184, v8, vcc
	v_cmp_lt_u32_e32 vcc, s83, v17
	v_add_u32_e32 v17, v16, v163
	v_accvgpr_read_b32 v10, a58
	v_cndmask_b32_e32 v9, v184, v9, vcc
	v_cmp_lt_u32_e32 vcc, s83, v17
	v_add_u32_e32 v17, v16, v187
	v_accvgpr_read_b32 v11, a59
	v_cndmask_b32_e32 v10, v184, v10, vcc
	v_cmp_lt_u32_e32 vcc, s83, v17
	v_add_u32_e32 v17, v16, v188
	v_accvgpr_read_b32 v12, a60
	v_cndmask_b32_e32 v11, v184, v11, vcc
	v_cmp_lt_u32_e32 vcc, s83, v17
	v_add_u32_e32 v17, v16, v189
	v_accvgpr_read_b32 v13, a61
	v_cndmask_b32_e32 v12, v184, v12, vcc
	v_cmp_lt_u32_e32 vcc, s83, v17
	v_add_u32_e32 v17, v16, v190
	v_accvgpr_read_b32 v14, a62
	v_cndmask_b32_e32 v13, v184, v13, vcc
	v_cmp_lt_u32_e32 vcc, s83, v17
	v_add_u32_e32 v16, v16, v191
	v_accvgpr_read_b32 v15, a63
	v_cndmask_b32_e32 v14, v184, v14, vcc
	v_cmp_lt_u32_e32 vcc, s83, v16
	v_accvgpr_write_b32 a34, v18
	v_accvgpr_write_b32 a35, v19
	v_cndmask_b32_e32 v15, v184, v15, vcc
	v_accvgpr_write_b32 a36, v20
	v_accvgpr_write_b32 a37, v21
	v_accvgpr_write_b32 a38, v22
	v_accvgpr_write_b32 a39, v23
	v_accvgpr_write_b32 a40, v24
	v_accvgpr_write_b32 a41, v25
	v_accvgpr_write_b32 a42, v26
	v_accvgpr_write_b32 a43, v27
	v_accvgpr_write_b32 a44, v28
	v_accvgpr_write_b32 a45, v29
	v_accvgpr_write_b32 a46, v30
	v_accvgpr_write_b32 a47, v31
	v_accvgpr_write_b32 a48, v0
	v_accvgpr_write_b32 a49, v1
	v_accvgpr_write_b32 a50, v2
	v_accvgpr_write_b32 a51, v3
	v_accvgpr_write_b32 a52, v4
	v_accvgpr_write_b32 a53, v5
	v_accvgpr_write_b32 a54, v6
	v_accvgpr_write_b32 a55, v7
	v_accvgpr_write_b32 a56, v8
	v_accvgpr_write_b32 a57, v9
	v_accvgpr_write_b32 a58, v10
	v_accvgpr_write_b32 a59, v11
	v_accvgpr_write_b32 a60, v12
	v_accvgpr_write_b32 a61, v13
	v_accvgpr_write_b32 a62, v14
	v_accvgpr_write_b32 a63, v15

.LBB0_441:
	v_exp_f32_e32 v48, v48
	v_exp_f32_e32 v49, v49
	v_exp_f32_e32 v50, v50
	v_exp_f32_e32 v51, v51
	v_exp_f32_e32 v52, v52
	v_exp_f32_e32 v53, v53
	v_exp_f32_e32 v54, v54
	v_exp_f32_e32 v55, v55
	v_exp_f32_e32 v16, v16
	v_exp_f32_e32 v17, v17
	v_exp_f32_e32 v18, v18
	v_exp_f32_e32 v19, v19
	v_exp_f32_e32 v20, v20
	v_exp_f32_e32 v21, v21
	v_exp_f32_e32 v22, v22
	v_exp_f32_e32 v23, v23
	v_lshl_add_u32 v153, s33, 1, v166
	ds_read_b128 a[80:83], v153 offset:18432
	ds_read_b128 a[84:87], v153 offset:18464
	ds_read_b128 a[88:91], v153 offset:18496
	ds_read_b128 a[92:95], v153 offset:18528
	v_cvt_pk_bf16_f32 v138, v48, v49
	v_cvt_pk_bf16_f32 v139, v50, v51
	v_cvt_pk_bf16_f32 v140, v52, v53
	v_cvt_pk_bf16_f32 v141, v54, v55
	v_cvt_pk_bf16_f32 v110, v16, v17
	v_cvt_pk_bf16_f32 v111, v18, v19
	v_cvt_pk_bf16_f32 v112, v20, v21
	v_cvt_pk_bf16_f32 v113, v22, v23
	v_accvgpr_write_b32 a16, v128
	v_accvgpr_write_b32 a17, v132
	v_accvgpr_write_b32 a18, v183
	v_accvgpr_write_b32 a19, v182
	v_accvgpr_write_b32 a20, v179
	v_accvgpr_write_b32 a21, v178
	v_accvgpr_write_b32 a22, v181
	v_accvgpr_write_b32 a23, v180
	v_accvgpr_write_b32 a24, v149
	v_accvgpr_write_b32 a25, v254
	v_accvgpr_write_b32 a26, v253
	v_accvgpr_write_b32 a27, v252
	v_accvgpr_write_b32 a28, v251
	v_accvgpr_write_b32 a29, v250
	v_accvgpr_write_b32 a30, v249
	v_accvgpr_write_b32 a31, v248
	v_accvgpr_write_b32 a0, v247
	v_accvgpr_write_b32 a1, v246
	v_accvgpr_write_b32 a2, v245
	v_accvgpr_write_b32 a3, v244
	v_accvgpr_write_b32 a4, v243
	v_accvgpr_write_b32 a5, v242
	v_accvgpr_write_b32 a6, v241
	v_accvgpr_write_b32 a7, v240
	v_accvgpr_write_b32 a8, v239
	v_accvgpr_write_b32 a9, v238
	v_accvgpr_write_b32 a10, v237
	v_accvgpr_write_b32 a11, v236
	v_accvgpr_write_b32 a12, v235
	v_accvgpr_write_b32 a13, v234
	v_accvgpr_write_b32 a14, v233
	v_accvgpr_write_b32 a15, v232
	s_waitcnt lgkmcnt(3)
	v_mfma_f32_32x32x16_bf16 a[16:31], a[80:83], v[110:113], a[16:31]
	v_exp_f32_e32 v56, v56
	v_exp_f32_e32 v57, v57
	v_exp_f32_e32 v58, v58
	v_exp_f32_e32 v59, v59
	v_exp_f32_e32 v60, v60
	v_exp_f32_e32 v61, v61
	v_exp_f32_e32 v62, v62
	v_mfma_f32_32x32x16_bf16 a[0:15], a[80:83], v[138:141], a[0:15]
	ds_read_b128 a[80:83], v153 offset:23040
	v_exp_f32_e32 v63, v63
	v_exp_f32_e32 v24, v24
	v_exp_f32_e32 v25, v25
	v_exp_f32_e32 v26, v26
	v_exp_f32_e32 v27, v27
	v_exp_f32_e32 v28, v28
	v_exp_f32_e32 v29, v29
	v_exp_f32_e32 v30, v30
	v_exp_f32_e32 v31, v31
	v_cvt_pk_bf16_f32 v102, v56, v57
	v_cvt_pk_bf16_f32 v103, v58, v59
	v_cvt_pk_bf16_f32 v104, v60, v61
	v_cvt_pk_bf16_f32 v105, v62, v63
	v_cvt_pk_bf16_f32 v114, v24, v25
	v_cvt_pk_bf16_f32 v115, v26, v27
	v_cvt_pk_bf16_f32 v116, v28, v29
	v_cvt_pk_bf16_f32 v117, v30, v31
	s_waitcnt lgkmcnt(3)
	v_mfma_f32_32x32x16_bf16 a[16:31], a[84:87], v[114:117], a[16:31]
	v_exp_f32_e32 v32, v32
	v_exp_f32_e32 v33, v33
	v_exp_f32_e32 v34, v34
	v_exp_f32_e32 v35, v35
	v_exp_f32_e32 v36, v36
	v_exp_f32_e32 v37, v37
	v_exp_f32_e32 v38, v38
	v_mfma_f32_32x32x16_bf16 a[0:15], a[84:87], v[102:105], a[0:15]
	ds_read_b128 a[84:87], v153 offset:23072
	v_exp_f32_e32 v39, v39
	v_exp_f32_e32 v0, v0
	v_exp_f32_e32 v1, v1
	v_exp_f32_e32 v2, v2
	v_exp_f32_e32 v3, v3
	v_exp_f32_e32 v4, v4
	v_exp_f32_e32 v5, v5
	v_exp_f32_e32 v6, v6
	v_exp_f32_e32 v7, v7
	v_cvt_pk_bf16_f32 v106, v32, v33
	v_cvt_pk_bf16_f32 v107, v34, v35
	v_cvt_pk_bf16_f32 v118, v0, v1
	v_cvt_pk_bf16_f32 v119, v2, v3
	v_cvt_pk_bf16_f32 v120, v4, v5
	v_cvt_pk_bf16_f32 v121, v6, v7
	v_cvt_pk_bf16_f32 v108, v36, v37
	v_cvt_pk_bf16_f32 v109, v38, v39
	s_waitcnt lgkmcnt(3)
	v_mfma_f32_32x32x16_bf16 a[16:31], a[88:91], v[118:121], a[16:31]
	v_exp_f32_e32 v40, v40
	v_exp_f32_e32 v41, v41
	v_exp_f32_e32 v42, v42
	v_exp_f32_e32 v43, v43
	v_exp_f32_e32 v44, v44
	v_exp_f32_e32 v8, v8
	v_exp_f32_e32 v9, v9
	v_mfma_f32_32x32x16_bf16 a[0:15], a[88:91], v[106:109], a[0:15]
	ds_read_b128 a[88:91], v153 offset:23136
	v_exp_f32_e32 v10, v10
	v_exp_f32_e32 v11, v11
	v_exp_f32_e32 v12, v12
	v_exp_f32_e32 v13, v13
	v_exp_f32_e32 v14, v14
	v_exp_f32_e32 v15, v15
	v_exp_f32_e32 v45, v45
	v_exp_f32_e32 v46, v46
	v_exp_f32_e32 v47, v47
	v_cvt_pk_bf16_f32 v178, v8, v9
	v_cvt_pk_bf16_f32 v179, v10, v11
	v_cvt_pk_bf16_f32 v180, v12, v13
	v_cvt_pk_bf16_f32 v181, v14, v15
	v_cvt_pk_bf16_f32 v236, v40, v41
	v_cvt_pk_bf16_f32 v237, v42, v43
	v_cvt_pk_bf16_f32 v238, v44, v45
	v_cvt_pk_bf16_f32 v239, v46, v47
	s_waitcnt lgkmcnt(3)
	v_mfma_f32_32x32x16_bf16 a[16:31], a[92:95], v[178:181], a[16:31]
	v_accvgpr_write_b32 a48, v231
	v_accvgpr_write_b32 a49, v230
	v_accvgpr_write_b32 a50, v229
	v_accvgpr_write_b32 a51, v228
	v_accvgpr_write_b32 a52, v227
	v_accvgpr_write_b32 a53, v226
	v_accvgpr_write_b32 a54, v225
	v_mfma_f32_32x32x16_bf16 a[0:15], a[92:95], v[236:239], a[0:15]
	v_accvgpr_write_b32 a55, v224
	v_accvgpr_write_b32 a56, v223
	v_accvgpr_write_b32 a57, v222
	v_accvgpr_write_b32 a58, v221
	v_accvgpr_write_b32 a59, v220
	v_accvgpr_write_b32 a60, v219
	v_accvgpr_write_b32 a61, v218
	v_accvgpr_write_b32 a62, v217
	v_accvgpr_write_b32 a63, v216
	v_accvgpr_write_b32 a32, v215
	v_accvgpr_write_b32 a33, v214
	v_accvgpr_write_b32 a34, v213
	v_accvgpr_write_b32 a35, v212
	v_accvgpr_write_b32 a36, v211
	v_accvgpr_write_b32 a37, v210
	v_accvgpr_write_b32 a38, v209
	v_accvgpr_write_b32 a39, v208
	v_accvgpr_write_b32 a40, v207
	v_accvgpr_write_b32 a41, v206
	v_accvgpr_write_b32 a42, v205
	v_accvgpr_write_b32 a43, v204
	v_accvgpr_write_b32 a44, v203
	v_accvgpr_write_b32 a45, v202
	v_accvgpr_write_b32 a46, v201
	v_accvgpr_write_b32 a47, v200
	s_waitcnt lgkmcnt(2)
	v_mfma_f32_32x32x16_bf16 a[48:63], a[80:83], v[110:113], a[48:63]
	s_and_b64 vcc, exec, s[8:9]
	s_mov_b64 s[8:9], -1
	v_mfma_f32_32x32x16_bf16 a[32:47], a[80:83], v[138:141], a[32:47]
	s_waitcnt lgkmcnt(1)
	v_mfma_f32_32x32x16_bf16 a[48:63], a[84:87], v[114:117], a[48:63]
	v_mfma_f32_32x32x16_bf16 a[32:47], a[84:87], v[102:105], a[32:47]
	ds_read_b128 v[102:105], v153 offset:23104
	s_waitcnt lgkmcnt(0)
	v_mfma_f32_32x32x16_bf16 a[48:63], v[102:105], v[118:121], a[48:63]
	v_mfma_f32_32x32x16_bf16 a[32:47], v[102:105], v[106:109], a[32:47]
	s_waitcnt lgkmcnt(1)
	v_mfma_f32_32x32x16_bf16 a[48:63], a[88:91], v[178:181], a[48:63]
	v_mfma_f32_32x32x16_bf16 a[32:47], a[88:91], v[236:239], a[32:47]
	s_cbranch_vccnz .LBB0_443
	v_add3_u32 v102, s70, v185, v154
	s_waitcnt vmcnt(1)
	ds_write_b128 v102, a[124:127] offset:18432
	v_add3_u32 v102, s70, v186, v154
	s_mov_b64 s[8:9], 0
	s_waitcnt vmcnt(0)
	ds_write_b128 v102, a[128:131] offset:18432

.LBB0_453:
	s_or_b64 exec, exec, s[62:63]
	s_waitcnt lgkmcnt(0)
	s_barrier
	ds_read_b128 a[32:35], v168 offset:43520
	ds_read_b128 a[36:39], v168 offset:43552
	ds_read_b128 a[40:43], v177
	ds_read_b128 a[44:47], v177 offset:4608
	ds_read_b128 v[52:55], v177 offset:32
	s_waitcnt lgkmcnt(2)
	v_mfma_f32_32x32x16_bf16 a[16:31], a[32:35], a[40:43], 0
	ds_read_b128 a[40:43], v177 offset:4640
	s_lshl_b32 s10, s69, 13
	s_movk_i32 s2, 0x3000
	s_mov_b32 s69, 1
	s_mov_b64 s[62:63], 0
	s_waitcnt lgkmcnt(2)
	v_mfma_f32_32x32x16_bf16 a[0:15], a[32:35], a[44:47], 0
	ds_read_b128 a[32:35], v168 offset:43584
	ds_read_b128 a[44:47], v177 offset:64
	s_waitcnt lgkmcnt(3)
	v_mfma_f32_32x32x16_bf16 a[16:31], a[36:39], v[52:55], a[16:31]
	s_waitcnt lgkmcnt(2)
	v_mfma_f32_32x32x16_bf16 a[0:15], a[36:39], a[40:43], a[0:15]
	ds_read_b128 a[36:39], v177 offset:4672
	ds_read_b128 a[40:43], v168 offset:43616
	s_waitcnt lgkmcnt(2)
	v_mfma_f32_32x32x16_bf16 a[16:31], a[32:35], a[44:47], a[16:31]
	ds_read_b128 a[44:47], v177 offset:96
	s_waitcnt lgkmcnt(2)
	v_mfma_f32_32x32x16_bf16 a[0:15], a[32:35], a[36:39], a[0:15]
	ds_read_b128 a[32:35], v177 offset:4704
	s_waitcnt lgkmcnt(1)
	v_mfma_f32_32x32x16_bf16 a[16:31], a[40:43], a[44:47], a[16:31]
	s_waitcnt lgkmcnt(0)
	v_mfma_f32_32x32x16_bf16 a[0:15], a[40:43], a[32:35], a[0:15]
	v_lshl_add_u64 v[36:37], s[10:11], 2, v[32:33]
	v_add_co_u32_e32 v38, vcc, s82, v36
	s_nop 6
	global_store_dword v[36:37], a16, off
	global_store_dword v[36:37], a17, off offset:512
	global_store_dword v[36:37], a18, off offset:1024
	global_store_dword v[36:37], a19, off offset:1536
	v_addc_co_u32_e32 v39, vcc, 0, v37, vcc
	v_add_co_u32_e32 v40, vcc, s80, v36
	s_nop 1
	v_addc_co_u32_e32 v41, vcc, 0, v37, vcc
	v_add_co_u32_e32 v42, vcc, s2, v36
	global_store_dword v[40:41], a20, off offset:-4096
	global_store_dword v[38:39], a21, off offset:512
	global_store_dword v[38:39], a22, off offset:1024
	global_store_dword v[38:39], a23, off offset:1536
	global_store_dword v[40:41], a24, off
	global_store_dword v[40:41], a25, off offset:512
	global_store_dword v[40:41], a26, off offset:1024
	global_store_dword v[40:41], a27, off offset:1536
	v_addc_co_u32_e32 v43, vcc, 0, v37, vcc
	s_and_b64 vcc, exec, s[8:9]
	global_store_dword v[42:43], a28, off
	global_store_dword v[42:43], a29, off offset:512
	global_store_dword v[42:43], a30, off offset:1024
	global_store_dword v[42:43], a31, off offset:1536
	global_store_dword v[36:37], a0, off offset:128
	global_store_dword v[36:37], a1, off offset:640
	global_store_dword v[36:37], a2, off offset:1152
	global_store_dword v[36:37], a3, off offset:1664
	global_store_dword v[38:39], a4, off offset:128
	global_store_dword v[38:39], a5, off offset:640
	global_store_dword v[38:39], a6, off offset:1152
	global_store_dword v[38:39], a7, off offset:1664
	global_store_dword v[40:41], a8, off offset:128
	global_store_dword v[40:41], a9, off offset:640
	global_store_dword v[40:41], a10, off offset:1152
	global_store_dword v[40:41], a11, off offset:1664
	global_store_dword v[42:43], a12, off offset:128
	global_store_dword v[42:43], a13, off offset:640
	global_store_dword v[42:43], a14, off offset:1152
	global_store_dword v[42:43], a15, off offset:1664
	s_barrier
	s_cbranch_vccz .LBB0_449

.LBB0_591:
	s_or_b64 exec, exec, s[96:97]
	v_accvgpr_read_b32 v0, a124
	v_accvgpr_read_b32 v1, a125
	s_waitcnt lgkmcnt(0)
	s_barrier
	global_load_ushort v6, v[0:1], off
	v_accvgpr_read_b32 v0, a126
	v_accvgpr_read_b32 v1, a127
	global_load_ushort v7, v[0:1], off
	v_accvgpr_read_b32 v0, a128
	v_accvgpr_read_b32 v1, a129
	global_load_ushort v8, v[0:1], off
	v_accvgpr_read_b32 v0, a130
	v_accvgpr_read_b32 v1, a131
	global_load_ushort v9, v[0:1], off
	v_accvgpr_read_b32 v0, a134
	v_accvgpr_read_b32 v1, a135
	global_load_ushort v10, v[0:1], off
	global_load_ushort v11, v[188:189], off
	global_load_ushort v12, v[190:191], off
	global_load_ushort v13, v[192:193], off
	global_load_ushort v14, v[194:195], off
	global_load_ushort v15, v[196:197], off
	global_load_ushort v16, v[218:219], off
	v_accvgpr_read_b32 v218, a60
	v_accvgpr_read_b32 v219, a62
	v_accvgpr_read_b32 v243, a63
	v_accvgpr_read_b32 v244, a116
	ds_read_b32 v17, v218 offset:36096
	ds_read2_b32 v[0:1], v219 offset0:64 offset1:129
	ds_read2_b32 v[2:3], v243 offset0:66 offset1:131
	ds_read2_b32 v[4:5], v244 offset0:68 offset1:133
	global_load_ushort v18, v[214:215], off
	global_load_ushort v19, v[222:223], off
	global_load_ushort v20, v[224:225], off
	global_load_ushort v21, v[226:227], off
	global_load_ushort v22, v[228:229], off
	global_load_ushort v23, v[230:231], off
	global_load_ushort v24, v[232:233], off
	global_load_ushort v25, v[234:235], off
	global_load_ushort v26, v[236:237], off
	s_waitcnt lgkmcnt(3)
	v_mul_f32_e32 v28, 0x3fb8aa3b, v17
	s_waitcnt lgkmcnt(2)
	v_mul_f32_e32 v29, 0x3fb8aa3b, v0
	v_mul_f32_e32 v0, 0xbfb8aa3b, v0
	v_mul_f32_e32 v30, 0x3fb8aa3b, v1
	s_waitcnt lgkmcnt(1)
	v_mul_f32_e32 v31, 0x3fb8aa3b, v2
	v_mul_f32_e32 v17, 0xbfb8aa3b, v17
	v_mul_f32_e32 v1, 0xbfb8aa3b, v1
	v_mul_f32_e32 v2, 0xbfb8aa3b, v2
	v_exp_f32_e32 v28, v28
	v_exp_f32_e32 v29, v29
	v_exp_f32_e32 v0, v0
	v_exp_f32_e32 v30, v30
	v_exp_f32_e32 v31, v31
	v_exp_f32_e32 v17, v17
	v_exp_f32_e32 v1, v1
	v_exp_f32_e32 v2, v2
	v_accvgpr_read_b32 v242, a61
	v_accvgpr_read_b32 v95, a48
	v_accvgpr_read_b32 v97, a49
	v_accvgpr_read_b32 v99, a50
	v_accvgpr_read_b32 v101, a51
	ds_read_b32 v27, v242 offset:39736
	v_mul_f32_e32 v32, 0x3fb8aa3b, v3
	v_mul_f32_e32 v3, 0xbfb8aa3b, v3
	v_exp_f32_e32 v3, v3
	v_accvgpr_read_b32 v103, a52
	v_accvgpr_read_b32 v105, a53
	v_accvgpr_read_b32 v107, a54
	v_accvgpr_read_b32 v226, a117
	v_exp_f32_e32 v32, v32
	v_accvgpr_read_b32 v109, a55
	s_add_u32 s86, s90, s94
	s_addc_u32 s87, s91, s95
	v_mov_b32_e32 v111, v65
	v_mov_b32_e32 v119, v65
	v_mov_b32_e32 v121, v65
	v_mov_b32_e32 v123, v65
	v_mov_b32_e32 v125, v65
	v_mov_b32_e32 v127, v65
	v_mov_b32_e32 v135, v65
	v_mov_b32_e32 v137, v65
	v_mov_b32_e32 v139, v65
	v_mov_b32_e32 v141, v65
	v_mov_b32_e32 v143, v65
	v_mov_b32_e32 v145, v65
	v_mov_b32_e32 v147, v65
	v_mov_b32_e32 v151, v65
	v_mov_b32_e32 v153, v65
	v_mov_b32_e32 v155, v65
	v_mov_b32_e32 v157, v65
	v_mov_b32_e32 v159, v65
	v_mov_b32_e32 v161, v65
	v_mov_b32_e32 v163, v65
	v_mov_b32_e32 v165, v65
	v_mov_b32_e32 v167, v65
	v_mov_b32_e32 v169, v65
	v_mov_b32_e32 v171, v65
	v_mov_b32_e32 v173, v65
	s_waitcnt vmcnt(19)
	v_lshlrev_b32_e32 v6, 16, v6
	v_mul_f32_e32 v6, v28, v6
	v_cvt_pk_bf16_f32 v6, v6, s0
	s_waitcnt vmcnt(18)
	v_lshlrev_b32_e32 v7, 16, v7
	v_mul_f32_e32 v7, v17, v7
	v_cvt_pk_bf16_f32 v7, v7, s0
	s_waitcnt vmcnt(17)
	v_lshlrev_b32_e32 v8, 16, v8
	s_waitcnt vmcnt(15)
	v_lshlrev_b32_e32 v10, 16, v10
	s_waitcnt vmcnt(13)
	v_lshlrev_b32_e32 v12, 16, v12
	v_lshlrev_b32_e32 v9, 16, v9
	v_lshlrev_b32_e32 v11, 16, v11
	s_waitcnt vmcnt(12)
	v_lshlrev_b32_e32 v13, 16, v13
	v_mul_f32_e32 v8, v29, v8
	v_mul_f32_e32 v0, v0, v9
	v_mul_f32_e32 v9, v30, v10
	v_mul_f32_e32 v10, v31, v12
	v_mul_f32_e32 v1, v1, v11
	v_mul_f32_e32 v2, v2, v13
	v_cvt_pk_bf16_f32 v8, v8, s0
	v_cvt_pk_bf16_f32 v9, v9, s0
	v_cvt_pk_bf16_f32 v10, v10, s0
	v_cvt_pk_bf16_f32 v0, v0, s0
	v_cvt_pk_bf16_f32 v1, v1, s0
	v_cvt_pk_bf16_f32 v2, v2, s0
	ds_write_b16 v95, v6 offset:52736
	ds_write_b16 v95, v7 offset:61952
	ds_write_b16 v97, v8 offset:52736
	ds_write_b16 v97, v0 offset:61952
	ds_write_b16 v99, v9 offset:52736
	ds_write_b16 v99, v1 offset:61952
	ds_write_b16 v101, v10 offset:52736
	ds_write_b16 v101, v2 offset:61952
	global_load_ushort v2, v[198:199], off
	global_load_ushort v6, v[204:205], off
	global_load_ushort v7, v[206:207], off
	global_load_ushort v10, v[210:211], off
	s_waitcnt lgkmcnt(9)
	v_mul_f32_e32 v1, 0x3fb8aa3b, v4
	s_waitcnt vmcnt(14)
	v_lshlrev_b32_e32 v0, 16, v15
	v_exp_f32_e32 v1, v1
	v_mul_f32_e32 v0, v3, v0
	v_cvt_pk_bf16_f32 v0, v0, s0
	global_load_ushort v3, v[200:201], off
	ds_write_b16 v103, v0 offset:61952
	s_waitcnt vmcnt(14)
	v_lshlrev_b32_e32 v0, 16, v16
	v_mul_f32_e32 v0, v1, v0
	v_mul_f32_e32 v1, 0xbfb8aa3b, v4
	v_exp_f32_e32 v1, v1
	global_load_ushort v4, v[202:203], off
	v_cvt_pk_bf16_f32 v0, v0, s0
	ds_write_b16 v105, v0 offset:52736
	s_waitcnt vmcnt(14)
	v_lshlrev_b32_e32 v0, 16, v18
	v_mul_f32_e32 v0, v1, v0
	v_mul_f32_e32 v1, 0x3fb8aa3b, v5
	v_exp_f32_e32 v1, v1
	v_cvt_pk_bf16_f32 v0, v0, s0
	ds_write_b16 v105, v0 offset:61952
	s_waitcnt vmcnt(13)
	v_lshlrev_b32_e32 v0, 16, v19
	v_mul_f32_e32 v0, v1, v0
	v_cvt_pk_bf16_f32 v0, v0, s0
	v_mul_f32_e32 v1, 0xbfb8aa3b, v5
	v_exp_f32_e32 v5, v1
	ds_write_b16 v107, v0 offset:52736
	ds_read2_b32 v[0:1], v226 offset0:70 offset1:135
	s_waitcnt vmcnt(12)
	v_lshlrev_b32_e32 v8, 16, v20
	v_mul_f32_e32 v5, v5, v8
	global_load_ushort v8, v[208:209], off
	v_cvt_pk_bf16_f32 v5, v5, s0
	s_waitcnt lgkmcnt(0)
	v_mul_f32_e32 v9, 0x3fb8aa3b, v0
	v_exp_f32_e32 v9, v9
	ds_write_b16 v107, v5 offset:61952
	s_waitcnt vmcnt(12)
	v_lshlrev_b32_e32 v5, 16, v21
	v_mul_f32_e32 v0, 0xbfb8aa3b, v0
	v_mul_f32_e32 v5, v9, v5
	v_cvt_pk_bf16_f32 v5, v5, s0
	v_exp_f32_e32 v0, v0
	ds_write_b16 v109, v5 offset:52736
	global_load_ushort v5, v[212:213], off
	v_lshlrev_b32_e32 v14, 16, v14
	s_waitcnt vmcnt(12)
	v_lshlrev_b32_e32 v9, 16, v22
	v_mul_f32_e32 v11, v32, v14
	v_mul_f32_e32 v0, v0, v9
	v_mul_f32_e32 v9, 0x3fb8aa3b, v1
	v_cvt_pk_bf16_f32 v11, v11, s0
	v_exp_f32_e32 v9, v9
	ds_write_b16 v103, v11 offset:52736
	global_load_ushort v11, v[216:217], off
	global_load_ushort v15, v[240:241], off
	v_cvt_pk_bf16_f32 v0, v0, s0
	ds_write_b16 v109, v0 offset:61952
	s_waitcnt vmcnt(13)
	v_lshlrev_b32_e32 v0, 16, v23
	v_mul_f32_e32 v0, v9, v0
	v_mul_f32_e32 v1, 0xbfb8aa3b, v1
	global_load_ushort v9, v[220:221], off
	v_exp_f32_e32 v12, v1
	s_waitcnt vmcnt(13)
	v_lshlrev_b32_e32 v13, 16, v24
	v_cvt_pk_bf16_f32 v0, v0, s0
	v_accvgpr_read_b32 v206, a56
	v_mul_f32_e32 v12, v12, v13
	global_load_ushort v13, v[238:239], off
	v_accvgpr_read_b32 v210, a118
	ds_write_b16 v206, v0 offset:52736
	ds_read2_b32 v[0:1], v210 offset0:72 offset1:137
	v_cvt_pk_bf16_f32 v12, v12, s0
	ds_write_b16 v206, v12 offset:61952
	s_waitcnt vmcnt(13)
	v_lshlrev_b32_e32 v12, 16, v25
	v_accvgpr_read_b32 v207, a57
	s_waitcnt lgkmcnt(1)
	v_mul_f32_e32 v14, 0x3fb8aa3b, v0
	v_exp_f32_e32 v14, v14
	v_mul_f32_e32 v0, 0xbfb8aa3b, v0
	v_exp_f32_e32 v0, v0
	v_accvgpr_read_b32 v211, a119
	v_mul_f32_e32 v12, v14, v12
	v_cvt_pk_bf16_f32 v12, v12, s0
	ds_write_b16 v207, v12 offset:52736
	s_waitcnt vmcnt(12)
	v_lshlrev_b32_e32 v12, 16, v26
	v_mul_f32_e32 v0, v0, v12
	v_mul_f32_e32 v12, 0x3fb8aa3b, v1
	v_exp_f32_e32 v12, v12
	v_cvt_pk_bf16_f32 v0, v0, s0
	ds_write_b16 v207, v0 offset:61952
	s_waitcnt vmcnt(11)
	v_lshlrev_b32_e32 v0, 16, v2
	v_mul_f32_e32 v2, v12, v0
	v_mul_f32_e32 v0, 0xbfb8aa3b, v1
	v_exp_f32_e32 v12, v0
	ds_read2_b32 v[0:1], v211 offset0:74 offset1:139
	v_cvt_pk_bf16_f32 v2, v2, s0
	v_accvgpr_read_b32 v208, a58
	ds_write_b16 v208, v2 offset:52736
	s_waitcnt vmcnt(7)
	v_lshlrev_b32_e32 v2, 16, v3
	s_waitcnt lgkmcnt(1)
	v_mul_f32_e32 v3, 0x3fb8aa3b, v0
	v_exp_f32_e32 v3, v3
	v_mul_f32_e32 v2, v12, v2
	v_cvt_pk_bf16_f32 v2, v2, s0
	v_mul_f32_e32 v0, 0xbfb8aa3b, v0
	ds_write_b16 v208, v2 offset:61952
	s_waitcnt vmcnt(6)
	v_lshlrev_b32_e32 v2, 16, v4
	v_exp_f32_e32 v0, v0
	v_mul_f32_e32 v2, v3, v2
	v_cvt_pk_bf16_f32 v2, v2, s0
	v_accvgpr_read_b32 v209, a59
	ds_write_b16 v209, v2 offset:52736
	v_lshlrev_b32_e32 v2, 16, v6
	v_mul_f32_e32 v0, v0, v2
	v_mul_f32_e32 v2, 0x3fb8aa3b, v1
	v_exp_f32_e32 v2, v2
	v_cvt_pk_bf16_f32 v0, v0, s0
	ds_write_b16 v209, v0 offset:61952
	v_lshlrev_b32_e32 v0, 16, v7
	v_mul_f32_e32 v2, v2, v0
	v_mul_f32_e32 v0, 0xbfb8aa3b, v1
	v_accvgpr_read_b32 v212, a120
	v_exp_f32_e32 v3, v0
	ds_read2_b32 v[0:1], v212 offset0:76 offset1:141
	v_cvt_pk_bf16_f32 v2, v2, s0
	ds_write_b16 v69, v2 offset:52736
	s_waitcnt vmcnt(5)
	v_lshlrev_b32_e32 v2, 16, v8
	v_mul_f32_e32 v2, v3, v2
	s_waitcnt lgkmcnt(1)
	v_mul_f32_e32 v3, 0x3fb8aa3b, v0
	v_exp_f32_e32 v3, v3
	v_cvt_pk_bf16_f32 v2, v2, s0
	v_mul_f32_e32 v0, 0xbfb8aa3b, v0
	ds_write_b16 v69, v2 offset:61952
	v_lshlrev_b32_e32 v2, 16, v10
	v_exp_f32_e32 v0, v0
	v_mul_f32_e32 v2, v3, v2
	v_cvt_pk_bf16_f32 v2, v2, s0
	ds_write_b16 v253, v2 offset:52736
	s_waitcnt vmcnt(4)
	v_lshlrev_b32_e32 v2, 16, v5
	v_mul_f32_e32 v0, v0, v2
	v_mul_f32_e32 v2, 0x3fb8aa3b, v1
	v_exp_f32_e32 v2, v2
	v_cvt_pk_bf16_f32 v0, v0, s0
	v_mul_f32_e32 v1, 0xbfb8aa3b, v1
	ds_write_b16 v253, v0 offset:61952
	s_waitcnt vmcnt(3)
	v_lshlrev_b32_e32 v0, 16, v11
	v_exp_f32_e32 v1, v1
	v_mul_f32_e32 v0, v2, v0
	v_cvt_pk_bf16_f32 v0, v0, s0
	ds_write_b16 v254, v0 offset:52736
	s_waitcnt vmcnt(1)
	v_lshlrev_b32_e32 v0, 16, v9
	v_mul_f32_e32 v0, v1, v0
	v_mul_f32_e32 v1, 0x3fb8aa3b, v27
	v_exp_f32_e32 v1, v1
	v_cvt_pk_bf16_f32 v0, v0, s0
	ds_write_b16 v254, v0 offset:61952
	s_waitcnt vmcnt(0)
	v_lshlrev_b32_e32 v0, 16, v13
	v_mul_f32_e32 v0, v1, v0
	v_mul_f32_e32 v1, 0xbfb8aa3b, v27
	v_exp_f32_e32 v1, v1
	v_cvt_pk_bf16_f32 v0, v0, s0
	ds_write_b16 v250, v0 offset:52736
	v_lshlrev_b32_e32 v0, 16, v15
	v_mul_f32_e32 v0, v1, v0
	v_cvt_pk_bf16_f32 v0, v0, s0
	ds_write_b16 v250, v0 offset:61952
	s_waitcnt lgkmcnt(0)
	s_barrier
	ds_read_b128 a[116:119], v133 offset:52736
	ds_read_b128 a[124:127], v251 offset:61952
	ds_read_b128 a[128:131], v133 offset:52768
	ds_read_b128 a[136:139], v251 offset:61984
	s_waitcnt lgkmcnt(2)
	v_mfma_f32_32x32x16_bf16 a[48:63], a[116:119], a[124:127], 0
	ds_read_b128 a[116:119], v133 offset:52800
	ds_read_b128 a[124:127], v251 offset:62016
	v_mov_b32_e32 v175, v65
	s_lshl_b32 s72, s2, 1
	v_mov_b32_e32 v113, v65
	s_mov_b64 s[2:3], 0x186fa500
	s_add_i32 s80, s74, s80
	s_add_i32 s84, s84, s75
	s_cmpk_gt_i32 s80, 0x5ff
	s_waitcnt lgkmcnt(2)
	v_mfma_f32_32x32x16_bf16 a[48:63], a[128:131], a[136:139], a[48:63]
	ds_read_b128 a[128:131], v133 offset:52832
	ds_read_b128 a[136:139], v251 offset:62048
	s_waitcnt lgkmcnt(2)
	v_mfma_f32_32x32x16_bf16 a[48:63], a[116:119], a[124:127], a[48:63]
	ds_read_b128 a[116:119], v66 offset:52736
	ds_read_b128 a[124:127], v66 offset:52768
	v_lshl_add_u64 v[0:1], s[86:87], 0, v[64:65]
	v_lshl_add_u64 v[0:1], v[0:1], 0, v[110:111]
	s_mov_b64 s[86:87], 0x2c802100
	v_lshl_add_u64 v[20:21], v[0:1], 0, s[86:87]
	v_lshl_add_u64 v[0:1], v[20:21], 0, v[118:119]
	global_load_dword v4, v[0:1], off
	global_load_dword v5, v[0:1], off offset:512
	global_load_dword v6, v[0:1], off offset:1024
	global_load_dword v7, v[0:1], off offset:1536
	global_load_dword v16, v[0:1], off offset:2048
	global_load_dword v17, v[0:1], off offset:2560
	global_load_dword v18, v[0:1], off offset:3072
	global_load_dword v19, v[0:1], off offset:3584
	s_waitcnt lgkmcnt(2)
	v_mfma_f32_32x32x16_bf16 a[48:63], a[128:131], a[136:139], a[48:63]
	ds_read_b128 a[128:131], v66 offset:57344
	ds_read_b128 a[136:139], v66 offset:57376
	v_lshl_add_u64 v[22:23], v[20:21], 0, v[138:139]
	v_lshl_add_u64 v[24:25], v[20:21], 0, v[140:141]
	v_readlane_b32 s86, v255, 18
	v_readlane_b32 s87, v255, 19
	s_waitcnt vmcnt(6)
	v_cvt_pk_bf16_f32 v4, v4, v5
	s_waitcnt vmcnt(4)
	v_cvt_pk_bf16_f32 v5, v6, v7
	s_waitcnt vmcnt(2)
	v_cvt_pk_bf16_f32 v6, v16, v17
	v_lshl_add_u64 v[16:17], v[20:21], 0, v[134:135]
	s_waitcnt vmcnt(0)
	v_cvt_pk_bf16_f32 v7, v18, v19
	v_lshl_add_u64 v[18:19], v[20:21], 0, v[136:137]
	s_waitcnt lgkmcnt(3)
	v_mfma_f32_32x32x16_bf16 a[16:31], a[116:119], v[4:7], a[16:31]
	ds_read_b128 a[116:119], v66 offset:52800
	s_waitcnt lgkmcnt(2)
	v_mfma_f32_32x32x16_bf16 a[0:15], a[128:131], v[4:7], a[0:15]
	ds_read_b128 a[128:131], v66 offset:57408
	v_lshl_add_u64 v[0:1], v[20:21], 0, v[120:121]
	v_lshl_add_u64 v[2:3], v[20:21], 0, v[122:123]
	v_lshl_add_u64 v[4:5], v[20:21], 0, v[124:125]
	v_lshl_add_u64 v[6:7], v[20:21], 0, v[126:127]
	global_load_dword v0, v[0:1], off
	s_nop 0
	global_load_dword v1, v[2:3], off
	s_nop 0
	global_load_dword v2, v[4:5], off
	global_load_dword v3, v[6:7], off
	s_nop 0
	global_load_dword v4, v[16:17], off
	global_load_dword v5, v[18:19], off
	global_load_dword v6, v[22:23], off
	global_load_dword v7, v[24:25], off
	v_lshl_add_u64 v[16:17], v[20:21], 0, v[152:153]
	v_lshl_add_u64 v[18:19], v[20:21], 0, v[154:155]
	v_lshl_add_u64 v[22:23], v[20:21], 0, v[156:157]
	v_lshl_add_u64 v[24:25], v[20:21], 0, v[158:159]
	s_waitcnt vmcnt(6)
	v_cvt_pk_bf16_f32 v0, v0, v1
	s_waitcnt vmcnt(4)
	v_cvt_pk_bf16_f32 v1, v2, v3
	s_waitcnt vmcnt(2)
	v_cvt_pk_bf16_f32 v2, v4, v5
	v_lshl_add_u64 v[4:5], v[20:21], 0, v[142:143]
	s_waitcnt vmcnt(0)
	v_cvt_pk_bf16_f32 v3, v6, v7
	v_lshl_add_u64 v[6:7], v[20:21], 0, v[144:145]
	s_nop 0
	s_waitcnt lgkmcnt(4)
	v_mfma_f32_32x32x16_bf16 a[16:31], a[124:127], v[0:3], a[16:31]
	v_lshl_add_u64 v[8:9], v[20:21], 0, v[146:147]
	v_lshl_add_u64 v[10:11], v[20:21], 0, v[150:151]
	global_load_dword v4, v[4:5], off
	s_nop 0
	global_load_dword v5, v[6:7], off
	s_nop 0
	global_load_dword v6, v[8:9], off
	global_load_dword v7, v[10:11], off
	s_nop 0
	global_load_dword v8, v[16:17], off
	global_load_dword v9, v[18:19], off
	global_load_dword v10, v[22:23], off
	global_load_dword v11, v[24:25], off
	v_lshl_add_u64 v[22:23], v[20:21], 0, v[172:173]
	s_waitcnt vmcnt(6)
	v_cvt_pk_bf16_f32 v4, v4, v5
	s_waitcnt lgkmcnt(2)
	v_mfma_f32_32x32x16_bf16 a[0:15], a[136:139], v[0:3], a[0:15]
	s_waitcnt vmcnt(4)
	v_cvt_pk_bf16_f32 v5, v6, v7
	s_waitcnt vmcnt(2)
	v_cvt_pk_bf16_f32 v6, v8, v9
	v_lshl_add_u64 v[12:13], v[20:21], 0, v[168:169]
	s_waitcnt vmcnt(0)
	v_cvt_pk_bf16_f32 v7, v10, v11
	ds_read_b128 v[8:11], v66 offset:52832
	v_lshl_add_u64 v[14:15], v[20:21], 0, v[170:171]
	s_waitcnt lgkmcnt(2)
	v_mfma_f32_32x32x16_bf16 a[16:31], a[116:119], v[4:7], a[16:31]
	ds_read_b128 v[16:19], v66 offset:57440
	s_waitcnt lgkmcnt(2)
	v_mfma_f32_32x32x16_bf16 a[0:15], a[128:131], v[4:7], a[0:15]
	v_lshl_add_u64 v[0:1], v[20:21], 0, v[160:161]
	v_lshl_add_u64 v[2:3], v[20:21], 0, v[162:163]
	v_lshl_add_u64 v[4:5], v[20:21], 0, v[164:165]
	v_lshl_add_u64 v[6:7], v[20:21], 0, v[166:167]
	v_lshl_add_u64 v[20:21], v[20:21], 0, v[174:175]
	global_load_dword v0, v[0:1], off
	s_nop 0
	global_load_dword v1, v[2:3], off
	s_nop 0
	global_load_dword v2, v[4:5], off
	global_load_dword v3, v[6:7], off
	s_nop 0
	global_load_dword v4, v[12:13], off
	global_load_dword v5, v[14:15], off
	global_load_dword v6, v[22:23], off
	global_load_dword v7, v[20:21], off
	s_waitcnt lgkmcnt(0)
	s_barrier
	s_waitcnt vmcnt(6)
	v_cvt_pk_bf16_f32 v20, v0, v1
	s_waitcnt vmcnt(4)
	v_cvt_pk_bf16_f32 v21, v2, v3
	s_waitcnt vmcnt(2)
	v_cvt_pk_bf16_f32 v22, v4, v5
	s_waitcnt vmcnt(0)
	v_cvt_pk_bf16_f32 v23, v6, v7
	s_nop 1
	v_mfma_f32_32x32x16_bf16 a[16:31], v[8:11], v[20:23], a[16:31]
	v_accvgpr_read_b32 v0, a32
	v_cndmask_b32_e64 v0, v0, 0, s[6:7]
	v_accvgpr_read_b32 v1, a33
	v_accvgpr_read_b32 v2, a34
	v_accvgpr_read_b32 v3, a35
	v_accvgpr_read_b32 v4, a36
	v_accvgpr_read_b32 v5, a37
	v_mfma_f32_32x32x16_bf16 a[0:15], v[16:19], v[20:23], a[0:15]
	v_accvgpr_read_b32 v16, a48
	v_cndmask_b32_e64 v16, v16, 0, s[86:87]
	v_add_f32_e32 v0, v0, v16
	v_readlane_b32 s86, v255, 20
	v_cvt_pk_bf16_f32 v0, v0, s0
	v_readlane_b32 s87, v255, 21
	ds_write_b16 v76, v0 offset:18432
	v_accvgpr_read_b32 v6, a38
	v_cndmask_b32_e64 v0, v1, 0, s[86:87]
	v_accvgpr_read_b32 v1, a49
	v_cndmask_b32_e64 v1, 0, v1, s[6:7]
	v_add_f32_e32 v0, v0, v1
	v_readlane_b32 s86, v255, 22
	v_cvt_pk_bf16_f32 v0, v0, s0
	v_readlane_b32 s87, v255, 23
	ds_write_b16 v76, v0 offset:18576
	v_accvgpr_read_b32 v1, a50
	v_cndmask_b32_e64 v0, v2, 0, s[86:87]
	v_readlane_b32 s86, v255, 16
	v_readlane_b32 s87, v255, 17
	v_accvgpr_read_b32 v7, a39
	v_accvgpr_read_b32 v8, a40
	v_cndmask_b32_e64 v1, v1, 0, s[86:87]
	v_add_f32_e32 v0, v0, v1
	v_readlane_b32 s86, v255, 26
	v_cvt_pk_bf16_f32 v0, v0, s0
	v_readlane_b32 s87, v255, 27
	v_accvgpr_read_b32 v1, a51
	ds_write_b16 v76, v0 offset:18720
	v_cndmask_b32_e64 v0, v3, 0, s[86:87]
	v_cndmask_b32_e64 v1, v1, 0, s[18:19]
	v_add_f32_e32 v0, v0, v1
	v_cvt_pk_bf16_f32 v0, v0, s0
	v_accvgpr_read_b32 v1, a52
	ds_write_b16 v76, v0 offset:18864
	v_cndmask_b32_e64 v0, v4, 0, s[20:21]
	v_cndmask_b32_e64 v1, v1, 0, s[22:23]
	v_add_f32_e32 v0, v0, v1
	v_cvt_pk_bf16_f32 v0, v0, s0
	v_accvgpr_read_b32 v1, a53
	ds_write_b16 v76, v0 offset:19584
	v_cndmask_b32_e64 v0, v5, 0, s[24:25]
	v_cndmask_b32_e64 v1, v1, 0, s[26:27]
	v_add_f32_e32 v0, v0, v1
	v_cvt_pk_bf16_f32 v0, v0, s0
	v_accvgpr_read_b32 v1, a54
	ds_write_b16 v76, v0 offset:19728
	v_cndmask_b32_e64 v0, v6, 0, s[28:29]
	v_cndmask_b32_e64 v1, v1, 0, s[30:31]
	v_add_f32_e32 v0, v0, v1
	v_cvt_pk_bf16_f32 v0, v0, s0
	v_accvgpr_read_b32 v1, a55
	ds_write_b16 v76, v0 offset:19872
	v_cndmask_b32_e64 v0, v7, 0, s[34:35]
	v_cndmask_b32_e64 v1, v1, 0, s[36:37]
	v_add_f32_e32 v0, v0, v1
	v_cvt_pk_bf16_f32 v0, v0, s0
	v_accvgpr_read_b32 v1, a56
	ds_write_b16 v76, v0 offset:20016
	v_cndmask_b32_e64 v0, v8, 0, s[38:39]
	v_cndmask_b32_e64 v1, v1, 0, s[40:41]
	v_add_f32_e32 v0, v0, v1
	v_accvgpr_read_b32 v9, a41
	v_cvt_pk_bf16_f32 v0, v0, s0
	v_accvgpr_read_b32 v1, a57
	ds_write_b16 v76, v0 offset:20736
	v_cndmask_b32_e64 v0, v9, 0, s[42:43]
	v_cndmask_b32_e64 v1, v1, 0, s[44:45]
	v_add_f32_e32 v0, v0, v1
	v_accvgpr_read_b32 v10, a42
	v_cvt_pk_bf16_f32 v0, v0, s0
	v_accvgpr_read_b32 v1, a58
	ds_write_b16 v76, v0 offset:20880
	v_cndmask_b32_e64 v0, v10, 0, s[46:47]
	v_cndmask_b32_e64 v1, v1, 0, s[48:49]
	v_add_f32_e32 v0, v0, v1
	v_accvgpr_read_b32 v11, a43
	v_cvt_pk_bf16_f32 v0, v0, s0
	v_accvgpr_read_b32 v1, a59
	ds_write_b16 v76, v0 offset:21024
	v_cndmask_b32_e64 v0, v11, 0, s[50:51]
	v_cndmask_b32_e64 v1, v1, 0, s[52:53]
	v_add_f32_e32 v0, v0, v1
	v_accvgpr_read_b32 v12, a44
	v_cvt_pk_bf16_f32 v0, v0, s0
	v_accvgpr_read_b32 v1, a60
	ds_write_b16 v76, v0 offset:21168
	v_cndmask_b32_e64 v0, v12, 0, s[54:55]
	v_cndmask_b32_e64 v1, v1, 0, s[56:57]
	v_add_f32_e32 v0, v0, v1
	v_accvgpr_read_b32 v13, a45
	v_cvt_pk_bf16_f32 v0, v0, s0
	v_accvgpr_read_b32 v1, a61
	ds_write_b16 v76, v0 offset:21888
	v_cndmask_b32_e64 v0, v13, 0, s[58:59]
	v_cndmask_b32_e64 v1, v1, 0, s[60:61]
	v_add_f32_e32 v0, v0, v1
	v_accvgpr_read_b32 v14, a46
	v_cvt_pk_bf16_f32 v0, v0, s0
	v_accvgpr_read_b32 v1, a62
	ds_write_b16 v76, v0 offset:22032
	v_cndmask_b32_e64 v0, v14, 0, s[62:63]
	v_cndmask_b32_e64 v1, v1, 0, s[64:65]
	v_add_f32_e32 v0, v0, v1
	v_accvgpr_read_b32 v15, a47
	v_cvt_pk_bf16_f32 v0, v0, s0
	v_accvgpr_read_b32 v1, a63
	ds_write_b16 v76, v0 offset:22176
	v_cndmask_b32_e64 v0, v15, 0, s[66:67]
	v_cndmask_b32_e64 v1, v1, 0, s[68:69]
	v_add_f32_e32 v0, v0, v1
	v_cvt_pk_bf16_f32 v0, v0, s0
	ds_write_b16 v76, v0 offset:22320
	s_waitcnt lgkmcnt(0)
	s_barrier
	ds_read_b128 a[32:35], v66 offset:18432
	ds_read_b128 a[36:39], v131
	ds_read_b128 a[40:43], v131 offset:32
	ds_read_b128 a[44:47], v66 offset:18464
	s_waitcnt lgkmcnt(2)
	v_mfma_f32_32x32x16_bf16 a[16:31], a[32:35], a[36:39], a[16:31]
	ds_read_b128 a[32:35], v66 offset:23040
	s_waitcnt lgkmcnt(0)
	v_mfma_f32_32x32x16_bf16 a[0:15], a[32:35], a[36:39], a[0:15]
	ds_read_b128 a[32:35], v66 offset:23072
	ds_read_b128 a[36:39], v66 offset:18496
	s_waitcnt lgkmcnt(3)
	v_mfma_f32_32x32x16_bf16 a[16:31], a[44:47], a[40:43], a[16:31]
	ds_read_b128 a[44:47], v131 offset:64
	s_waitcnt lgkmcnt(2)
	v_mfma_f32_32x32x16_bf16 a[0:15], a[32:35], a[40:43], a[0:15]
	ds_read_b128 a[32:35], v131 offset:96
	ds_read_b128 a[40:43], v66 offset:18528
	s_waitcnt lgkmcnt(2)
	v_mfma_f32_32x32x16_bf16 a[16:31], a[36:39], a[44:47], a[16:31]
	ds_read_b128 a[36:39], v66 offset:23104
	s_waitcnt lgkmcnt(0)
	v_mfma_f32_32x32x16_bf16 a[0:15], a[36:39], a[44:47], a[0:15]
	ds_read_b128 a[36:39], v66 offset:23136
	v_accvgpr_read_b32 v0, a64
	s_waitcnt lgkmcnt(2)
	v_mfma_f32_32x32x16_bf16 a[16:31], a[40:43], a[32:35], a[16:31]
	v_add_u32_e32 v12, 0x8d00, v77
	s_waitcnt lgkmcnt(0)
	v_mfma_f32_32x32x16_bf16 a[0:15], a[36:39], a[32:35], a[0:15]
	s_nop 8
	ds_write_b32 v130, a16 offset:36096
	ds_write_b32 v130, a17 offset:36612
	ds_write_b32 v130, a18 offset:37128
	ds_write_b32 v130, a19 offset:37644
	ds_write_b32 v130, a20 offset:40224
	ds_write_b32 v130, a21 offset:40740
	ds_write_b32 v130, a22 offset:41256
	ds_write_b32 v130, a23 offset:41772
	ds_write_b32 v130, a24 offset:44352
	ds_write_b32 v130, a25 offset:44868
	ds_write_b32 v130, a26 offset:45384
	ds_write_b32 v130, a27 offset:45900
	ds_write_b32 v130, a28 offset:48480
	ds_write_b32 v130, a29 offset:48996
	ds_write_b32 v130, a30 offset:49512
	ds_write_b32 v130, a31 offset:50028
	ds_write_b32 v130, a0 offset:52608
	ds_write_b32 v130, a1 offset:53124
	ds_write_b32 v130, a2 offset:53640
	ds_write_b32 v130, a3 offset:54156
	ds_write_b32 v130, a4 offset:56736
	ds_write_b32 v130, a5 offset:57252
	ds_write_b32 v130, a6 offset:57768
	ds_write_b32 v130, a7 offset:58284
	ds_write_b32 v130, a8 offset:60864
	ds_write_b32 v130, a9 offset:61380
	ds_write_b32 v130, a10 offset:61896
	ds_write_b32 v130, a11 offset:62412
	ds_write_b32 v130, a12 offset:64992
	ds_write_b32 v130, a13 offset:65508
	ds_write_b32 v0, a14 offset:29928
	ds_write_b32 v0, a15 offset:30444
	v_accvgpr_read_b32 v0, a213
	v_add_u32_e32 v0, s70, v0
	v_ashrrev_i32_e32 v1, 31, v0
	v_lshlrev_b64 v[2:3], 10, v[0:1]
	v_lshl_add_u64 v[2:3], s[76:77], 0, v[2:3]
	v_lshl_add_u64 v[2:3], v[2:3], 0, s[72:73]
	v_lshl_add_u64 v[4:5], v[2:3], 0, v[112:113]
	s_waitcnt lgkmcnt(0)
	s_barrier
	global_load_dwordx4 v[58:61], v[4:5], off
	v_lshlrev_b64 v[0:1], 11, v[0:1]
	v_lshl_add_u64 v[0:1], s[90:91], 0, v[0:1]
	v_add_u32_e32 v2, 0x8d70, v77
	v_add_u32_e32 v3, 0x8d78, v77
	v_lshl_add_u64 v[0:1], v[0:1], 0, s[72:73]
	v_add_u32_e32 v8, 0x8d18, v77
	ds_read2_b32 v[24:25], v2 offset1:1
	ds_read2_b32 v[22:23], v3 offset1:1
	global_load_dwordx4 v[16:19], v[4:5], off offset:16
	v_lshl_add_u64 v[26:27], v[0:1], 0, v[112:113]
	global_load_dwordx4 v[0:3], v[4:5], off offset:48
	s_nop 0
	global_load_dwordx4 v[4:7], v[4:5], off offset:32
	ds_read2_b32 v[28:29], v8 offset1:1
	v_lshl_add_u64 v[20:21], v[26:27], 0, s[2:3]
	v_add_u32_e32 v10, 0x8d10, v77
	v_add_u32_e32 v11, 0x8d08, v77
	ds_read2_b32 v[34:35], v10 offset1:1
	ds_read2_b32 v[36:37], v11 offset1:1
	ds_read2_b32 v[38:39], v12 offset1:1
	s_waitcnt lgkmcnt(3)
	v_pk_mul_f32 v[44:45], v[28:29], v[28:29]
	v_pk_mul_f32 v[32:33], v[24:25], v[24:25]
	s_waitcnt lgkmcnt(2)
	v_pk_mul_f32 v[48:49], v[34:35], v[34:35]
	v_pk_mul_f32 v[30:31], v[22:23], v[22:23]
	s_waitcnt vmcnt(3)
	v_lshlrev_b32_e32 v46, 16, v60
	v_and_b32_e32 v42, 0xffff0000, v60
	v_mul_f32_e32 v8, 0xbfb8aa3b, v46
	v_mul_f32_e32 v9, 0xbfb8aa3b, v42
	v_exp_f32_e32 v8, v8
	v_exp_f32_e32 v9, v9
	v_lshlrev_b32_e32 v53, 16, v59
	v_and_b32_e32 v56, 0xffff0000, v59
	v_and_b32_e32 v60, 0xffff0000, v58
	v_pk_add_f32 v[40:41], v[8:9], 1.0 op_sel_hi:[1,0]
	s_waitcnt vmcnt(2)
	v_lshlrev_b32_e32 v79, 16, v18
	v_div_scale_f32 v43, s[2:3], v41, v41, v42
	v_rcp_f32_e32 v47, v43
	v_and_b32_e32 v18, 0xffff0000, v18
	global_load_dwordx4 v[8:11], v[72:73], off offset:16
	global_load_dwordx4 v[12:15], v[72:73], off
	v_fma_f32 v50, -v43, v47, 1.0
	v_fmac_f32_e32 v47, v50, v47
	v_div_scale_f32 v50, vcc, v42, v41, v42
	v_mul_f32_e32 v51, v50, v47
	v_fma_f32 v52, -v43, v51, v50
	v_fmac_f32_e32 v51, v52, v47
	v_fma_f32 v43, -v43, v51, v50
	v_div_scale_f32 v50, s[2:3], v40, v40, v46
	v_rcp_f32_e32 v52, v50
	v_div_fmas_f32 v43, v43, v47, v51
	v_div_fixup_f32 v41, v43, v41, v42
	v_mul_f32_e32 v43, 0xbfb8aa3b, v56
	v_fma_f32 v42, -v50, v52, 1.0
	v_fmac_f32_e32 v52, v42, v52
	v_mul_f32_e32 v42, 0xbfb8aa3b, v53
	v_exp_f32_e32 v42, v42
	v_exp_f32_e32 v43, v43
	v_div_scale_f32 v47, vcc, v46, v40, v46
	v_mul_f32_e32 v51, v47, v52
	v_fma_f32 v54, -v50, v51, v47
	v_fmac_f32_e32 v51, v54, v52
	v_pk_add_f32 v[42:43], v[42:43], 1.0 op_sel_hi:[1,0]
	v_fma_f32 v47, -v50, v51, v47
	v_div_scale_f32 v50, s[2:3], v43, v43, v56
	v_rcp_f32_e32 v57, v50
	v_div_fmas_f32 v47, v47, v52, v51
	v_div_fixup_f32 v40, v47, v40, v46
	s_waitcnt lgkmcnt(1)
	v_pk_mul_f32 v[54:55], v[36:37], v[36:37]
	v_fma_f32 v46, -v50, v57, 1.0
	v_fmac_f32_e32 v57, v46, v57
	v_div_scale_f32 v46, vcc, v56, v43, v56
	v_mul_f32_e32 v47, v46, v57
	v_fma_f32 v51, -v50, v47, v46
	v_fmac_f32_e32 v47, v51, v57
	v_fma_f32 v46, -v50, v47, v46
	v_div_scale_f32 v50, s[2:3], v42, v42, v53
	v_rcp_f32_e32 v51, v50
	v_div_fmas_f32 v46, v46, v57, v47
	v_div_fixup_f32 v43, v46, v43, v56
	v_lshlrev_b32_e32 v57, 16, v58
	v_fma_f32 v46, -v50, v51, 1.0
	v_fmac_f32_e32 v51, v46, v51
	v_mul_f32_e32 v46, 0xbfb8aa3b, v57
	v_mul_f32_e32 v47, 0xbfb8aa3b, v60
	v_exp_f32_e32 v46, v46
	v_exp_f32_e32 v47, v47
	v_div_scale_f32 v52, vcc, v53, v42, v53
	v_mul_f32_e32 v56, v52, v51
	v_fma_f32 v58, -v50, v56, v52
	v_fmac_f32_e32 v56, v58, v51
	v_pk_add_f32 v[46:47], v[46:47], 1.0 op_sel_hi:[1,0]
	v_fma_f32 v50, -v50, v56, v52
	v_div_scale_f32 v52, s[2:3], v47, v47, v60
	v_rcp_f32_e32 v62, v52
	v_div_fmas_f32 v50, v50, v51, v56
	v_div_fixup_f32 v42, v50, v42, v53
	s_waitcnt lgkmcnt(0)
	v_pk_mul_f32 v[58:59], v[38:39], v[38:39]
	v_fma_f32 v50, -v52, v62, 1.0
	v_fmac_f32_e32 v62, v50, v62
	v_div_scale_f32 v50, vcc, v60, v47, v60
	v_mul_f32_e32 v51, v50, v62
	v_fma_f32 v53, -v52, v51, v50
	v_fmac_f32_e32 v51, v53, v62
	v_fma_f32 v50, -v52, v51, v50
	v_div_scale_f32 v52, s[2:3], v46, v46, v57
	v_rcp_f32_e32 v56, v52
	v_div_fmas_f32 v50, v50, v62, v51
	v_lshlrev_b32_e32 v62, 16, v61
	v_and_b32_e32 v61, 0xffff0000, v61
	v_div_fixup_f32 v53, v50, v47, v60
	v_mul_f32_e32 v50, 0xbfb8aa3b, v62
	v_mul_f32_e32 v51, 0xbfb8aa3b, v61
	v_exp_f32_e32 v50, v50
	v_exp_f32_e32 v51, v51
	v_fma_f32 v47, -v52, v56, 1.0
	v_fmac_f32_e32 v56, v47, v56
	v_div_scale_f32 v47, vcc, v57, v46, v57
	v_mul_f32_e32 v60, v47, v56
	v_fma_f32 v63, -v52, v60, v47
	v_pk_add_f32 v[50:51], v[50:51], 1.0 op_sel_hi:[1,0]
	v_fmac_f32_e32 v60, v63, v56
	v_div_scale_f32 v63, s[2:3], v51, v51, v61
	v_rcp_f32_e32 v70, v63
	v_fma_f32 v47, -v52, v60, v47
	v_div_fmas_f32 v47, v47, v56, v60
	v_div_fixup_f32 v52, v47, v46, v57
	v_fma_f32 v46, -v63, v70, 1.0
	v_fmac_f32_e32 v70, v46, v70
	v_div_scale_f32 v46, vcc, v61, v51, v61
	v_mul_f32_e32 v47, v46, v70
	v_fma_f32 v56, -v63, v47, v46
	v_fmac_f32_e32 v47, v56, v70
	v_div_scale_f32 v56, s[2:3], v50, v50, v62
	v_rcp_f32_e32 v60, v56
	v_fma_f32 v46, -v63, v47, v46
	v_div_fmas_f32 v46, v46, v70, v47
	v_div_fixup_f32 v57, v46, v51, v61
	v_fma_f32 v46, -v56, v60, 1.0
	v_fmac_f32_e32 v60, v46, v60
	v_div_scale_f32 v46, vcc, v62, v50, v62
	v_mul_f32_e32 v47, v46, v60
	v_fma_f32 v51, -v56, v47, v46
	v_fmac_f32_e32 v47, v51, v60
	v_fma_f32 v46, -v56, v47, v46
	v_div_fmas_f32 v46, v46, v60, v47
	v_mul_f32_e32 v47, 0xbfb8aa3b, v79
	v_exp_f32_e32 v60, v47
	v_mul_f32_e32 v47, 0xbfb8aa3b, v18
	v_exp_f32_e32 v61, v47
	v_div_fixup_f32 v56, v46, v50, v62
	v_add_u32_e32 v46, 0x8d38, v77
	v_add_u32_e32 v50, 0x8d30, v77
	v_pk_add_f32 v[70:71], v[60:61], 1.0 op_sel_hi:[1,0]
	v_add_u32_e32 v60, 0x8d28, v77
	v_div_scale_f32 v74, s[2:3], v71, v71, v18
	v_rcp_f32_e32 v75, v74
	v_add_u32_e32 v62, 0x8d20, v77
	v_add_f32_e32 v58, v58, v59
	ds_read2_b32 v[46:47], v46 offset1:1
	ds_read2_b32 v[50:51], v50 offset1:1
	v_fma_f32 v81, -v74, v75, 1.0
	v_fmac_f32_e32 v75, v81, v75
	v_div_scale_f32 v81, vcc, v18, v71, v18
	v_mul_f32_e32 v83, v81, v75
	v_fma_f32 v85, -v74, v83, v81
	v_fmac_f32_e32 v83, v85, v75
	v_fma_f32 v74, -v74, v83, v81
	v_div_scale_f32 v81, s[2:3], v70, v70, v79
	v_rcp_f32_e32 v85, v81
	v_div_fmas_f32 v74, v74, v75, v83
	v_lshlrev_b32_e32 v83, 16, v17
	v_and_b32_e32 v17, 0xffff0000, v17
	v_div_fixup_f32 v177, v74, v71, v18
	v_mul_f32_e32 v74, 0xbfb8aa3b, v83
	v_mul_f32_e32 v75, 0xbfb8aa3b, v17
	v_fma_f32 v18, -v81, v85, 1.0
	v_exp_f32_e32 v74, v74
	v_exp_f32_e32 v75, v75
	v_fmac_f32_e32 v85, v18, v85
	v_div_scale_f32 v18, vcc, v79, v70, v79
	v_mul_f32_e32 v71, v18, v85
	v_fma_f32 v87, -v81, v71, v18
	v_fmac_f32_e32 v71, v87, v85
	v_pk_add_f32 v[74:75], v[74:75], 1.0 op_sel_hi:[1,0]
	v_fma_f32 v18, -v81, v71, v18
	v_div_scale_f32 v81, s[2:3], v75, v75, v17
	v_rcp_f32_e32 v87, v81
	v_div_fmas_f32 v18, v18, v85, v71
	v_div_fixup_f32 v176, v18, v70, v79
	ds_read2_b32 v[60:61], v60 offset1:1
	ds_read2_b32 v[62:63], v62 offset1:1
	v_fma_f32 v18, -v81, v87, 1.0
	v_fmac_f32_e32 v87, v18, v87
	v_div_scale_f32 v18, vcc, v17, v75, v17
	v_mul_f32_e32 v70, v18, v87
	v_fma_f32 v71, -v81, v70, v18
	v_fmac_f32_e32 v70, v71, v87
	v_div_scale_f32 v71, s[2:3], v74, v74, v83
	v_rcp_f32_e32 v79, v71
	v_fma_f32 v18, -v81, v70, v18
	v_div_fmas_f32 v18, v18, v87, v70
	v_div_fixup_f32 v179, v18, v75, v17
	v_fma_f32 v17, -v71, v79, 1.0
	v_lshlrev_b32_e32 v81, 16, v16
	v_and_b32_e32 v75, 0xffff0000, v16
	v_fmac_f32_e32 v79, v17, v79
	v_mul_f32_e32 v16, 0xbfb8aa3b, v81
	v_mul_f32_e32 v17, 0xbfb8aa3b, v75
	v_exp_f32_e32 v16, v16
	v_exp_f32_e32 v17, v17
	v_div_scale_f32 v18, vcc, v83, v74, v83
	v_mul_f32_e32 v70, v18, v79
	v_pk_add_f32 v[180:181], v[16:17], 1.0 op_sel_hi:[1,0]
	v_fma_f32 v85, -v71, v70, v18
	v_div_scale_f32 v16, s[2:3], v181, v181, v75
	v_rcp_f32_e32 v17, v16
	v_fmac_f32_e32 v70, v85, v79
	v_fma_f32 v18, -v71, v70, v18
	v_div_fmas_f32 v18, v18, v79, v70
	v_div_fixup_f32 v178, v18, v74, v83
	v_fma_f32 v18, -v16, v17, 1.0
	v_fmac_f32_e32 v17, v18, v17
	v_div_scale_f32 v18, vcc, v75, v181, v75
	v_mul_f32_e32 v70, v18, v17
	v_fma_f32 v71, -v16, v70, v18
	v_fmac_f32_e32 v70, v71, v17
	v_fma_f32 v16, -v16, v70, v18
	v_div_scale_f32 v18, s[2:3], v180, v180, v81
	v_rcp_f32_e32 v79, v18
	v_div_fmas_f32 v16, v16, v17, v70
	v_add_f32_e32 v54, v58, v54
	v_div_fixup_f32 v181, v16, v181, v75
	v_fma_f32 v16, -v18, v79, 1.0
	v_lshlrev_b32_e32 v85, 16, v19
	v_and_b32_e32 v87, 0xffff0000, v19
	v_add_f32_e32 v54, v54, v55
	v_fmac_f32_e32 v79, v16, v79
	v_mul_f32_e32 v16, 0xbfb8aa3b, v85
	v_mul_f32_e32 v17, 0xbfb8aa3b, v87
	v_add_f32_e32 v48, v54, v48
	v_div_scale_f32 v70, vcc, v81, v180, v81
	v_exp_f32_e32 v16, v16
	v_exp_f32_e32 v17, v17
	v_add_f32_e32 v48, v48, v49
	v_mul_f32_e32 v83, v70, v79
	v_add_f32_e32 v44, v48, v44
	s_waitcnt lgkmcnt(0)
	v_pk_mul_f32 v[148:149], v[62:63], v[62:63]
	v_fma_f32 v19, -v18, v83, v70
	v_add_f32_e32 v44, v44, v45
	v_fmac_f32_e32 v83, v19, v79
	v_add_f32_e32 v44, v44, v148
	v_pk_mul_f32 v[196:197], v[60:61], v[60:61]
	v_fma_f32 v89, -v18, v83, v70
	v_pk_add_f32 v[194:195], v[16:17], 1.0 op_sel_hi:[1,0]
	v_add_u32_e32 v16, 0x8d58, v77
	v_add_u32_e32 v18, 0x8d50, v77
	v_add_f32_e32 v44, v44, v149
	ds_read2_b32 v[16:17], v16 offset1:1
	v_add_u32_e32 v70, 0x8d48, v77
	v_add_u32_e32 v71, 0x8d40, v77
	ds_read2_b32 v[18:19], v18 offset1:1
	ds_read2_b32 v[182:183], v70 offset1:1
	ds_read2_b32 v[184:185], v71 offset1:1
	v_add_f32_e32 v44, v44, v196
	v_pk_mul_f32 v[190:191], v[50:51], v[50:51]
	v_add_f32_e32 v44, v44, v197
	v_add_f32_e32 v44, v44, v190
	v_pk_mul_f32 v[188:189], v[46:47], v[46:47]
	v_add_f32_e32 v44, v44, v191
	v_add_f32_e32 v44, v44, v188
	s_waitcnt lgkmcnt(0)
	v_pk_mul_f32 v[200:201], v[184:185], v[184:185]
	v_add_f32_e32 v44, v44, v189
	v_add_f32_e32 v44, v44, v200
	v_add_u32_e32 v74, 0x8d68, v77
	v_pk_mul_f32 v[198:199], v[182:183], v[182:183]
	v_add_f32_e32 v44, v44, v201
	v_add_u32_e32 v75, 0x8d60, v77
	ds_read2_b32 v[186:187], v74 offset1:1
	ds_read2_b32 v[192:193], v75 offset1:1
	v_add_f32_e32 v44, v44, v198
	v_pk_mul_f32 v[74:75], v[18:19], v[18:19]
	v_add_f32_e32 v44, v44, v199
	v_add_f32_e32 v44, v44, v74
	v_pk_mul_f32 v[70:71], v[16:17], v[16:17]
	v_add_f32_e32 v44, v44, v75
	v_add_f32_e32 v44, v44, v70
	s_waitcnt lgkmcnt(0)
	v_pk_mul_f32 v[204:205], v[192:193], v[192:193]
	v_add_f32_e32 v44, v44, v71
	v_add_f32_e32 v44, v44, v204
	v_pk_mul_f32 v[202:203], v[186:187], v[186:187]
	v_add_f32_e32 v44, v44, v205
	v_add_f32_e32 v44, v44, v202
	v_add_f32_e32 v44, v44, v203
	v_add_f32_e32 v32, v44, v32
	v_add_f32_e32 v32, v32, v33
	v_add_f32_e32 v30, v32, v30
	v_add_f32_e32 v30, v30, v31
	v_accvgpr_read_b32 v31, a121
	ds_bpermute_b32 v31, v31, v30
	v_div_scale_f32 v91, s[2:3], v195, v195, v87
	v_rcp_f32_e32 v93, v91
	s_mov_b32 s2, 0x800000
	s_waitcnt lgkmcnt(0)
	v_add_f32_e32 v30, v30, v31
	v_accvgpr_read_b32 v31, a122
	ds_bpermute_b32 v31, v31, v30
	v_div_fmas_f32 v32, v89, v79, v83
	v_div_fixup_f32 v180, v32, v180, v81
	v_fma_f32 v32, -v91, v93, 1.0
	v_fmac_f32_e32 v93, v32, v93
	s_waitcnt lgkmcnt(0)
	v_add_f32_e32 v30, v30, v31
	v_mov_b32_e32 v31, 0x358637bd
	v_fmamk_f32 v30, v30, 0x3c000000, v31
	v_mul_f32_e32 v31, 0x4b800000, v30
	v_cmp_gt_f32_e64 s[70:71], s2, v30
	v_div_scale_f32 v32, vcc, v87, v195, v87
	s_nop 0
	v_cndmask_b32_e64 v30, v30, v31, s[70:71]
	v_rsq_f32_e32 v30, v30
	v_mul_f32_e32 v44, v32, v93
	v_fma_f32 v31, -v91, v44, v32
	v_fmac_f32_e32 v44, v31, v93
	v_fma_f32 v31, -v91, v44, v32
	v_mul_f32_e32 v32, 0x45800000, v30
	v_cndmask_b32_e64 v30, v30, v32, s[70:71]
	v_pk_mul_f32 v[32:33], v[38:39], v[30:31] op_sel_hi:[1,0]
	s_mov_b32 s2, 0x186fa000
	s_waitcnt vmcnt(0)
	v_pk_mul_f32 v[12:13], v[12:13], v[32:33]
	v_pk_mul_f32 v[32:33], v[36:37], v[30:31] op_sel_hi:[1,0]
	v_pk_mul_f32 v[12:13], v[52:53], v[12:13]
	v_pk_mul_f32 v[14:15], v[14:15], v[32:33]
	v_cvt_pk_bf16_f32 v12, v12, v13
	v_pk_mul_f32 v[14:15], v[42:43], v[14:15]
	v_lshlrev_b32_e32 v38, 16, v5
	v_cvt_pk_bf16_f32 v13, v14, v15
	v_pk_mul_f32 v[14:15], v[34:35], v[30:31] op_sel_hi:[1,0]
	v_lshlrev_b32_e32 v34, 16, v6
	v_pk_mul_f32 v[8:9], v[8:9], v[14:15]
	v_and_b32_e32 v6, 0xffff0000, v6
	v_pk_mul_f32 v[8:9], v[40:41], v[8:9]
	v_and_b32_e32 v5, 0xffff0000, v5
	v_cvt_pk_bf16_f32 v14, v8, v9
	v_pk_mul_f32 v[8:9], v[28:29], v[30:31] op_sel_hi:[1,0]
	v_mul_f32_e32 v29, 0xbfb8aa3b, v6
	v_pk_mul_f32 v[8:9], v[10:11], v[8:9]
	v_exp_f32_e32 v29, v29
	v_pk_mul_f32 v[8:9], v[56:57], v[8:9]
	s_nop 0
	v_cvt_pk_bf16_f32 v15, v8, v9
	v_add_co_u32_e64 v8, s[70:71], s2, v26
	v_div_scale_f32 v26, s[2:3], v194, v194, v85
	s_nop 0
	v_addc_co_u32_e64 v9, s[70:71], 0, v27, s[70:71]
	global_store_dwordx4 v[8:9], v[12:15], off offset:1280
	global_load_dwordx4 v[8:11], v[72:73], off offset:48
	s_nop 0
	global_load_dwordx4 v[12:15], v[72:73], off offset:32
	v_rcp_f32_e32 v32, v26
	v_div_fmas_f32 v27, v31, v93, v44
	v_div_scale_f32 v31, vcc, v85, v194, v85
	v_fma_f32 v28, -v26, v32, 1.0
	v_fmac_f32_e32 v32, v28, v32
	v_mul_f32_e32 v28, 0xbfb8aa3b, v34
	v_exp_f32_e32 v28, v28
	v_mul_f32_e32 v33, v31, v32
	v_fma_f32 v35, -v26, v33, v31
	v_fmac_f32_e32 v33, v35, v32
	v_pk_add_f32 v[28:29], v[28:29], 1.0 op_sel_hi:[1,0]
	v_fma_f32 v26, -v26, v33, v31
	v_div_scale_f32 v31, s[2:3], v29, v29, v6
	v_rcp_f32_e32 v35, v31
	v_div_fmas_f32 v26, v26, v32, v33
	v_div_fixup_f32 v27, v27, v195, v87
	v_div_fixup_f32 v26, v26, v194, v85
	v_fma_f32 v32, -v31, v35, 1.0
	v_fmac_f32_e32 v35, v32, v35
	v_div_scale_f32 v32, vcc, v6, v29, v6
	v_mul_f32_e32 v33, v32, v35
	v_fma_f32 v36, -v31, v33, v32
	v_fmac_f32_e32 v33, v36, v35
	v_div_scale_f32 v36, s[2:3], v28, v28, v34
	v_rcp_f32_e32 v37, v36
	v_fma_f32 v31, -v31, v33, v32
	v_div_fmas_f32 v31, v31, v35, v33
	v_mul_f32_e32 v32, 0xbfb8aa3b, v38
	v_mul_f32_e32 v33, 0xbfb8aa3b, v5
	v_exp_f32_e32 v32, v32
	v_exp_f32_e32 v33, v33
	v_div_fixup_f32 v29, v31, v29, v6
	v_fma_f32 v6, -v36, v37, 1.0
	v_fmac_f32_e32 v37, v6, v37
	v_div_scale_f32 v6, vcc, v34, v28, v34
	v_mul_f32_e32 v31, v6, v37
	v_fma_f32 v35, -v36, v31, v6
	v_pk_add_f32 v[32:33], v[32:33], 1.0 op_sel_hi:[1,0]
	v_fmac_f32_e32 v31, v35, v37
	v_div_scale_f32 v35, s[2:3], v33, v33, v5
	v_fma_f32 v6, -v36, v31, v6
	v_rcp_f32_e32 v36, v35
	v_div_fmas_f32 v6, v6, v37, v31
	v_div_fixup_f32 v28, v6, v28, v34
	v_div_scale_f32 v37, s[2:3], v32, v32, v38
	v_fma_f32 v6, -v35, v36, 1.0
	v_fmac_f32_e32 v36, v6, v36
	v_div_scale_f32 v6, vcc, v5, v33, v5
	v_mul_f32_e32 v31, v6, v36
	v_fma_f32 v34, -v35, v31, v6
	v_fmac_f32_e32 v31, v34, v36
	v_fma_f32 v6, -v35, v31, v6
	v_pk_mul_f32 v[34:35], v[62:63], v[30:31] op_sel_hi:[1,0]
	v_rcp_f32_e32 v39, v37
	v_div_fmas_f32 v6, v6, v36, v31
	v_div_fixup_f32 v33, v6, v33, v5
	v_div_scale_f32 v6, vcc, v38, v32, v38
	v_fma_f32 v5, -v37, v39, 1.0
	v_fmac_f32_e32 v39, v5, v39
	s_waitcnt vmcnt(0)
	v_pk_mul_f32 v[12:13], v[34:35], v[12:13]
	v_pk_mul_f32 v[34:35], v[60:61], v[30:31] op_sel_hi:[1,0]
	v_pk_mul_f32 v[12:13], v[12:13], v[180:181]
	v_pk_mul_f32 v[14:15], v[34:35], v[14:15]
	v_cvt_pk_bf16_f32 v12, v12, v13
	v_pk_mul_f32 v[14:15], v[14:15], v[178:179]
	s_nop 0
	v_cvt_pk_bf16_f32 v13, v14, v15
	v_pk_mul_f32 v[14:15], v[50:51], v[30:31] op_sel_hi:[1,0]
	s_nop 0
	v_pk_mul_f32 v[8:9], v[14:15], v[8:9]
	s_nop 0
	v_pk_mul_f32 v[8:9], v[8:9], v[176:177]
	s_nop 0
	v_cvt_pk_bf16_f32 v14, v8, v9
	v_pk_mul_f32 v[8:9], v[46:47], v[30:31] op_sel_hi:[1,0]
	v_and_b32_e32 v31, 0xffff0000, v4
	v_pk_mul_f32 v[8:9], v[8:9], v[10:11]
	v_mul_f32_e32 v5, 0xbfb8aa3b, v31
	v_pk_mul_f32 v[8:9], v[26:27], v[8:9]
	v_lshlrev_b32_e32 v27, 16, v4
	v_cvt_pk_bf16_f32 v15, v8, v9
	global_store_dwordx4 v[20:21], v[12:15], off offset:16
	global_load_dwordx4 v[8:11], v[72:73], off offset:80
	s_nop 0
	global_load_dwordx4 v[12:15], v[72:73], off offset:64
	v_mul_f32_e32 v4, 0xbfb8aa3b, v27
	v_exp_f32_e32 v4, v4
	v_exp_f32_e32 v5, v5
	v_mul_f32_e32 v26, v6, v39
	v_fma_f32 v34, -v37, v26, v6
	v_fmac_f32_e32 v26, v34, v39
	v_pk_add_f32 v[4:5], v[4:5], 1.0 op_sel_hi:[1,0]
	v_fma_f32 v6, -v37, v26, v6
	v_div_scale_f32 v34, s[2:3], v5, v5, v31
	v_rcp_f32_e32 v35, v34
	v_div_fmas_f32 v6, v6, v39, v26
	v_div_fixup_f32 v32, v6, v32, v38
	v_and_b32_e32 v37, 0xffff0000, v7
	v_fma_f32 v6, -v34, v35, 1.0
	v_fmac_f32_e32 v35, v6, v35
	v_div_scale_f32 v6, vcc, v31, v5, v31
	v_mul_f32_e32 v26, v6, v35
	v_fma_f32 v36, -v34, v26, v6
	v_fmac_f32_e32 v26, v36, v35
	v_fma_f32 v6, -v34, v26, v6
	v_div_scale_f32 v34, s[2:3], v4, v4, v27
	v_rcp_f32_e32 v36, v34
	v_div_fmas_f32 v6, v6, v35, v26
	v_div_fixup_f32 v5, v6, v5, v31
	v_lshlrev_b32_e32 v35, 16, v7
	v_fma_f32 v6, -v34, v36, 1.0
	v_fmac_f32_e32 v36, v6, v36
	v_mul_f32_e32 v6, 0xbfb8aa3b, v35
	v_mul_f32_e32 v7, 0xbfb8aa3b, v37
	v_exp_f32_e32 v6, v6
	v_exp_f32_e32 v7, v7
	v_div_scale_f32 v26, vcc, v27, v4, v27
	v_mul_f32_e32 v31, v26, v36
	v_fma_f32 v38, -v34, v31, v26
	v_fmac_f32_e32 v31, v38, v36
	v_pk_add_f32 v[6:7], v[6:7], 1.0 op_sel_hi:[1,0]
	v_fma_f32 v26, -v34, v31, v26
	v_div_scale_f32 v34, s[2:3], v7, v7, v37
	v_rcp_f32_e32 v38, v34
	v_div_fmas_f32 v26, v26, v36, v31
	v_div_fixup_f32 v4, v26, v4, v27
	v_fma_f32 v26, -v34, v38, 1.0
	v_fmac_f32_e32 v38, v26, v38
	v_div_scale_f32 v26, vcc, v37, v7, v37
	v_mul_f32_e32 v27, v26, v38
	v_fma_f32 v31, -v34, v27, v26
	v_fmac_f32_e32 v27, v31, v38
	v_div_scale_f32 v31, s[2:3], v6, v6, v35
	v_fma_f32 v26, -v34, v27, v26
	v_rcp_f32_e32 v34, v31
	v_div_fmas_f32 v26, v26, v38, v27
	v_div_fixup_f32 v27, v26, v7, v37
	v_fma_f32 v7, -v31, v34, 1.0
	v_fmac_f32_e32 v34, v7, v34
	v_div_scale_f32 v7, vcc, v35, v6, v35
	v_mul_f32_e32 v26, v7, v34
	v_fma_f32 v36, -v31, v26, v7
	v_fmac_f32_e32 v26, v36, v34
	v_fma_f32 v7, -v31, v26, v7
	v_div_fmas_f32 v7, v7, v34, v26
	v_div_fixup_f32 v26, v7, v6, v35
	v_pk_mul_f32 v[6:7], v[184:185], v[30:31] op_sel_hi:[1,0]
	s_waitcnt vmcnt(0)
	v_pk_mul_f32 v[6:7], v[6:7], v[12:13]
	s_nop 0
	v_pk_mul_f32 v[4:5], v[6:7], v[4:5]
	v_pk_mul_f32 v[6:7], v[182:183], v[30:31] op_sel_hi:[1,0]
	v_cvt_pk_bf16_f32 v4, v4, v5
	v_pk_mul_f32 v[6:7], v[6:7], v[14:15]
	v_lshlrev_b32_e32 v14, 16, v0
	v_pk_mul_f32 v[6:7], v[6:7], v[32:33]
	v_and_b32_e32 v0, 0xffff0000, v0
	v_cvt_pk_bf16_f32 v5, v6, v7
	v_pk_mul_f32 v[6:7], v[18:19], v[30:31] op_sel_hi:[1,0]
	s_nop 0
	v_pk_mul_f32 v[6:7], v[6:7], v[8:9]
	v_pk_mul_f32 v[8:9], v[16:17], v[30:31] op_sel_hi:[1,0]
	v_pk_mul_f32 v[6:7], v[6:7], v[28:29]
	v_pk_mul_f32 v[8:9], v[8:9], v[10:11]
	v_cvt_pk_bf16_f32 v6, v6, v7
	v_pk_mul_f32 v[8:9], v[26:27], v[8:9]
	s_nop 0
	v_cvt_pk_bf16_f32 v7, v8, v9
	global_store_dwordx4 v[20:21], v[4:7], off offset:32
	global_load_dwordx4 v[4:7], v[72:73], off offset:96
	v_mul_f32_e32 v8, 0xbfb8aa3b, v14
	v_mul_f32_e32 v9, 0xbfb8aa3b, v0
	v_exp_f32_e32 v8, v8
	v_exp_f32_e32 v9, v9
	s_nop 0
	v_pk_add_f32 v[12:13], v[8:9], 1.0 op_sel_hi:[1,0]
	global_load_dwordx4 v[8:11], v[72:73], off offset:112
	v_div_scale_f32 v15, s[2:3], v13, v13, v0
	v_rcp_f32_e32 v16, v15
	s_nop 0
	v_fma_f32 v17, -v15, v16, 1.0
	v_fmac_f32_e32 v16, v17, v16
	v_div_scale_f32 v17, vcc, v0, v13, v0
	v_mul_f32_e32 v18, v17, v16
	v_fma_f32 v19, -v15, v18, v17
	v_fmac_f32_e32 v18, v19, v16
	v_fma_f32 v15, -v15, v18, v17
	v_div_scale_f32 v17, s[2:3], v12, v12, v14
	v_rcp_f32_e32 v19, v17
	v_div_fmas_f32 v15, v15, v16, v18
	v_div_fixup_f32 v13, v15, v13, v0
	v_fma_f32 v0, -v17, v19, 1.0
	v_fmac_f32_e32 v19, v0, v19
	v_div_scale_f32 v0, vcc, v14, v12, v14
	v_mul_f32_e32 v15, v0, v19
	v_fma_f32 v16, -v17, v15, v0
	v_fmac_f32_e32 v15, v16, v19
	v_fma_f32 v0, -v17, v15, v0
	v_div_fmas_f32 v0, v0, v19, v15
	v_lshlrev_b32_e32 v16, 16, v1
	v_and_b32_e32 v17, 0xffff0000, v1
	v_div_fixup_f32 v12, v0, v12, v14
	v_mul_f32_e32 v0, 0xbfb8aa3b, v16
	v_mul_f32_e32 v1, 0xbfb8aa3b, v17
	v_exp_f32_e32 v0, v0
	v_exp_f32_e32 v1, v1
	v_pk_mul_f32 v[14:15], v[192:193], v[30:31] op_sel_hi:[1,0]
	s_waitcnt vmcnt(1)
	v_pk_mul_f32 v[4:5], v[14:15], v[4:5]
	s_nop 0
	v_pk_mul_f32 v[4:5], v[4:5], v[12:13]
	v_pk_add_f32 v[12:13], v[0:1], 1.0 op_sel_hi:[1,0]
	v_cvt_pk_bf16_f32 v0, v4, v5
	v_div_scale_f32 v1, s[2:3], v13, v13, v17
	v_rcp_f32_e32 v14, v1
	v_pk_mul_f32 v[4:5], v[186:187], v[30:31] op_sel_hi:[1,0]
	s_nop 0
	v_pk_mul_f32 v[4:5], v[4:5], v[6:7]
	v_fma_f32 v6, -v1, v14, 1.0
	v_fmac_f32_e32 v14, v6, v14
	v_div_scale_f32 v6, vcc, v17, v13, v17
	v_mul_f32_e32 v7, v6, v14
	v_fma_f32 v15, -v1, v7, v6
	v_fmac_f32_e32 v7, v15, v14
	v_fma_f32 v1, -v1, v7, v6
	v_div_scale_f32 v6, s[2:3], v12, v12, v16
	v_rcp_f32_e32 v18, v6
	v_div_fmas_f32 v1, v1, v14, v7
	v_div_fixup_f32 v7, v1, v13, v17
	v_lshlrev_b32_e32 v17, 16, v2
	v_fma_f32 v1, -v6, v18, 1.0
	v_fmac_f32_e32 v18, v1, v18
	v_div_scale_f32 v1, vcc, v16, v12, v16
	v_mul_f32_e32 v13, v1, v18
	v_fma_f32 v14, -v6, v13, v1
	v_fmac_f32_e32 v13, v14, v18
	v_fma_f32 v1, -v6, v13, v1
	v_and_b32_e32 v2, 0xffff0000, v2
	v_mul_f32_e32 v6, 0xbfb8aa3b, v17
	v_exp_f32_e32 v14, v6
	v_mul_f32_e32 v6, 0xbfb8aa3b, v2
	v_exp_f32_e32 v15, v6
	v_div_fmas_f32 v1, v1, v18, v13
	v_div_fixup_f32 v6, v1, v12, v16
	v_pk_mul_f32 v[4:5], v[4:5], v[6:7]
	v_pk_add_f32 v[6:7], v[14:15], 1.0 op_sel_hi:[1,0]
	v_cvt_pk_bf16_f32 v1, v4, v5
	v_div_scale_f32 v12, s[2:3], v7, v7, v2
	v_rcp_f32_e32 v13, v12
	v_pk_mul_f32 v[4:5], v[24:25], v[30:31] op_sel_hi:[1,0]
	s_waitcnt vmcnt(0)
	v_pk_mul_f32 v[4:5], v[4:5], v[8:9]
	v_fma_f32 v8, -v12, v13, 1.0
	v_fmac_f32_e32 v13, v8, v13
	v_div_scale_f32 v8, vcc, v2, v7, v2
	v_mul_f32_e32 v9, v8, v13
	v_fma_f32 v14, -v12, v9, v8
	v_fmac_f32_e32 v9, v14, v13
	v_fma_f32 v8, -v12, v9, v8
	v_div_scale_f32 v12, s[2:3], v6, v6, v17
	v_rcp_f32_e32 v14, v12
	v_div_fmas_f32 v8, v8, v13, v9
	v_div_fixup_f32 v7, v8, v7, v2
	v_and_b32_e32 v13, 0xffff0000, v3
	v_fma_f32 v2, -v12, v14, 1.0
	v_fmac_f32_e32 v14, v2, v14
	v_div_scale_f32 v2, vcc, v17, v6, v17
	v_mul_f32_e32 v8, v2, v14
	v_fma_f32 v9, -v12, v8, v2
	v_fmac_f32_e32 v8, v9, v14
	v_fma_f32 v9, -v12, v8, v2
	v_lshlrev_b32_e32 v12, 16, v3
	v_mul_f32_e32 v2, 0xbfb8aa3b, v12
	v_mul_f32_e32 v3, 0xbfb8aa3b, v13
	v_exp_f32_e32 v2, v2
	v_exp_f32_e32 v3, v3
	v_div_fmas_f32 v8, v9, v14, v8
	v_div_fixup_f32 v6, v8, v6, v17
	v_pk_mul_f32 v[4:5], v[4:5], v[6:7]
	v_pk_add_f32 v[6:7], v[2:3], 1.0 op_sel_hi:[1,0]
	v_cvt_pk_bf16_f32 v2, v4, v5
	v_div_scale_f32 v3, s[2:3], v7, v7, v13
	v_rcp_f32_e32 v8, v3
	v_pk_mul_f32 v[4:5], v[22:23], v[30:31] op_sel_hi:[1,0]
	v_fma_f32 v9, -v3, v8, 1.0
	v_fmac_f32_e32 v8, v9, v8
	v_div_scale_f32 v9, vcc, v13, v7, v13
	v_pk_mul_f32 v[4:5], v[4:5], v[10:11]
	v_mul_f32_e32 v10, v9, v8
	v_fma_f32 v11, -v3, v10, v9
	v_fmac_f32_e32 v10, v11, v8
	v_fma_f32 v3, -v3, v10, v9
	v_div_scale_f32 v9, s[2:3], v6, v6, v12
	v_rcp_f32_e32 v11, v9
	v_div_fmas_f32 v3, v3, v8, v10
	v_div_fixup_f32 v7, v3, v7, v13
	v_fma_f32 v3, -v9, v11, 1.0
	v_fmac_f32_e32 v11, v3, v11
	v_div_scale_f32 v3, vcc, v12, v6, v12
	v_mul_f32_e32 v8, v3, v11
	v_fma_f32 v10, -v9, v8, v3
	v_fmac_f32_e32 v8, v10, v11
	v_fma_f32 v3, -v9, v8, v3
	v_div_fmas_f32 v3, v3, v11, v8
	v_div_fixup_f32 v6, v3, v6, v12
	v_pk_mul_f32 v[4:5], v[6:7], v[4:5]
	s_nop 0
	v_cvt_pk_bf16_f32 v3, v4, v5
	global_store_dwordx4 v[20:21], v[0:3], off offset:48
	s_barrier
	s_cbranch_scc1 .LBB0_602

.LBB0_1086:
	s_lshl_b64 s[58:59], s[8:9], 10
	s_lshl_b64 s[64:65], s[8:9], 11
	v_mov_b32_e32 v245, v151
	s_lshl_b32 s8, s68, 7
	v_lshl_add_u64 v[0:1], s[62:63], 0, v[244:245]
	v_mov_b32_e32 v165, v151
	v_mov_b32_e32 v247, v151
	s_add_u32 s70, s62, s8
	v_lshl_add_u64 v[0:1], v[0:1], 0, v[164:165]
	v_lshl_add_u64 v[2:3], s[62:63], 0, v[246:247]
	s_addc_u32 s71, s63, 0
	v_lshl_add_u64 v[2:3], v[2:3], 0, v[164:165]
	global_load_dwordx4 v[32:35], v[0:1], off
	global_load_dwordx4 v[36:39], v[2:3], off
	v_lshl_add_u64 v[0:1], s[70:71], 0, v[244:245]
	v_lshl_add_u64 v[0:1], v[0:1], 0, v[164:165]
	v_lshl_add_u64 v[2:3], s[70:71], 0, v[246:247]
	v_lshl_add_u64 v[2:3], v[2:3], 0, v[164:165]
	global_load_dwordx4 v[40:43], v[0:1], off
	global_load_dwordx4 v[44:47], v[2:3], off
	v_accvgpr_read_b32 v0, a209
	v_mul_u32_u24_e32 v0, s68, v0
	v_lshlrev_b32_e32 v64, 1, v0
	v_mov_b32_e32 v65, v151
	v_mul_u32_u24_e32 v2, s68, v154
	v_lshl_add_u64 v[0:1], s[60:61], 0, v[64:65]
	v_lshlrev_b32_e32 v66, 1, v2
	v_mov_b32_e32 v67, v151
	v_lshl_add_u64 v[0:1], v[0:1], 0, v[164:165]
	v_lshl_add_u64 v[2:3], s[60:61], 0, v[66:67]
	v_lshl_add_u64 v[2:3], v[2:3], 0, v[164:165]
	global_load_dwordx4 v[48:51], v[0:1], off
	global_load_dwordx4 v[52:55], v[2:3], off
	v_mul_u32_u24_e32 v0, s68, v155
	v_lshlrev_b32_e32 v68, 1, v0
	v_mov_b32_e32 v69, v151
	v_mul_u32_u24_e32 v2, s68, v162
	v_lshl_add_u64 v[0:1], s[60:61], 0, v[68:69]
	v_lshlrev_b32_e32 v70, 1, v2
	v_mov_b32_e32 v71, v151
	v_lshl_add_u64 v[0:1], v[0:1], 0, v[164:165]
	v_lshl_add_u64 v[2:3], s[60:61], 0, v[70:71]
	v_lshl_add_u64 v[2:3], v[2:3], 0, v[164:165]
	global_load_dwordx4 v[56:59], v[0:1], off
	global_load_dwordx4 v[60:63], v[2:3], off
	v_mov_b32_e32 v251, v151
	v_lshl_add_u64 v[0:1], v[168:169], 0, s[64:65]
	v_lshl_add_u64 v[2:3], v[0:1], 0, v[150:151]
	v_lshl_add_u64 v[0:1], v[0:1], 0, v[250:251]
	global_load_dwordx4 v[28:31], v[2:3], off
	global_load_dwordx4 v[24:27], v[2:3], off offset:32
	global_load_dwordx4 v[20:23], v[2:3], off offset:64
	global_load_dwordx4 v[16:19], v[2:3], off offset:96
	global_load_dwordx4 v[12:15], v[0:1], off
	global_load_dwordx4 v[8:11], v[0:1], off offset:32
	global_load_dwordx4 v[4:7], v[0:1], off offset:64
	s_nop 0
	global_load_dwordx4 v[0:3], v[0:1], off offset:96
	v_lshl_add_u64 v[82:83], s[62:63], 0, v[170:171]
	v_lshl_add_u64 v[84:85], s[62:63], 0, v[242:243]
	v_lshl_add_u64 v[86:87], v[82:83], 0, s[8:9]
	v_lshl_add_u64 v[88:89], v[84:85], 0, s[8:9]
	s_add_i32 s8, s67, 1
	s_add_u32 s60, s60, 0x80
	v_mov_b32_e32 v80, 0
	s_addc_u32 s61, s61, 0
	v_accvgpr_write_b32 a31, 0
	v_accvgpr_write_b32 a30, 0
	v_accvgpr_write_b32 a29, 0
	v_accvgpr_write_b32 a28, 0
	v_accvgpr_write_b32 a27, 0
	v_accvgpr_write_b32 a26, 0
	v_accvgpr_write_b32 a25, 0
	v_accvgpr_write_b32 a24, 0
	v_accvgpr_write_b32 a23, 0
	v_accvgpr_write_b32 a22, 0
	v_lshl_add_u64 v[90:91], s[60:61], 0, v[64:65]
	v_lshl_add_u64 v[92:93], s[60:61], 0, v[66:67]
	v_lshl_add_u64 v[94:95], s[60:61], 0, v[68:69]
	v_lshl_add_u64 v[96:97], s[60:61], 0, v[70:71]
	v_accvgpr_write_b32 a21, 0
	v_accvgpr_write_b32 a20, 0
	v_accvgpr_write_b32 a19, 0
	v_accvgpr_write_b32 a18, 0
	v_accvgpr_write_b32 a17, 0
	v_accvgpr_write_b32 a16, 0
	v_accvgpr_write_b32 a111, 0
	v_accvgpr_write_b32 a110, 0
	v_accvgpr_write_b32 a109, 0
	v_accvgpr_write_b32 a108, 0
	v_accvgpr_write_b32 a107, 0
	v_accvgpr_write_b32 a106, 0
	v_accvgpr_write_b32 a105, 0
	v_accvgpr_write_b32 a104, 0
	v_accvgpr_write_b32 a103, 0
	v_accvgpr_write_b32 a102, 0
	v_accvgpr_write_b32 a101, 0
	v_accvgpr_write_b32 a100, 0
	v_accvgpr_write_b32 a99, 0
	v_accvgpr_write_b32 a98, 0
	v_accvgpr_write_b32 a97, 0
	v_accvgpr_write_b32 a96, 0
	v_accvgpr_write_b32 a143, 0
	v_accvgpr_write_b32 a142, 0
	v_accvgpr_write_b32 a141, 0
	v_accvgpr_write_b32 a140, 0
	v_accvgpr_write_b32 a139, 0
	v_accvgpr_write_b32 a138, 0
	v_accvgpr_write_b32 a137, 0
	v_accvgpr_write_b32 a136, 0
	v_accvgpr_write_b32 a135, 0
	v_accvgpr_write_b32 a134, 0
	v_accvgpr_write_b32 a133, 0
	v_accvgpr_write_b32 a132, 0
	v_accvgpr_write_b32 a131, 0
	v_accvgpr_write_b32 a130, 0
	v_accvgpr_write_b32 a129, 0
	v_accvgpr_write_b32 a128, 0
	v_accvgpr_write_b32 a63, 0
	v_accvgpr_write_b32 a62, 0
	v_accvgpr_write_b32 a61, 0
	v_accvgpr_write_b32 a60, 0
	v_accvgpr_write_b32 a59, 0
	v_accvgpr_write_b32 a58, 0
	v_accvgpr_write_b32 a57, 0
	v_accvgpr_write_b32 a56, 0
	v_accvgpr_write_b32 a55, 0
	v_accvgpr_write_b32 a54, 0
	v_accvgpr_write_b32 a53, 0
	v_accvgpr_write_b32 a52, 0
	v_accvgpr_write_b32 a51, 0
	v_accvgpr_write_b32 a50, 0
	v_accvgpr_write_b32 a49, 0
	v_accvgpr_write_b32 a48, 0
	v_accvgpr_write_b32 a95, 0
	v_accvgpr_write_b32 a94, 0
	v_accvgpr_write_b32 a93, 0
	v_accvgpr_write_b32 a92, 0
	v_accvgpr_write_b32 a91, 0
	v_accvgpr_write_b32 a90, 0
	v_accvgpr_write_b32 a89, 0
	v_accvgpr_write_b32 a88, 0
	v_accvgpr_write_b32 a87, 0
	v_accvgpr_write_b32 a86, 0
	v_accvgpr_write_b32 a85, 0
	v_accvgpr_write_b32 a84, 0
	v_accvgpr_write_b32 a83, 0
	v_accvgpr_write_b32 a82, 0
	v_accvgpr_write_b32 a81, 0
	v_accvgpr_write_b32 a80, 0
	v_accvgpr_write_b32 a47, 0
	v_accvgpr_write_b32 a46, 0
	v_accvgpr_write_b32 a45, 0
	v_accvgpr_write_b32 a44, 0
	v_accvgpr_write_b32 a43, 0
	v_accvgpr_write_b32 a42, 0
	v_accvgpr_write_b32 a41, 0
	v_accvgpr_write_b32 a40, 0
	v_accvgpr_write_b32 a39, 0
	v_accvgpr_write_b32 a38, 0
	v_accvgpr_write_b32 a37, 0
	v_accvgpr_write_b32 a36, 0
	v_accvgpr_write_b32 a35, 0
	v_accvgpr_write_b32 a34, 0
	v_accvgpr_write_b32 a33, 0
	v_accvgpr_write_b32 a32, 0
	v_accvgpr_write_b32 a127, 0
	v_accvgpr_write_b32 a126, 0
	v_accvgpr_write_b32 a125, 0
	v_accvgpr_write_b32 a124, 0
	v_accvgpr_write_b32 a123, 0
	v_accvgpr_write_b32 a122, 0
	v_accvgpr_write_b32 a121, 0
	v_accvgpr_write_b32 a120, 0
	v_accvgpr_write_b32 a119, 0
	v_accvgpr_write_b32 a118, 0
	v_accvgpr_write_b32 a117, 0
	v_accvgpr_write_b32 a116, 0
	v_accvgpr_write_b32 a115, 0
	v_accvgpr_write_b32 a114, 0
	v_accvgpr_write_b32 a113, 0
	v_accvgpr_write_b32 a112, 0
	v_accvgpr_write_b32 a79, 0
	v_accvgpr_write_b32 a78, 0
	v_accvgpr_write_b32 a77, 0
	v_accvgpr_write_b32 a76, 0
	v_accvgpr_write_b32 a75, 0
	v_accvgpr_write_b32 a74, 0
	v_accvgpr_write_b32 a73, 0
	v_accvgpr_write_b32 a72, 0
	v_accvgpr_write_b32 a71, 0
	v_accvgpr_write_b32 a70, 0
	v_accvgpr_write_b32 a69, 0
	v_accvgpr_write_b32 a68, 0
	v_accvgpr_write_b32 a67, 0
	v_accvgpr_write_b32 a66, 0
	v_accvgpr_write_b32 a65, 0
	v_accvgpr_write_b32 a64, 0
	s_mov_b32 s60, 0
	v_mov_b32_e32 v81, v80
	s_waitcnt vmcnt(15)
	ds_write_b128 v129, v[32:35]
	s_waitcnt vmcnt(14)
	ds_write_b128 v135, v[36:39]
	s_waitcnt vmcnt(13)
	ds_write_b128 v129, v[40:43] offset:9216
	s_waitcnt vmcnt(12)
	ds_write_b128 v135, v[44:47] offset:9216
	s_waitcnt vmcnt(11)
	ds_write_b128 v129, v[48:51] offset:36864
	s_waitcnt vmcnt(10)
	ds_write_b128 v135, v[52:55] offset:36864
	s_waitcnt vmcnt(9)
	ds_write_b128 v163, v[56:59] offset:36864
	s_waitcnt vmcnt(8)
	ds_write_b128 v166, v[60:63] offset:36864
	v_accvgpr_write_b32 a160, 0
	v_mov_b32_e32 v48, 0
	v_accvgpr_write_b32 a161, 0
	v_mov_b32_e32 v49, 0
	v_accvgpr_write_b32 a162, 0
	v_mov_b32_e32 v50, 0
	v_accvgpr_write_b32 a163, 0
	v_mov_b32_e32 v51, 0
	v_accvgpr_write_b32 a164, 0
	v_mov_b32_e32 v52, 0
	v_accvgpr_write_b32 a165, 0
	v_mov_b32_e32 v53, 0
	v_accvgpr_write_b32 a166, 0
	v_mov_b32_e32 v54, 0
	v_accvgpr_write_b32 a167, 0
	v_mov_b32_e32 v55, 0
	v_accvgpr_write_b32 a168, 0
	v_mov_b32_e32 v56, 0
	v_accvgpr_write_b32 a169, 0
	v_mov_b32_e32 v57, 0
	v_accvgpr_write_b32 a170, 0
	v_mov_b32_e32 v58, 0
	v_accvgpr_write_b32 a171, 0
	v_mov_b32_e32 v59, 0
	v_accvgpr_write_b32 a172, 0
	v_mov_b32_e32 v60, 0
	v_accvgpr_write_b32 a173, 0
	v_mov_b32_e32 v61, 0
	v_accvgpr_write_b32 a174, 0
	v_mov_b32_e32 v62, 0
	v_accvgpr_write_b32 a175, 0
	v_mov_b32_e32 v63, 0
	v_accvgpr_write_b32 a176, 0
	v_mov_b32_e32 v116, 0
	v_accvgpr_write_b32 a177, 0
	v_mov_b32_e32 v117, 0
	v_accvgpr_write_b32 a178, 0
	v_mov_b32_e32 v118, 0
	v_accvgpr_write_b32 a179, 0
	v_mov_b32_e32 v119, 0
	v_accvgpr_write_b32 a180, 0
	v_mov_b32_e32 v120, 0
	v_accvgpr_write_b32 a181, 0
	v_mov_b32_e32 v121, 0
	v_accvgpr_write_b32 a182, 0
	v_mov_b32_e32 v122, 0
	v_accvgpr_write_b32 a183, 0
	v_mov_b32_e32 v123, 0
	v_accvgpr_write_b32 a184, 0
	v_mov_b32_e32 v124, 0
	v_accvgpr_write_b32 a185, 0
	v_mov_b32_e32 v125, 0
	v_accvgpr_write_b32 a186, 0
	v_mov_b32_e32 v126, 0
	v_accvgpr_write_b32 a187, 0
	v_mov_b32_e32 v127, 0
	v_accvgpr_write_b32 a188, 0
	v_mov_b32_e32 v130, 0
	v_accvgpr_write_b32 a189, 0
	v_mov_b32_e32 v131, 0
	v_accvgpr_write_b32 a190, 0
	v_mov_b32_e32 v132, 0
	v_accvgpr_write_b32 a191, 0
	v_mov_b32_e32 v133, 0
	v_mov_b32_e32 v204, 0
	v_mov_b32_e32 v205, 0
	v_mov_b32_e32 v206, 0
	v_mov_b32_e32 v207, 0
	v_mov_b32_e32 v208, 0
	v_mov_b32_e32 v209, 0
	v_mov_b32_e32 v210, 0
	v_mov_b32_e32 v211, 0
	v_mov_b32_e32 v212, 0
	v_mov_b32_e32 v213, 0
	v_mov_b32_e32 v214, 0
	v_mov_b32_e32 v215, 0
	v_mov_b32_e32 v216, 0
	v_mov_b32_e32 v217, 0
	v_mov_b32_e32 v218, 0
	v_mov_b32_e32 v219, 0
	v_mov_b32_e32 v136, 0
	v_mov_b32_e32 v137, 0
	v_mov_b32_e32 v100, 0
	v_mov_b32_e32 v101, 0
	v_mov_b32_e32 v102, 0
	v_mov_b32_e32 v103, 0
	v_mov_b32_e32 v104, 0
	v_mov_b32_e32 v105, 0
	v_mov_b32_e32 v106, 0
	v_mov_b32_e32 v107, 0
	v_mov_b32_e32 v108, 0
	v_mov_b32_e32 v109, 0
	v_mov_b32_e32 v110, 0
	v_mov_b32_e32 v111, 0
	v_mov_b32_e32 v112, 0
	v_mov_b32_e32 v113, 0
	v_mov_b32_e32 v114, 0
	v_mov_b32_e32 v115, 0
	v_mov_b32_e32 v148, 0
	v_mov_b32_e32 v149, 0
	v_accvgpr_read_b32 v32, a0
	v_accvgpr_read_b32 v33, a0
	v_accvgpr_read_b32 v34, a0
	v_accvgpr_read_b32 v35, a0
	v_accvgpr_read_b32 v36, a0
	v_accvgpr_read_b32 v37, a0
	v_accvgpr_read_b32 v38, a0
	v_accvgpr_read_b32 v39, a0
	v_accvgpr_read_b32 v40, a0
	v_accvgpr_read_b32 v41, a0
	v_accvgpr_read_b32 v42, a0
	v_accvgpr_read_b32 v43, a0
	v_accvgpr_read_b32 v44, a0
	v_accvgpr_read_b32 v45, a0
	v_accvgpr_read_b32 v46, a0
	v_accvgpr_read_b32 v47, a0
	v_mbcnt_lo_u32_b32 v235, -1, 0
	v_mbcnt_hi_u32_b32 v235, -1, v235
	v_lshlrev_b32_e32 v235, 4, v235
	v_add_u32_e32 v235, 0xd800, v235
	s_waitcnt lgkmcnt(0)
	ds_write_b128 v235, a[160:163]
	ds_write_b128 v235, a[160:163] offset:1024
	ds_write_b128 v235, a[160:163] offset:2048
	ds_write_b128 v235, a[160:163] offset:3072
	ds_write_b128 v235, a[160:163] offset:4096
	ds_write_b128 v235, a[160:163] offset:5120
	ds_write_b128 v235, a[160:163] offset:6144
	ds_write_b128 v235, a[160:163] offset:7168
	ds_write_b128 v235, a[160:163] offset:8192
	s_waitcnt lgkmcnt(0)
	ds_write_b128 v235, a[160:163] offset:9216
	ds_write_b128 v235, a[160:163] offset:10240
	ds_write_b128 v235, a[160:163] offset:11264
	ds_write_b128 v235, a[160:163] offset:12288
	ds_write_b128 v235, a[160:163] offset:13312
	ds_write_b128 v235, a[160:163] offset:14336
	ds_write_b128 v235, a[160:163] offset:15360
	ds_write_b128 v235, a[160:163] offset:16384
	ds_write_b128 v235, a[160:163] offset:17408
.LBB0_1087:
	s_and_b32 s61, s60, 1
	s_xor_b32 s62, s61, 1
	s_mulk_i32 s61, 0x4800
	s_mulk_i32 s62, 0x4800
	v_add_u32_e32 v233, s61, v128
	v_add_u32_e32 v234, s62, v152
	s_waitcnt vmcnt(0) lgkmcnt(0)
	s_barrier
	ds_read_b128 a[144:147], v233
	ds_read_b128 a[148:151], v233 offset:32
	ds_read_b128 a[152:155], v233 offset:64
	ds_read_b128 a[156:159], v233 offset:96
	s_waitcnt lgkmcnt(3)
	v_mfma_f32_32x32x16_bf16 v[188:203], a[144:147], v[28:31], v[32:47]
	v_pk_add_f32 v[136:137], v[136:137], v[204:205]
	v_pk_add_f32 v[136:137], v[136:137], v[206:207]
	v_pk_add_f32 v[136:137], v[136:137], v[208:209]
	v_pk_add_f32 v[136:137], v[136:137], v[210:211]
	v_pk_add_f32 v[136:137], v[136:137], v[212:213]
	v_pk_add_f32 v[136:137], v[136:137], v[214:215]
	s_cmp_eq_u32 s60, 0
	s_cselect_b32 s32, 0x9000, s61
	v_mfma_f32_32x32x16_bf16 v[172:187], a[144:147], v[12:15], v[32:47]
	v_pk_add_f32 v[136:137], v[136:137], v[216:217]
	v_pk_add_f32 v[136:137], v[136:137], v[218:219]
	v_cvt_pk_bf16_f32 v56, v204, v205
	v_cvt_pk_bf16_f32 v57, v206, v207
	v_cvt_pk_bf16_f32 v58, v208, v209
	v_add3_u32 v224, s32, v153, v134
	ds_read_b128 a[144:147], v233 offset:4608
	s_waitcnt lgkmcnt(3)
	v_mfma_f32_32x32x16_bf16 v[188:203], a[148:151], v[24:27], v[188:203]
	v_cvt_pk_bf16_f32 v59, v210, v211
	v_cvt_pk_bf16_f32 v60, v212, v213
	v_cvt_pk_bf16_f32 v61, v214, v215
	v_cvt_pk_bf16_f32 v62, v216, v217
	v_cvt_pk_bf16_f32 v63, v218, v219
	v_add3_u32 v230, s32, v158, v134
	v_mfma_f32_32x32x16_bf16 v[172:187], a[148:151], v[8:11], v[172:187]
	v_add_f32_e32 v235, v136, v137
	v_add_f32_e32 v81, v81, v235
	v_pk_add_f32 v[148:149], v[148:149], v[100:101]
	v_pk_add_f32 v[148:149], v[148:149], v[102:103]
	v_pk_add_f32 v[148:149], v[148:149], v[104:105]
	v_add3_u32 v231, s32, v159, v134
	ds_read_b128 a[148:151], v233 offset:4640
	s_waitcnt lgkmcnt(3)
	v_mfma_f32_32x32x16_bf16 v[188:203], a[152:155], v[20:23], v[188:203]
	v_pk_add_f32 v[148:149], v[148:149], v[106:107]
	v_pk_add_f32 v[148:149], v[148:149], v[108:109]
	v_pk_add_f32 v[148:149], v[148:149], v[110:111]
	v_pk_add_f32 v[148:149], v[148:149], v[112:113]
	v_pk_add_f32 v[148:149], v[148:149], v[114:115]
	v_add3_u32 v232, s32, v160, v134
	v_mfma_f32_32x32x16_bf16 v[172:187], a[152:155], v[4:7], v[172:187]
	v_cvt_pk_bf16_f32 v124, v100, v101
	v_cvt_pk_bf16_f32 v125, v102, v103
	v_cvt_pk_bf16_f32 v126, v104, v105
	v_cvt_pk_bf16_f32 v127, v106, v107
	v_cvt_pk_bf16_f32 v130, v108, v109
	ds_write_b128 v224, v[140:143] offset:36864
	ds_read_b128 a[152:155], v233 offset:4672
	s_waitcnt lgkmcnt(4)
	v_mfma_f32_32x32x16_bf16 v[188:203], a[156:159], v[16:19], v[188:203]
	v_cvt_pk_bf16_f32 v131, v110, v111
	v_cvt_pk_bf16_f32 v132, v112, v113
	v_cvt_pk_bf16_f32 v133, v114, v115
	v_add_f32_e32 v235, v148, v149
	v_add_f32_e32 v80, v80, v235
	ds_write_b128 v230, v[144:147] offset:36864
	v_mfma_f32_32x32x16_bf16 v[172:187], a[156:159], v[0:3], v[172:187]
	ds_write_b128 v231, v[220:223] offset:36864
	ds_read_b128 a[156:159], v233 offset:4704
	s_waitcnt lgkmcnt(6)
	v_mfma_f32_32x32x16_bf16 v[204:219], a[144:147], v[28:31], v[32:47]
	ds_write_b128 v232, v[226:229] offset:36864
	v_lshl_add_u64 v[98:99], v[82:83], 0, v[156:157]
	global_load_dwordx4 v[64:67], v[98:99], off
	v_lshl_add_u64 v[98:99], v[84:85], 0, v[156:157]
	global_load_dwordx4 v[68:71], v[98:99], off
	v_lshl_add_u64 v[98:99], v[86:87], 0, v[156:157]
	v_mfma_f32_32x32x16_bf16 v[100:115], a[144:147], v[12:15], v[32:47]
	global_load_dwordx4 v[72:75], v[98:99], off
	v_lshl_add_u64 v[98:99], v[88:89], 0, v[156:157]
	global_load_dwordx4 v[76:79], v[98:99], off
	v_accvgpr_write_b32 a160, v48
	v_accvgpr_write_b32 a161, v49
	v_accvgpr_write_b32 a162, v50
	s_waitcnt lgkmcnt(6)
	v_mfma_f32_32x32x16_bf16 v[204:219], a[148:151], v[24:27], v[204:219]
	v_accvgpr_write_b32 a163, v51
	v_accvgpr_write_b32 a164, v52
	v_accvgpr_write_b32 a165, v53
	v_accvgpr_write_b32 a166, v54
	v_accvgpr_write_b32 a167, v55
	v_mfma_f32_32x32x16_bf16 v[100:115], a[148:151], v[8:11], v[100:115]
	v_accvgpr_write_b32 a176, v116
	v_accvgpr_write_b32 a177, v117
	v_accvgpr_write_b32 a178, v118
	v_accvgpr_write_b32 a179, v119
	v_accvgpr_write_b32 a180, v120
	v_accvgpr_write_b32 a181, v121
	s_waitcnt lgkmcnt(4)
	v_mfma_f32_32x32x16_bf16 v[204:219], a[152:155], v[20:23], v[204:219]
	v_accvgpr_write_b32 a182, v122
	v_accvgpr_write_b32 a183, v123
	v_lshl_add_u64 v[82:83], v[82:83], 0, s[54:55]
	v_lshl_add_u64 v[84:85], v[84:85], 0, s[54:55]
	v_lshl_add_u64 v[86:87], v[86:87], 0, s[54:55]
	v_lshl_add_u64 v[88:89], v[88:89], 0, s[54:55]
	v_mfma_f32_32x32x16_bf16 v[100:115], a[152:155], v[4:7], v[100:115]
	v_accvgpr_write_b32 a168, v56
	v_accvgpr_write_b32 a169, v57
	v_accvgpr_write_b32 a170, v58
	v_accvgpr_write_b32 a171, v59
	v_accvgpr_write_b32 a172, v60
	s_waitcnt lgkmcnt(1)
	v_mfma_f32_32x32x16_bf16 v[204:219], a[156:159], v[16:19], v[204:219]
	v_accvgpr_write_b32 a173, v61
	v_accvgpr_write_b32 a174, v62
	v_accvgpr_write_b32 a175, v63
	v_accvgpr_write_b32 a184, v124
	v_accvgpr_write_b32 a185, v125
	v_accvgpr_write_b32 a186, v126
	v_mfma_f32_32x32x16_bf16 v[100:115], a[156:159], v[0:3], v[100:115]
	v_accvgpr_write_b32 a187, v127
	v_accvgpr_write_b32 a188, v130
	v_accvgpr_write_b32 a189, v131
	v_accvgpr_write_b32 a190, v132
	v_accvgpr_write_b32 a191, v133
	ds_read_b128 a[144:147], v234 offset:36864
	ds_read_b128 a[148:151], v234 offset:36896
	ds_read_b128 a[152:155], v234 offset:36928
	ds_read_b128 a[156:159], v234 offset:36960
	s_waitcnt lgkmcnt(3)
	v_mfma_f32_32x32x16_bf16 a[128:143], a[144:147], a[160:163], a[128:143]
	v_exp_f32_e32 v188, v188
	v_exp_f32_e32 v189, v189
	v_exp_f32_e32 v190, v190
	v_mfma_f32_32x32x16_bf16 a[112:127], a[144:147], a[176:179], a[112:127]
	v_exp_f32_e32 v191, v191
	v_exp_f32_e32 v192, v192
	v_exp_f32_e32 v193, v193
	ds_read_b128 a[144:147], v234 offset:41472
	s_waitcnt lgkmcnt(3)
	v_mfma_f32_32x32x16_bf16 a[128:143], a[148:151], a[164:167], a[128:143]
	v_exp_f32_e32 v194, v194
	v_exp_f32_e32 v195, v195
	v_exp_f32_e32 v196, v196
	v_mfma_f32_32x32x16_bf16 a[112:127], a[148:151], a[180:183], a[112:127]
	v_exp_f32_e32 v197, v197
	v_exp_f32_e32 v198, v198
	v_exp_f32_e32 v199, v199
	ds_read_b128 a[148:151], v234 offset:41504
	s_waitcnt lgkmcnt(3)
	v_mfma_f32_32x32x16_bf16 a[128:143], a[152:155], a[168:171], a[128:143]
	v_exp_f32_e32 v200, v200
	v_exp_f32_e32 v201, v201
	v_exp_f32_e32 v202, v202
	v_mfma_f32_32x32x16_bf16 a[112:127], a[152:155], a[184:187], a[112:127]
	v_exp_f32_e32 v203, v203
	v_pk_add_f32 v[136:137], v[188:189], v[190:191]
	v_pk_add_f32 v[136:137], v[136:137], v[192:193]
	ds_read_b128 a[152:155], v234 offset:41536
	s_waitcnt lgkmcnt(3)
	v_mfma_f32_32x32x16_bf16 a[128:143], a[156:159], a[172:175], a[128:143]
	v_pk_add_f32 v[136:137], v[136:137], v[194:195]
	v_pk_add_f32 v[136:137], v[136:137], v[196:197]
	v_pk_add_f32 v[136:137], v[136:137], v[198:199]
	v_mfma_f32_32x32x16_bf16 a[112:127], a[156:159], a[188:191], a[112:127]
	v_pk_add_f32 v[136:137], v[136:137], v[200:201]
	v_pk_add_f32 v[136:137], v[136:137], v[202:203]
	v_cvt_pk_bf16_f32 v48, v188, v189
	v_cvt_pk_bf16_f32 v49, v190, v191
	ds_read_b128 a[156:159], v234 offset:41568
	s_waitcnt lgkmcnt(3)
	v_mfma_f32_32x32x16_bf16 a[48:63], a[144:147], a[160:163], a[48:63]
	v_cvt_pk_bf16_f32 v50, v192, v193
	v_cvt_pk_bf16_f32 v51, v194, v195
	v_cvt_pk_bf16_f32 v52, v196, v197
	v_cvt_pk_bf16_f32 v53, v198, v199
	v_cvt_pk_bf16_f32 v54, v200, v201
	v_cvt_pk_bf16_f32 v55, v202, v203
	v_mfma_f32_32x32x16_bf16 a[64:79], a[144:147], a[176:179], a[64:79]
	v_add3_u32 v224, s62, v153, v134
	v_add3_u32 v230, s62, v158, v134
	s_waitcnt vmcnt(3)
	ds_write_b128 v224, v[64:67]
	s_waitcnt vmcnt(2)
	ds_write_b128 v230, v[68:71]
	s_waitcnt vmcnt(1)
	ds_read_b128 a[144:147], v234 offset:46080
	s_waitcnt lgkmcnt(5)
	v_mfma_f32_32x32x16_bf16 a[48:63], a[148:151], a[164:167], a[48:63]
	ds_write_b128 v224, v[72:75] offset:9216
	s_waitcnt vmcnt(0)
	ds_write_b128 v230, v[76:79] offset:9216
	v_lshl_add_u64 v[98:99], v[90:91], 0, v[156:157]
	global_load_dwordx4 v[140:143], v[98:99], off
	v_mfma_f32_32x32x16_bf16 a[64:79], a[148:151], a[180:183], a[64:79]
	v_lshl_add_u64 v[98:99], v[92:93], 0, v[156:157]
	global_load_dwordx4 v[144:147], v[98:99], off
	v_lshl_add_u64 v[98:99], v[94:95], 0, v[156:157]
	global_load_dwordx4 v[220:223], v[98:99], off
	v_lshl_add_u64 v[98:99], v[96:97], 0, v[156:157]
	global_load_dwordx4 v[226:229], v[98:99], off
	ds_read_b128 a[148:151], v234 offset:46112
	s_waitcnt lgkmcnt(7)
	v_mfma_f32_32x32x16_bf16 a[48:63], a[152:155], a[168:171], a[48:63]
	v_lshl_add_u64 v[90:91], v[90:91], 0, s[56:57]
	v_lshl_add_u64 v[92:93], v[92:93], 0, s[56:57]
	v_lshl_add_u64 v[94:95], v[94:95], 0, s[56:57]
	v_lshl_add_u64 v[96:97], v[96:97], 0, s[56:57]
	v_exp_f32_e32 v172, v172
	v_mfma_f32_32x32x16_bf16 a[64:79], a[152:155], a[184:187], a[64:79]
	v_exp_f32_e32 v173, v173
	v_exp_f32_e32 v174, v174
	v_exp_f32_e32 v175, v175
	ds_read_b128 a[152:155], v234 offset:46144
	s_waitcnt lgkmcnt(7)
	v_mfma_f32_32x32x16_bf16 a[48:63], a[156:159], a[172:175], a[48:63]
	v_exp_f32_e32 v176, v176
	v_exp_f32_e32 v177, v177
	v_exp_f32_e32 v178, v178
	v_mfma_f32_32x32x16_bf16 a[64:79], a[156:159], a[188:191], a[64:79]
	v_exp_f32_e32 v179, v179
	v_exp_f32_e32 v180, v180
	v_exp_f32_e32 v181, v181
	ds_read_b128 a[156:159], v234 offset:46176
	s_waitcnt lgkmcnt(5)
	v_mfma_f32_32x32x16_bf16 a[80:95], a[144:147], a[160:163], a[80:95]
	v_exp_f32_e32 v182, v182
	v_exp_f32_e32 v183, v183
	v_exp_f32_e32 v184, v184
	v_mfma_f32_32x32x16_bf16 a[96:111], a[144:147], a[176:179], a[96:111]
	v_exp_f32_e32 v185, v185
	v_exp_f32_e32 v186, v186
	v_exp_f32_e32 v187, v187
	ds_read_b128 a[144:147], v234 offset:50688
	s_waitcnt lgkmcnt(3)
	v_mfma_f32_32x32x16_bf16 a[80:95], a[148:151], a[164:167], a[80:95]
	v_pk_add_f32 v[148:149], v[172:173], v[174:175]
	v_pk_add_f32 v[148:149], v[148:149], v[176:177]
	v_pk_add_f32 v[148:149], v[148:149], v[178:179]
	v_mfma_f32_32x32x16_bf16 a[96:111], a[148:151], a[180:183], a[96:111]
	v_pk_add_f32 v[148:149], v[148:149], v[180:181]
	v_pk_add_f32 v[148:149], v[148:149], v[182:183]
	v_pk_add_f32 v[148:149], v[148:149], v[184:185]
	ds_read_b128 a[148:151], v234 offset:50720
	s_waitcnt lgkmcnt(3)
	v_mfma_f32_32x32x16_bf16 a[80:95], a[152:155], a[168:171], a[80:95]
	v_pk_add_f32 v[148:149], v[148:149], v[186:187]
	v_cvt_pk_bf16_f32 v116, v172, v173
	v_cvt_pk_bf16_f32 v117, v174, v175
	v_cvt_pk_bf16_f32 v118, v176, v177
	v_cvt_pk_bf16_f32 v119, v178, v179
	v_cvt_pk_bf16_f32 v120, v180, v181
	v_mfma_f32_32x32x16_bf16 a[96:111], a[152:155], a[184:187], a[96:111]
	v_cvt_pk_bf16_f32 v121, v182, v183
	v_cvt_pk_bf16_f32 v122, v184, v185
	v_cvt_pk_bf16_f32 v123, v186, v187
	v_exp_f32_e32 v204, v204
	ds_read_b128 a[152:155], v234 offset:50752
	s_waitcnt lgkmcnt(3)
	v_mfma_f32_32x32x16_bf16 a[80:95], a[156:159], a[172:175], a[80:95]
	v_exp_f32_e32 v205, v205
	v_exp_f32_e32 v206, v206
	v_exp_f32_e32 v207, v207
	v_mfma_f32_32x32x16_bf16 a[96:111], a[156:159], a[188:191], a[96:111]
	v_exp_f32_e32 v208, v208
	v_exp_f32_e32 v209, v209
	v_exp_f32_e32 v210, v210
	ds_read_b128 a[156:159], v234 offset:50784
	s_waitcnt lgkmcnt(3)
	v_mfma_f32_32x32x16_bf16 a[32:47], a[144:147], a[160:163], a[32:47]
	v_exp_f32_e32 v211, v211
	v_exp_f32_e32 v212, v212
	v_exp_f32_e32 v213, v213
	v_mfma_f32_32x32x16_bf16 a[16:31], a[144:147], a[176:179], a[16:31]
	v_exp_f32_e32 v214, v214
	v_exp_f32_e32 v215, v215
	v_exp_f32_e32 v216, v216
	s_waitcnt lgkmcnt(2)
	v_mfma_f32_32x32x16_bf16 a[32:47], a[148:151], a[164:167], a[32:47]
	v_exp_f32_e32 v217, v217
	v_exp_f32_e32 v218, v218
	v_exp_f32_e32 v219, v219
	v_mfma_f32_32x32x16_bf16 a[16:31], a[148:151], a[180:183], a[16:31]
	v_exp_f32_e32 v100, v100
	v_exp_f32_e32 v101, v101
	v_exp_f32_e32 v102, v102
	s_waitcnt lgkmcnt(1)
	v_mfma_f32_32x32x16_bf16 a[32:47], a[152:155], a[168:171], a[32:47]
	v_exp_f32_e32 v103, v103
	v_exp_f32_e32 v104, v104
	v_exp_f32_e32 v105, v105
	v_mfma_f32_32x32x16_bf16 a[16:31], a[152:155], a[184:187], a[16:31]
	v_exp_f32_e32 v106, v106
	v_exp_f32_e32 v107, v107
	v_exp_f32_e32 v108, v108
	s_waitcnt lgkmcnt(0)
	v_mfma_f32_32x32x16_bf16 a[32:47], a[156:159], a[172:175], a[32:47]
	v_exp_f32_e32 v109, v109
	v_exp_f32_e32 v110, v110
	v_exp_f32_e32 v111, v111
	v_mfma_f32_32x32x16_bf16 a[16:31], a[156:159], a[188:191], a[16:31]
	v_exp_f32_e32 v112, v112
	v_exp_f32_e32 v113, v113
	v_exp_f32_e32 v114, v114
	v_exp_f32_e32 v115, v115
	s_add_i32 s60, s60, 1
	s_cmp_eq_u32 s8, s60
	s_cbranch_scc0 .LBB0_1087
	s_waitcnt vmcnt(0) lgkmcnt(0)
	s_barrier
	v_add3_u32 v224, s62, v153, v134
	v_add3_u32 v230, s62, v158, v134
	v_add3_u32 v231, s62, v159, v134
	v_add3_u32 v232, s62, v160, v134
	ds_write_b128 v224, v[140:143] offset:36864
	ds_write_b128 v230, v[144:147] offset:36864
	ds_write_b128 v231, v[220:223] offset:36864
	ds_write_b128 v232, v[226:229] offset:36864
	v_add_u32_e32 v234, s61, v152
	v_pk_add_f32 v[136:137], v[136:137], v[204:205]
	v_pk_add_f32 v[136:137], v[136:137], v[206:207]
	v_pk_add_f32 v[136:137], v[136:137], v[208:209]
	v_pk_add_f32 v[136:137], v[136:137], v[210:211]
	v_pk_add_f32 v[136:137], v[136:137], v[212:213]
	v_pk_add_f32 v[136:137], v[136:137], v[214:215]
	v_pk_add_f32 v[136:137], v[136:137], v[216:217]
	v_pk_add_f32 v[136:137], v[136:137], v[218:219]
	v_cvt_pk_bf16_f32 v56, v204, v205
	v_cvt_pk_bf16_f32 v57, v206, v207
	v_cvt_pk_bf16_f32 v58, v208, v209
	v_cvt_pk_bf16_f32 v59, v210, v211
	v_cvt_pk_bf16_f32 v60, v212, v213
	v_cvt_pk_bf16_f32 v61, v214, v215
	v_cvt_pk_bf16_f32 v62, v216, v217
	v_cvt_pk_bf16_f32 v63, v218, v219
	v_add_f32_e32 v235, v136, v137
	v_add_f32_e32 v81, v81, v235
	v_pk_add_f32 v[148:149], v[148:149], v[100:101]
	v_pk_add_f32 v[148:149], v[148:149], v[102:103]
	v_pk_add_f32 v[148:149], v[148:149], v[104:105]
	v_pk_add_f32 v[148:149], v[148:149], v[106:107]
	v_pk_add_f32 v[148:149], v[148:149], v[108:109]
	v_pk_add_f32 v[148:149], v[148:149], v[110:111]
	v_pk_add_f32 v[148:149], v[148:149], v[112:113]
	v_pk_add_f32 v[148:149], v[148:149], v[114:115]
	v_cvt_pk_bf16_f32 v124, v100, v101
	v_cvt_pk_bf16_f32 v125, v102, v103
	v_cvt_pk_bf16_f32 v126, v104, v105
	v_cvt_pk_bf16_f32 v127, v106, v107
	v_cvt_pk_bf16_f32 v130, v108, v109
	v_cvt_pk_bf16_f32 v131, v110, v111
	v_cvt_pk_bf16_f32 v132, v112, v113
	v_cvt_pk_bf16_f32 v133, v114, v115
	v_add_f32_e32 v235, v148, v149
	v_add_f32_e32 v80, v80, v235
	s_nop 1
	ds_read_b128 a[144:147], v234 offset:36864
	ds_read_b128 a[148:151], v234 offset:36896
	ds_read_b128 a[152:155], v234 offset:36928
	ds_read_b128 a[156:159], v234 offset:36960
	s_waitcnt lgkmcnt(3)
	v_mfma_f32_32x32x16_bf16 a[128:143], a[144:147], v[48:51], a[128:143]
	v_mfma_f32_32x32x16_bf16 a[112:127], a[144:147], v[116:119], a[112:127]
	ds_read_b128 a[144:147], v234 offset:41472
	s_waitcnt lgkmcnt(3)
	v_mfma_f32_32x32x16_bf16 a[128:143], a[148:151], v[52:55], a[128:143]
	v_mfma_f32_32x32x16_bf16 a[112:127], a[148:151], v[120:123], a[112:127]
	ds_read_b128 a[148:151], v234 offset:41504
	s_waitcnt lgkmcnt(3)
	v_mfma_f32_32x32x16_bf16 a[128:143], a[152:155], v[56:59], a[128:143]
	v_mfma_f32_32x32x16_bf16 a[112:127], a[152:155], v[124:127], a[112:127]
	ds_read_b128 a[152:155], v234 offset:41536
	s_waitcnt lgkmcnt(3)
	v_mfma_f32_32x32x16_bf16 a[128:143], a[156:159], v[60:63], a[128:143]
	v_mfma_f32_32x32x16_bf16 a[112:127], a[156:159], v[130:133], a[112:127]
	ds_read_b128 a[156:159], v234 offset:41568
	s_waitcnt lgkmcnt(3)
	v_mfma_f32_32x32x16_bf16 a[48:63], a[144:147], v[48:51], a[48:63]
	v_mfma_f32_32x32x16_bf16 a[64:79], a[144:147], v[116:119], a[64:79]
	ds_read_b128 a[144:147], v234 offset:46080
	s_waitcnt lgkmcnt(3)
	v_mfma_f32_32x32x16_bf16 a[48:63], a[148:151], v[52:55], a[48:63]
	v_mfma_f32_32x32x16_bf16 a[64:79], a[148:151], v[120:123], a[64:79]
	ds_read_b128 a[148:151], v234 offset:46112
	s_waitcnt lgkmcnt(3)
	v_mfma_f32_32x32x16_bf16 a[48:63], a[152:155], v[56:59], a[48:63]
	v_mfma_f32_32x32x16_bf16 a[64:79], a[152:155], v[124:127], a[64:79]
	ds_read_b128 a[152:155], v234 offset:46144
	s_waitcnt lgkmcnt(3)
	v_mfma_f32_32x32x16_bf16 a[48:63], a[156:159], v[60:63], a[48:63]
	v_mfma_f32_32x32x16_bf16 a[64:79], a[156:159], v[130:133], a[64:79]
	ds_read_b128 a[156:159], v234 offset:46176
	s_waitcnt lgkmcnt(3)
	v_mfma_f32_32x32x16_bf16 a[80:95], a[144:147], v[48:51], a[80:95]
	v_mfma_f32_32x32x16_bf16 a[96:111], a[144:147], v[116:119], a[96:111]
	ds_read_b128 a[144:147], v234 offset:50688
	s_waitcnt lgkmcnt(3)
	v_mfma_f32_32x32x16_bf16 a[80:95], a[148:151], v[52:55], a[80:95]
	v_mfma_f32_32x32x16_bf16 a[96:111], a[148:151], v[120:123], a[96:111]
	ds_read_b128 a[148:151], v234 offset:50720
	s_waitcnt lgkmcnt(3)
	v_mfma_f32_32x32x16_bf16 a[80:95], a[152:155], v[56:59], a[80:95]
	v_mfma_f32_32x32x16_bf16 a[96:111], a[152:155], v[124:127], a[96:111]
	ds_read_b128 a[152:155], v234 offset:50752
	s_waitcnt lgkmcnt(3)
	v_mfma_f32_32x32x16_bf16 a[80:95], a[156:159], v[60:63], a[80:95]
	v_mfma_f32_32x32x16_bf16 a[96:111], a[156:159], v[130:133], a[96:111]
	ds_read_b128 a[156:159], v234 offset:50784
	s_waitcnt lgkmcnt(3)
	v_mfma_f32_32x32x16_bf16 a[32:47], a[144:147], v[48:51], a[32:47]
	v_mfma_f32_32x32x16_bf16 a[16:31], a[144:147], v[116:119], a[16:31]
	s_waitcnt lgkmcnt(2)
	v_mfma_f32_32x32x16_bf16 a[32:47], a[148:151], v[52:55], a[32:47]
	v_mfma_f32_32x32x16_bf16 a[16:31], a[148:151], v[120:123], a[16:31]
	s_waitcnt lgkmcnt(1)
	v_mfma_f32_32x32x16_bf16 a[32:47], a[152:155], v[56:59], a[32:47]
	v_mfma_f32_32x32x16_bf16 a[16:31], a[152:155], v[124:127], a[16:31]
	s_waitcnt lgkmcnt(0)
	v_mfma_f32_32x32x16_bf16 a[32:47], a[156:159], v[60:63], a[32:47]
	v_mfma_f32_32x32x16_bf16 a[16:31], a[156:159], v[130:133], a[16:31]
	s_bitcmp1_b32 s8, 0
	s_cselect_b32 s8, 0x4800, 0
	v_add_u32_e32 v48, s8, v128
	s_waitcnt lgkmcnt(0)
	s_barrier
	ds_read_b128 v[32:35], v48
	ds_read_b128 v[36:39], v48 offset:32
	s_waitcnt lgkmcnt(1)
	v_mfma_f32_32x32x16_bf16 a[186:201], v[32:35], v[28:31], a[0:15]
	v_add_u32_e32 v83, s8, v152
	v_mfma_f32_32x32x16_bf16 a[144:159], v[32:35], v[12:15], a[0:15]
	s_waitcnt lgkmcnt(0)
	v_mfma_f32_32x32x16_bf16 a[186:201], v[36:39], v[24:27], a[186:201]
	v_mfma_f32_32x32x16_bf16 a[144:159], v[36:39], v[8:11], a[144:159]
	ds_read_b128 v[32:35], v48 offset:64
	ds_read_b128 v[36:39], v48 offset:96
	s_waitcnt lgkmcnt(1)
	v_mfma_f32_32x32x16_bf16 a[186:201], v[32:35], v[20:23], a[186:201]
	s_waitcnt lgkmcnt(0)
	v_mfma_f32_32x32x16_bf16 a[186:201], v[36:39], v[16:19], a[186:201]
	v_mfma_f32_32x32x16_bf16 a[144:159], v[32:35], v[4:7], a[144:159]
	ds_read_b128 v[32:35], v48 offset:4608
	ds_read_b128 v[40:43], v48 offset:4640
	ds_read_b128 v[44:47], v48 offset:4672
	ds_read_b128 v[48:51], v48 offset:4704
	s_nop 6
	v_accvgpr_read_b32 v52, a186
	v_accvgpr_read_b32 v53, a187
	v_accvgpr_read_b32 v54, a188
	v_exp_f32_e32 v52, v52
	v_exp_f32_e32 v53, v53
	s_waitcnt lgkmcnt(3)
	v_mfma_f32_32x32x16_bf16 a[172:187], v[32:35], v[28:31], a[0:15]
	v_accvgpr_read_b32 v28, a189
	v_exp_f32_e32 v55, v28
	v_accvgpr_read_b32 v28, a190
	v_exp_f32_e32 v56, v28
	v_accvgpr_read_b32 v28, a191
	v_exp_f32_e32 v54, v54
	v_exp_f32_e32 v57, v28
	s_waitcnt lgkmcnt(2)
	v_mfma_f32_32x32x16_bf16 a[172:187], v[40:43], v[24:27], a[172:187]
	v_accvgpr_read_b32 v24, a192
	v_exp_f32_e32 v58, v24
	v_accvgpr_read_b32 v24, a193
	v_exp_f32_e32 v59, v24
	v_accvgpr_read_b32 v24, a194
	v_exp_f32_e32 v60, v24
	v_accvgpr_read_b32 v24, a195
	s_waitcnt lgkmcnt(1)
	v_mfma_f32_32x32x16_bf16 a[172:187], v[44:47], v[20:23], a[172:187]
	v_accvgpr_read_b32 v20, a196
	v_exp_f32_e32 v62, v20
	v_accvgpr_read_b32 v20, a197
	v_exp_f32_e32 v63, v20
	v_accvgpr_read_b32 v20, a198
	v_exp_f32_e32 v64, v20
	v_exp_f32_e32 v61, v24
	s_waitcnt lgkmcnt(0)
	v_mfma_f32_32x32x16_bf16 a[172:187], v[48:51], v[16:19], a[172:187]
	v_accvgpr_read_b32 v16, a199
	v_exp_f32_e32 v65, v16
	v_accvgpr_read_b32 v16, a200
	v_exp_f32_e32 v66, v16
	v_accvgpr_read_b32 v16, a201
	v_exp_f32_e32 v67, v16
	ds_read_b128 v[28:31], v83 offset:36928
	v_mfma_f32_32x32x16_bf16 a[144:159], v[36:39], v[0:3], a[144:159]
	s_nop 3
	v_accvgpr_read_b32 v16, a172
	v_exp_f32_e32 v36, v16
	v_accvgpr_read_b32 v16, a173
	v_exp_f32_e32 v37, v16
	v_accvgpr_read_b32 v16, a174
	v_exp_f32_e32 v38, v16
	v_accvgpr_read_b32 v16, a175
	v_mfma_f32_32x32x16_bf16 a[160:175], v[32:35], v[12:15], a[0:15]
	v_exp_f32_e32 v39, v16
	v_accvgpr_read_b32 v16, a144
	v_accvgpr_read_b32 v12, a176
	v_exp_f32_e32 v68, v12
	v_accvgpr_read_b32 v12, a177
	v_accvgpr_read_b32 v20, a157
	v_exp_f32_e32 v69, v12
	v_mfma_f32_32x32x16_bf16 a[160:175], v[40:43], v[8:11], a[160:175]
	v_accvgpr_read_b32 v12, a178
	v_exp_f32_e32 v84, v20
	v_accvgpr_read_b32 v20, a158
	v_exp_f32_e32 v70, v12
	v_accvgpr_read_b32 v12, a179
	v_exp_f32_e32 v85, v20
	v_accvgpr_read_b32 v20, a159
	v_mfma_f32_32x32x16_bf16 a[160:175], v[44:47], v[4:7], a[160:175]
	v_exp_f32_e32 v40, v12
	v_cvt_pk_bf16_f32 v12, v52, v53
	v_cvt_pk_bf16_f32 v13, v54, v55
	v_cvt_pk_bf16_f32 v14, v56, v57
	v_cvt_pk_bf16_f32 v15, v58, v59
	v_exp_f32_e32 v86, v20
	ds_read_b128 v[20:23], v83 offset:36896
	v_mfma_f32_32x32x16_bf16 a[160:175], v[48:51], v[0:3], a[160:175]
	v_exp_f32_e32 v49, v16
	v_accvgpr_read_b32 v16, a145
	v_exp_f32_e32 v50, v16
	v_accvgpr_read_b32 v16, a146
	v_exp_f32_e32 v51, v16
	v_accvgpr_read_b32 v16, a147
	v_exp_f32_e32 v71, v16
	v_accvgpr_read_b32 v16, a148
	v_exp_f32_e32 v72, v16
	v_accvgpr_read_b32 v16, a149
	v_exp_f32_e32 v73, v16
	v_accvgpr_read_b32 v16, a150
	v_exp_f32_e32 v74, v16
	v_accvgpr_read_b32 v16, a151
	v_exp_f32_e32 v75, v16
	v_accvgpr_read_b32 v16, a152
	v_exp_f32_e32 v76, v16
	v_accvgpr_read_b32 v16, a153
	v_exp_f32_e32 v77, v16
	v_accvgpr_read_b32 v16, a154
	v_exp_f32_e32 v78, v16
	v_accvgpr_read_b32 v16, a155
	v_exp_f32_e32 v79, v16
	v_accvgpr_read_b32 v16, a156
	v_exp_f32_e32 v82, v16
	ds_read_b128 v[16:19], v83 offset:36864
	v_accvgpr_read_b32 v24, a160
	v_exp_f32_e32 v87, v24
	v_accvgpr_read_b32 v24, a161
	v_exp_f32_e32 v88, v24
	v_cvt_pk_bf16_f32 v24, v49, v50
	v_cvt_pk_bf16_f32 v25, v51, v71
	v_cvt_pk_bf16_f32 v26, v72, v73
	v_cvt_pk_bf16_f32 v27, v74, v75
	s_waitcnt lgkmcnt(0)
	v_mfma_f32_32x32x16_bf16 a[144:159], v[16:19], v[12:15], a[128:143]
	v_accvgpr_read_b32 v8, a180
	v_exp_f32_e32 v41, v8
	v_accvgpr_read_b32 v8, a181
	v_exp_f32_e32 v42, v8
	v_accvgpr_read_b32 v8, a182
	v_exp_f32_e32 v43, v8
	v_cvt_pk_bf16_f32 v8, v60, v61
	v_mfma_f32_32x32x16_bf16 a[128:143], v[16:19], v[24:27], a[112:127]
	v_accvgpr_read_b32 v16, a162
	v_exp_f32_e32 v89, v16
	v_accvgpr_read_b32 v16, a163
	v_exp_f32_e32 v90, v16
	v_accvgpr_read_b32 v16, a164
	v_exp_f32_e32 v91, v16
	v_accvgpr_read_b32 v16, a165
	v_cvt_pk_bf16_f32 v9, v62, v63
	v_cvt_pk_bf16_f32 v10, v64, v65
	v_cvt_pk_bf16_f32 v11, v66, v67
	v_exp_f32_e32 v92, v16
	v_cvt_pk_bf16_f32 v16, v76, v77
	v_cvt_pk_bf16_f32 v17, v78, v79
	v_cvt_pk_bf16_f32 v18, v82, v84
	v_cvt_pk_bf16_f32 v19, v85, v86
	v_mfma_f32_32x32x16_bf16 a[144:159], v[20:23], v[8:11], a[144:159]
	v_accvgpr_read_b32 v32, a166
	v_accvgpr_read_b32 v4, a183
	v_exp_f32_e32 v93, v32
	v_exp_f32_e32 v44, v4
	v_accvgpr_read_b32 v4, a184
	v_exp_f32_e32 v45, v4
	v_accvgpr_read_b32 v4, a185
	v_mfma_f32_32x32x16_bf16 a[128:143], v[20:23], v[16:19], a[128:143]
	v_accvgpr_read_b32 v20, a167
	v_exp_f32_e32 v94, v20
	v_accvgpr_read_b32 v32, a169
	v_exp_f32_e32 v46, v4
	v_accvgpr_read_b32 v4, a186
	v_exp_f32_e32 v96, v32
	v_accvgpr_read_b32 v32, a170
	v_exp_f32_e32 v47, v4
	v_cvt_pk_bf16_f32 v4, v36, v37
	v_cvt_pk_bf16_f32 v5, v38, v39
	v_cvt_pk_bf16_f32 v6, v68, v69
	v_cvt_pk_bf16_f32 v7, v70, v40
	v_accvgpr_read_b32 v20, a168
	v_exp_f32_e32 v97, v32
	v_cvt_pk_bf16_f32 v32, v87, v88
	v_cvt_pk_bf16_f32 v33, v89, v90
	v_cvt_pk_bf16_f32 v34, v91, v92
	v_cvt_pk_bf16_f32 v35, v93, v94
	v_exp_f32_e32 v95, v20
	ds_read_b128 v[20:23], v83 offset:36960
	v_mfma_f32_32x32x16_bf16 a[144:159], v[28:31], v[4:7], a[144:159]
	v_accvgpr_read_b32 v0, a187
	v_exp_f32_e32 v48, v0
	v_cvt_pk_bf16_f32 v0, v41, v42
	v_cvt_pk_bf16_f32 v1, v43, v44
	v_cvt_pk_bf16_f32 v2, v45, v46
	v_cvt_pk_bf16_f32 v3, v47, v48
	v_cvt_pk_bf16_f32 v130, v95, v96
	v_mfma_f32_32x32x16_bf16 a[128:143], v[28:31], v[32:35], a[128:143]
	v_accvgpr_read_b32 v28, a171
	v_exp_f32_e32 v98, v28
	v_accvgpr_read_b32 v28, a172
	v_exp_f32_e32 v99, v28
	v_accvgpr_read_b32 v28, a173
	v_exp_f32_e32 v100, v28
	v_accvgpr_read_b32 v28, a174
	v_exp_f32_e32 v101, v28
	v_accvgpr_read_b32 v28, a175
	v_exp_f32_e32 v102, v28
	v_cvt_pk_bf16_f32 v131, v97, v98
	v_cvt_pk_bf16_f32 v132, v99, v100
	s_waitcnt lgkmcnt(0)
	v_mfma_f32_32x32x16_bf16 a[144:159], v[20:23], v[0:3], a[144:159]
	v_cvt_pk_bf16_f32 v133, v101, v102
	s_nop 1
	v_mfma_f32_32x32x16_bf16 a[128:143], v[20:23], v[130:133], a[128:143]
	ds_read_b128 v[20:23], v83 offset:41472
	ds_read_b128 v[28:31], v83 offset:41504
	s_nop 5
	v_accvgpr_read_b32 v112, a144
	v_accvgpr_read_b32 v113, a145
	v_accvgpr_read_b32 v114, a146
	v_accvgpr_read_b32 v115, a147
	s_waitcnt lgkmcnt(1)
	v_mfma_f32_32x32x16_bf16 a[112:127], v[20:23], v[12:15], a[48:63]
	v_accvgpr_read_b32 v116, a148
	v_accvgpr_read_b32 v117, a149
	v_accvgpr_read_b32 v118, a150
	v_accvgpr_read_b32 v119, a151
	v_accvgpr_read_b32 v120, a152
	v_accvgpr_read_b32 v121, a153
	v_accvgpr_read_b32 v122, a154
	v_mfma_f32_32x32x16_bf16 a[48:63], v[20:23], v[24:27], a[64:79]
	v_accvgpr_read_b32 v123, a155
	v_accvgpr_read_b32 v124, a156
	v_accvgpr_read_b32 v125, a157
	v_accvgpr_read_b32 v126, a158
	v_accvgpr_read_b32 v127, a159
	s_waitcnt lgkmcnt(0)
	v_mfma_f32_32x32x16_bf16 a[112:127], v[28:31], v[8:11], a[112:127]
	v_mfma_f32_32x32x16_bf16 a[48:63], v[28:31], v[16:19], a[48:63]
	ds_read_b128 v[20:23], v83 offset:41536
	ds_read_b128 v[28:31], v83 offset:41568
	s_waitcnt lgkmcnt(1)
	v_mfma_f32_32x32x16_bf16 a[112:127], v[20:23], v[4:7], a[112:127]
	v_mfma_f32_32x32x16_bf16 a[48:63], v[20:23], v[32:35], a[48:63]
	s_waitcnt lgkmcnt(0)
	v_mfma_f32_32x32x16_bf16 a[112:127], v[28:31], v[0:3], a[112:127]
	v_mfma_f32_32x32x16_bf16 a[48:63], v[28:31], v[130:133], a[48:63]
	ds_read_b128 v[20:23], v83 offset:46080
	ds_read_b128 v[28:31], v83 offset:46112
	s_waitcnt lgkmcnt(1)
	v_mfma_f32_32x32x16_bf16 a[64:79], v[20:23], v[12:15], a[80:95]
	v_mfma_f32_32x32x16_bf16 a[80:95], v[20:23], v[24:27], a[96:111]
	ds_read_b128 v[20:23], v83 offset:46144
	s_waitcnt lgkmcnt(1)
	v_mfma_f32_32x32x16_bf16 a[64:79], v[28:31], v[8:11], a[64:79]
	v_mfma_f32_32x32x16_bf16 a[80:95], v[28:31], v[16:19], a[80:95]
	v_add_f32_e32 v28, 0, v52
	v_add_f32_e32 v28, v53, v28
	v_add_f32_e32 v28, v54, v28
	v_add_f32_e32 v28, v55, v28
	v_add_f32_e32 v52, v56, v28
	v_add_f32_e32 v52, v57, v52
	v_add_f32_e32 v52, v58, v52
	v_add_f32_e32 v52, v59, v52
	v_add_f32_e32 v52, v60, v52
	v_add_f32_e32 v52, v61, v52
	v_add_f32_e32 v52, v62, v52
	v_add_f32_e32 v52, v63, v52
	ds_read_b128 v[28:31], v83 offset:46176
	s_waitcnt lgkmcnt(1)
	v_mfma_f32_32x32x16_bf16 a[64:79], v[20:23], v[4:7], a[64:79]
	v_mfma_f32_32x32x16_bf16 a[80:95], v[20:23], v[32:35], a[80:95]
	v_add_f32_e32 v20, v64, v52
	v_add_f32_e32 v20, v65, v20
	v_add_f32_e32 v20, v66, v20
	v_add_f32_e32 v20, v67, v20
	v_add_f32_e32 v20, v36, v20
	v_add_f32_e32 v20, v37, v20
	v_add_f32_e32 v20, v38, v20
	v_add_f32_e32 v20, v39, v20
	v_add_f32_e32 v20, v68, v20
	v_add_f32_e32 v20, v69, v20
	v_add_f32_e32 v20, v70, v20
	v_add_f32_e32 v20, v40, v20
	v_add_f32_e32 v36, v41, v20
	ds_read_b128 v[20:23], v83 offset:50688
	s_waitcnt lgkmcnt(1)
	v_mfma_f32_32x32x16_bf16 a[64:79], v[28:31], v[0:3], a[64:79]
	v_mfma_f32_32x32x16_bf16 a[80:95], v[28:31], v[130:133], a[80:95]
	v_add_f32_e32 v28, v42, v36
	v_add_f32_e32 v28, v43, v28
	v_add_f32_e32 v28, v44, v28
	v_add_f32_e32 v28, v45, v28
	v_add_f32_e32 v28, v46, v28
	v_add_f32_e32 v36, v47, v28
	ds_read_b128 v[28:31], v83 offset:50720
	s_waitcnt lgkmcnt(1)
	v_mfma_f32_32x32x16_bf16 a[96:111], v[20:23], v[12:15], a[32:47]
	v_add_f32_e32 v12, v48, v36
	v_add_f32_e32 v136, v81, v12
	v_add_f32_e32 v12, 0, v49
	v_add_f32_e32 v12, v50, v12
	v_add_f32_e32 v12, v51, v12
	v_add_f32_e32 v12, v71, v12
	v_add_f32_e32 v12, v72, v12
	v_add_f32_e32 v12, v73, v12
	v_add_f32_e32 v12, v74, v12
	v_add_f32_e32 v12, v75, v12
	v_add_f32_e32 v12, v76, v12
	v_add_f32_e32 v12, v77, v12
	v_add_f32_e32 v12, v78, v12
	v_add_f32_e32 v12, v79, v12
	s_waitcnt lgkmcnt(0)
	v_mfma_f32_32x32x16_bf16 a[96:111], v[28:31], v[8:11], a[96:111]
	v_add_f32_e32 v8, v82, v12
	v_add_f32_e32 v8, v84, v8
	v_add_f32_e32 v8, v85, v8
	v_add_f32_e32 v8, v86, v8
	v_add_f32_e32 v8, v87, v8
	v_add_f32_e32 v12, v88, v8
	ds_read_b128 v[8:11], v83 offset:50752
	v_mfma_f32_32x32x16_bf16 a[32:47], v[20:23], v[24:27], a[16:31]
	v_add_f32_e32 v12, v89, v12
	v_add_f32_e32 v12, v90, v12
	v_add_f32_e32 v12, v91, v12
	v_add_f32_e32 v12, v92, v12
	v_add_f32_e32 v12, v93, v12
	v_accvgpr_read_b32 v48, a128
	v_accvgpr_read_b32 v49, a129
	v_mfma_f32_32x32x16_bf16 a[32:47], v[28:31], v[16:19], a[32:47]
	v_add_f32_e32 v16, v94, v12
	ds_read_b128 v[12:15], v83 offset:50784
	v_accvgpr_read_b32 v50, a130
	v_accvgpr_read_b32 v51, a131
	v_accvgpr_read_b32 v52, a132
	v_accvgpr_read_b32 v53, a133
	v_accvgpr_read_b32 v54, a134
	s_waitcnt lgkmcnt(1)
	v_mfma_f32_32x32x16_bf16 a[96:111], v[8:11], v[4:7], a[96:111]
	v_add_f32_e32 v4, v95, v16
	v_add_f32_e32 v4, v96, v4
	v_add_f32_e32 v4, v97, v4
	v_add_f32_e32 v4, v98, v4
	v_add_f32_e32 v4, v99, v4
	v_add_f32_e32 v4, v100, v4
	v_add_f32_e32 v4, v101, v4
	v_add_f32_e32 v4, v102, v4
	v_add_f32_e32 v137, v80, v4
	ds_bpermute_b32 v4, v161, v136
	v_mfma_f32_32x32x16_bf16 a[32:47], v[8:11], v[32:35], a[32:47]
	v_accvgpr_read_b32 v96, a112
	v_accvgpr_read_b32 v32, a48
	v_accvgpr_read_b32 v95, a79
	s_waitcnt lgkmcnt(0)
	v_add_f32_e32 v136, v136, v4
	v_div_scale_f32 v140, s[60:61], v136, v136, 1.0
	v_rcp_f32_e32 v141, v140
	v_mfma_f32_32x32x16_bf16 a[32:47], v[12:15], v[130:133], a[32:47]
	ds_bpermute_b32 v131, v161, v137
	v_accvgpr_read_b32 v16, a80
	v_fma_f32 v130, -v140, v141, 1.0
	v_fmac_f32_e32 v141, v130, v141
	v_div_scale_f32 v130, vcc, 1.0, v136, 1.0
	v_mul_f32_e32 v132, v130, v141
	v_fma_f32 v133, -v140, v132, v130
	s_waitcnt lgkmcnt(0)
	v_add_f32_e32 v131, v137, v131
	v_fmac_f32_e32 v132, v133, v141
	v_div_scale_f32 v133, s[60:61], v131, v131, 1.0
	v_rcp_f32_e32 v137, v133
	v_mfma_f32_32x32x16_bf16 a[96:111], v[12:15], v[0:3], a[96:111]
	v_fma_f32 v130, -v140, v132, v130
	v_div_fmas_f32 v130, v130, v141, v132
	v_div_fixup_f32 v224, v130, v136, 1.0
	v_fma_f32 v130, -v133, v137, 1.0
	v_fmac_f32_e32 v137, v130, v137
	v_div_scale_f32 v130, vcc, 1.0, v131, 1.0
	v_mul_f32_e32 v132, v130, v137
	v_fma_f32 v136, -v133, v132, v130
	v_fmac_f32_e32 v132, v136, v137
	v_fma_f32 v130, -v133, v132, v130
	v_accvgpr_read_b32 v0, a32
	s_nop 0
	v_accvgpr_read_b32 v64, a96
	v_div_fmas_f32 v130, v130, v137, v132
	v_accvgpr_read_b32 v55, a135
	v_accvgpr_read_b32 v56, a136
	v_accvgpr_read_b32 v57, a137
	v_accvgpr_read_b32 v58, a138
	v_accvgpr_read_b32 v59, a139
	v_accvgpr_read_b32 v60, a140
	v_accvgpr_read_b32 v61, a141
	v_accvgpr_read_b32 v62, a142
	v_accvgpr_read_b32 v63, a143
	v_accvgpr_read_b32 v97, a113
	v_accvgpr_read_b32 v98, a114
	v_accvgpr_read_b32 v99, a115
	v_accvgpr_read_b32 v100, a116
	v_accvgpr_read_b32 v101, a117
	v_accvgpr_read_b32 v102, a118
	v_accvgpr_read_b32 v103, a119
	v_accvgpr_read_b32 v104, a120
	v_accvgpr_read_b32 v105, a121
	v_accvgpr_read_b32 v106, a122
	v_accvgpr_read_b32 v107, a123
	v_accvgpr_read_b32 v108, a124
	v_accvgpr_read_b32 v109, a125
	v_accvgpr_read_b32 v110, a126
	v_accvgpr_read_b32 v111, a127
	v_accvgpr_read_b32 v33, a49
	v_accvgpr_read_b32 v34, a50
	v_accvgpr_read_b32 v35, a51
	v_accvgpr_read_b32 v36, a52
	v_accvgpr_read_b32 v37, a53
	v_accvgpr_read_b32 v38, a54
	v_accvgpr_read_b32 v39, a55
	v_accvgpr_read_b32 v40, a56
	v_accvgpr_read_b32 v41, a57
	v_accvgpr_read_b32 v42, a58
	v_accvgpr_read_b32 v43, a59
	v_accvgpr_read_b32 v44, a60
	v_accvgpr_read_b32 v45, a61
	v_accvgpr_read_b32 v46, a62
	v_accvgpr_read_b32 v47, a63
	v_accvgpr_read_b32 v94, a78
	v_accvgpr_read_b32 v93, a77
	v_accvgpr_read_b32 v92, a76
	v_accvgpr_read_b32 v91, a75
	v_accvgpr_read_b32 v90, a74
	v_accvgpr_read_b32 v89, a73
	v_accvgpr_read_b32 v88, a72
	v_accvgpr_read_b32 v87, a71
	v_accvgpr_read_b32 v86, a70
	v_accvgpr_read_b32 v85, a69
	v_accvgpr_read_b32 v84, a68
	v_accvgpr_read_b32 v83, a67
	v_accvgpr_read_b32 v82, a66
	v_accvgpr_read_b32 v81, a65
	v_accvgpr_read_b32 v80, a64
	v_accvgpr_read_b32 v17, a81
	v_accvgpr_read_b32 v18, a82
	v_accvgpr_read_b32 v19, a83
	v_accvgpr_read_b32 v20, a84
	v_accvgpr_read_b32 v21, a85
	v_accvgpr_read_b32 v22, a86
	v_accvgpr_read_b32 v23, a87
	v_accvgpr_read_b32 v24, a88
	v_accvgpr_read_b32 v25, a89
	v_accvgpr_read_b32 v26, a90
	v_accvgpr_read_b32 v27, a91
	v_accvgpr_read_b32 v28, a92
	v_accvgpr_read_b32 v29, a93
	v_accvgpr_read_b32 v30, a94
	v_accvgpr_read_b32 v31, a95
	v_accvgpr_read_b32 v65, a97
	v_accvgpr_read_b32 v66, a98
	v_accvgpr_read_b32 v67, a99
	v_accvgpr_read_b32 v68, a100
	v_accvgpr_read_b32 v69, a101
	v_accvgpr_read_b32 v70, a102
	v_accvgpr_read_b32 v71, a103
	v_accvgpr_read_b32 v72, a104
	v_accvgpr_read_b32 v73, a105
	v_accvgpr_read_b32 v74, a106
	v_accvgpr_read_b32 v75, a107
	v_accvgpr_read_b32 v76, a108
	v_accvgpr_read_b32 v77, a109
	v_accvgpr_read_b32 v78, a110
	v_accvgpr_read_b32 v79, a111
	v_accvgpr_read_b32 v1, a33
	v_accvgpr_read_b32 v2, a34
	v_accvgpr_read_b32 v3, a35
	v_accvgpr_read_b32 v4, a36
	v_accvgpr_read_b32 v5, a37
	v_accvgpr_read_b32 v6, a38
	v_accvgpr_read_b32 v7, a39
	v_accvgpr_read_b32 v8, a40
	v_accvgpr_read_b32 v9, a41
	v_accvgpr_read_b32 v10, a42
	v_accvgpr_read_b32 v11, a43
	v_accvgpr_read_b32 v12, a44
	v_accvgpr_read_b32 v13, a45
	v_accvgpr_read_b32 v14, a46
	v_accvgpr_read_b32 v15, a47
	v_div_fixup_f32 v172, v130, v131, 1.0
	s_barrier
	s_and_saveexec_b64 s[60:61], s[4:5]
	s_cbranch_execz .LBB0_1090
	v_accvgpr_read_b32 v133, a252
	v_mul_f32_e32 v130, v133, v224
	v_mul_f32_e32 v131, v112, v130
	v_mul_f32_e32 v132, v113, v130
	ds_write2st64_b32 v139, v131, v132 offset1:1
	v_mul_f32_e32 v131, v114, v130
	v_mul_f32_e32 v132, v115, v130
	ds_write2st64_b32 v139, v131, v132 offset0:2 offset1:3
	v_mul_f32_e32 v131, v116, v130
	v_mul_f32_e32 v132, v117, v130
	ds_write2st64_b32 v139, v131, v132 offset0:4 offset1:5
	v_mul_f32_e32 v131, v118, v130
	v_mul_f32_e32 v132, v119, v130
	ds_write2st64_b32 v139, v131, v132 offset0:6 offset1:7
	v_mul_f32_e32 v131, v120, v130
	v_mul_f32_e32 v132, v121, v130
	ds_write2st64_b32 v139, v131, v132 offset0:8 offset1:9
	v_mul_f32_e32 v131, v122, v130
	v_mul_f32_e32 v132, v123, v130
	ds_write2st64_b32 v139, v131, v132 offset0:10 offset1:11
	v_mul_f32_e32 v131, v124, v130
	v_mul_f32_e32 v132, v125, v130
	ds_write2st64_b32 v139, v131, v132 offset0:12 offset1:13
	v_mul_f32_e32 v131, v126, v130
	v_mul_f32_e32 v132, v127, v130
	ds_write2st64_b32 v139, v131, v132 offset0:14 offset1:15
	v_mul_f32_e32 v131, v96, v130
	v_mul_f32_e32 v132, v97, v130
	ds_write2st64_b32 v139, v131, v132 offset0:16 offset1:17
	v_mul_f32_e32 v131, v98, v130
	v_mul_f32_e32 v132, v99, v130
	ds_write2st64_b32 v139, v131, v132 offset0:18 offset1:19
	v_mul_f32_e32 v131, v100, v130
	v_mul_f32_e32 v132, v101, v130
	ds_write2st64_b32 v139, v131, v132 offset0:20 offset1:21
	v_mul_f32_e32 v131, v102, v130
	v_mul_f32_e32 v132, v103, v130
	ds_write2st64_b32 v139, v131, v132 offset0:22 offset1:23
	v_mul_f32_e32 v131, v104, v130
	v_mul_f32_e32 v132, v105, v130
	ds_write2st64_b32 v139, v131, v132 offset0:24 offset1:25
	v_mul_f32_e32 v131, v106, v130
	v_mul_f32_e32 v132, v107, v130
	ds_write2st64_b32 v139, v131, v132 offset0:26 offset1:27
	v_mul_f32_e32 v131, v108, v130
	v_mul_f32_e32 v132, v109, v130
	ds_write2st64_b32 v139, v131, v132 offset0:28 offset1:29
	v_mul_f32_e32 v131, v110, v130
	v_mul_f32_e32 v132, v111, v130
	ds_write2st64_b32 v139, v131, v132 offset0:30 offset1:31
	v_mul_f32_e32 v131, v80, v130
	v_mul_f32_e32 v132, v81, v130
	ds_write2st64_b32 v139, v131, v132 offset0:32 offset1:33
	v_mul_f32_e32 v131, v82, v130
	v_mul_f32_e32 v132, v83, v130
	ds_write2st64_b32 v139, v131, v132 offset0:34 offset1:35
	v_mul_f32_e32 v131, v84, v130
	v_mul_f32_e32 v132, v85, v130
	ds_write2st64_b32 v139, v131, v132 offset0:36 offset1:37
	v_mul_f32_e32 v131, v86, v130
	v_mul_f32_e32 v132, v87, v130
	ds_write2st64_b32 v139, v131, v132 offset0:38 offset1:39
	v_mul_f32_e32 v131, v88, v130
	v_mul_f32_e32 v132, v89, v130
	ds_write2st64_b32 v139, v131, v132 offset0:40 offset1:41
	v_mul_f32_e32 v131, v90, v130
	v_mul_f32_e32 v132, v91, v130
	ds_write2st64_b32 v139, v131, v132 offset0:42 offset1:43
	v_mul_f32_e32 v131, v92, v130
	v_mul_f32_e32 v132, v93, v130
	ds_write2st64_b32 v139, v131, v132 offset0:44 offset1:45
	v_mul_f32_e32 v131, v94, v130
	v_mul_f32_e32 v132, v95, v130
	ds_write2st64_b32 v139, v131, v132 offset0:46 offset1:47
	v_mul_f32_e32 v131, v64, v130
	v_mul_f32_e32 v132, v65, v130
	ds_write2st64_b32 v139, v131, v132 offset0:48 offset1:49
	v_mul_f32_e32 v131, v66, v130
	v_mul_f32_e32 v132, v67, v130
	ds_write2st64_b32 v139, v131, v132 offset0:50 offset1:51
	v_mul_f32_e32 v131, v68, v130
	v_mul_f32_e32 v132, v69, v130
	ds_write2st64_b32 v139, v131, v132 offset0:52 offset1:53
	v_mul_f32_e32 v131, v70, v130
	v_mul_f32_e32 v132, v71, v130
	ds_write2st64_b32 v139, v131, v132 offset0:54 offset1:55
	v_mul_f32_e32 v131, v72, v130
	v_mul_f32_e32 v132, v73, v130
	ds_write2st64_b32 v139, v131, v132 offset0:56 offset1:57
	v_mul_f32_e32 v131, v74, v130
	v_mul_f32_e32 v132, v75, v130
	ds_write2st64_b32 v139, v131, v132 offset0:58 offset1:59
	v_mul_f32_e32 v131, v76, v130
	v_mul_f32_e32 v132, v77, v130
	ds_write2st64_b32 v139, v131, v132 offset0:60 offset1:61
	v_mul_f32_e32 v131, v78, v130
	v_mul_f32_e32 v130, v79, v130
	ds_write2st64_b32 v139, v131, v130 offset0:62 offset1:63
	v_mul_f32_e32 v130, v133, v172
	v_mul_f32_e32 v131, v48, v130
	v_mul_f32_e32 v132, v49, v130
	ds_write2st64_b32 v254, v131, v132 offset1:1
	v_mul_f32_e32 v131, v50, v130
	v_mul_f32_e32 v132, v51, v130
	ds_write2st64_b32 v254, v131, v132 offset0:2 offset1:3
	v_mul_f32_e32 v131, v52, v130
	v_mul_f32_e32 v132, v53, v130
	ds_write2st64_b32 v254, v131, v132 offset0:4 offset1:5
	v_mul_f32_e32 v131, v54, v130
	v_mul_f32_e32 v132, v55, v130
	ds_write2st64_b32 v254, v131, v132 offset0:6 offset1:7
	v_mul_f32_e32 v131, v56, v130
	v_mul_f32_e32 v132, v57, v130
	ds_write2st64_b32 v254, v131, v132 offset0:8 offset1:9
	v_mul_f32_e32 v131, v58, v130
	v_mul_f32_e32 v132, v59, v130
	ds_write2st64_b32 v254, v131, v132 offset0:10 offset1:11
	v_mul_f32_e32 v131, v60, v130
	v_mul_f32_e32 v132, v61, v130
	ds_write2st64_b32 v254, v131, v132 offset0:12 offset1:13
	v_mul_f32_e32 v131, v62, v130
	v_mul_f32_e32 v132, v63, v130
	ds_write2st64_b32 v254, v131, v132 offset0:14 offset1:15
	v_mul_f32_e32 v131, v32, v130
	v_mul_f32_e32 v132, v33, v130
	ds_write2st64_b32 v254, v131, v132 offset0:16 offset1:17
	v_mul_f32_e32 v131, v34, v130
	v_mul_f32_e32 v132, v35, v130
	ds_write2st64_b32 v254, v131, v132 offset0:18 offset1:19
	v_mul_f32_e32 v131, v36, v130
	v_mul_f32_e32 v132, v37, v130
	ds_write2st64_b32 v254, v131, v132 offset0:20 offset1:21
	v_mul_f32_e32 v131, v38, v130
	v_mul_f32_e32 v132, v39, v130
	ds_write2st64_b32 v254, v131, v132 offset0:22 offset1:23
	v_mul_f32_e32 v131, v40, v130
	v_mul_f32_e32 v132, v41, v130
	ds_write2st64_b32 v254, v131, v132 offset0:24 offset1:25
	v_mul_f32_e32 v131, v42, v130
	v_mul_f32_e32 v132, v43, v130
	ds_write2st64_b32 v254, v131, v132 offset0:26 offset1:27
	v_mul_f32_e32 v131, v44, v130
	v_mul_f32_e32 v132, v45, v130
	ds_write2st64_b32 v254, v131, v132 offset0:28 offset1:29
	v_mul_f32_e32 v131, v46, v130
	v_mul_f32_e32 v132, v47, v130
	ds_write2st64_b32 v254, v131, v132 offset0:30 offset1:31
	v_mul_f32_e32 v131, v16, v130
	v_mul_f32_e32 v132, v17, v130
	ds_write2st64_b32 v254, v131, v132 offset0:32 offset1:33
	v_mul_f32_e32 v131, v18, v130
	v_mul_f32_e32 v132, v19, v130
	ds_write2st64_b32 v254, v131, v132 offset0:34 offset1:35
	v_mul_f32_e32 v131, v20, v130
	v_mul_f32_e32 v132, v21, v130
	ds_write2st64_b32 v254, v131, v132 offset0:36 offset1:37
	v_mul_f32_e32 v131, v22, v130
	v_mul_f32_e32 v132, v23, v130
	ds_write2st64_b32 v254, v131, v132 offset0:38 offset1:39
	v_mul_f32_e32 v131, v24, v130
	v_mul_f32_e32 v132, v25, v130
	ds_write2st64_b32 v254, v131, v132 offset0:40 offset1:41
	v_mul_f32_e32 v131, v26, v130
	v_mul_f32_e32 v132, v27, v130
	ds_write2st64_b32 v254, v131, v132 offset0:42 offset1:43
	v_mul_f32_e32 v131, v28, v130
	v_mul_f32_e32 v132, v29, v130
	ds_write2st64_b32 v254, v131, v132 offset0:44 offset1:45
	v_mul_f32_e32 v131, v30, v130
	v_mul_f32_e32 v132, v31, v130
	ds_write2st64_b32 v254, v131, v132 offset0:46 offset1:47
	v_mul_f32_e32 v131, v0, v130
	v_mul_f32_e32 v132, v1, v130
	ds_write2st64_b32 v254, v131, v132 offset0:48 offset1:49
	v_mul_f32_e32 v131, v2, v130
	v_mul_f32_e32 v132, v3, v130
	ds_write2st64_b32 v254, v131, v132 offset0:50 offset1:51
	v_mul_f32_e32 v131, v4, v130
	v_mul_f32_e32 v132, v5, v130
	ds_write2st64_b32 v254, v131, v132 offset0:52 offset1:53
	v_mul_f32_e32 v131, v6, v130
	v_mul_f32_e32 v132, v7, v130
	ds_write2st64_b32 v254, v131, v132 offset0:54 offset1:55
	v_mul_f32_e32 v131, v8, v130
	v_mul_f32_e32 v132, v9, v130
	ds_write2st64_b32 v254, v131, v132 offset0:56 offset1:57
	v_mul_f32_e32 v131, v10, v130
	v_mul_f32_e32 v132, v11, v130
	ds_write2st64_b32 v254, v131, v132 offset0:58 offset1:59
	v_mul_f32_e32 v131, v12, v130
	v_mul_f32_e32 v132, v13, v130
	ds_write2st64_b32 v254, v131, v132 offset0:60 offset1:61
	v_mul_f32_e32 v131, v14, v130
	v_mul_f32_e32 v130, v15, v130
	ds_write2st64_b32 v254, v131, v130 offset0:62 offset1:63

.LBB0_1624:
	s_cmp_lt_i32 s10, s71
	s_cselect_b64 vcc, -1, 0
	s_and_b64 s[80:81], vcc, exec
	s_cselect_b32 s11, s11, s75
	s_and_b32 s67, s10, 1
	s_mul_i32 s75, s67, 0x1200
	v_lshl_add_u32 v8, s75, 1, v133
	ds_read_b128 a[80:83], v8
	ds_read_b128 a[84:87], v8 offset:32
	ds_read_b128 a[88:91], v8 offset:4704
	ds_read_b128 a[92:95], v8 offset:64
	s_and_b64 s[80:81], s[60:61], vcc
	s_lshl_b32 s78, s11, 6
	s_waitcnt vmcnt(7)
	s_waitcnt lgkmcnt(3)
	v_mfma_f32_32x32x16_bf16 a[32:47], a[80:83], v[64:67], a[64:79]
	s_andn2_b64 vcc, exec, s[80:81]
	v_subrev_u32_e32 v151, s78, v131
	s_waitcnt vmcnt(3)
	v_mfma_f32_32x32x16_bf16 a[0:15], a[80:83], v[80:83], a[64:79]
	ds_read_b128 a[80:83], v8 offset:96
	s_waitcnt lgkmcnt(3)
	v_mfma_f32_32x32x16_bf16 a[32:47], a[84:87], v[68:71], a[32:47]
	s_waitcnt vmcnt(2)
	v_mfma_f32_32x32x16_bf16 a[0:15], a[84:87], v[84:87], a[0:15]
	ds_read_b128 a[84:87], v8 offset:4608
	s_waitcnt lgkmcnt(2)
	v_mfma_f32_32x32x16_bf16 a[32:47], a[92:95], v[72:75], a[32:47]
	s_waitcnt vmcnt(1)
	v_mfma_f32_32x32x16_bf16 a[0:15], a[92:95], v[88:91], a[0:15]
	ds_read_b128 a[92:95], v8 offset:4640
	s_waitcnt lgkmcnt(2)
	v_mfma_f32_32x32x16_bf16 a[32:47], a[80:83], v[76:79], a[32:47]
	s_waitcnt vmcnt(0)
	v_mfma_f32_32x32x16_bf16 a[0:15], a[80:83], v[92:95], a[0:15]
	ds_read_b128 a[80:83], v8 offset:4672
	s_waitcnt lgkmcnt(2)
	v_mfma_f32_32x32x16_bf16 a[48:63], a[84:87], v[64:67], a[64:79]
	v_mfma_f32_32x32x16_bf16 a[16:31], a[84:87], v[80:83], a[64:79]
	s_waitcnt lgkmcnt(1)
	v_mfma_f32_32x32x16_bf16 a[48:63], a[92:95], v[68:71], a[48:63]
	v_mfma_f32_32x32x16_bf16 a[16:31], a[92:95], v[84:87], a[16:31]
	s_waitcnt lgkmcnt(0)
	v_mfma_f32_32x32x16_bf16 a[48:63], a[80:83], v[72:75], a[48:63]
	v_mfma_f32_32x32x16_bf16 a[16:31], a[80:83], v[88:91], a[16:31]
	s_waitcnt lgkmcnt(5)
	v_mfma_f32_32x32x16_bf16 a[48:63], a[88:91], v[76:79], a[48:63]
	v_mfma_f32_32x32x16_bf16 a[16:31], a[88:91], v[92:95], a[16:31]
	v_cndmask_b32_e64 v32, 0, 1, s[80:81]
	v_cmp_ne_u32_e64 s[10:11], 1, v32
	s_cbranch_vccnz .LBB0_1626
	v_add_u32_e32 v32, v151, v169
	v_accvgpr_read_b32 v16, a32
	v_cmp_lt_u32_e32 vcc, s97, v32
	v_add_u32_e32 v32, v151, v171
	v_accvgpr_read_b32 v17, a33
	v_cndmask_b32_e32 v16, v184, v16, vcc
	v_cmp_lt_u32_e32 vcc, s97, v32
	v_add_u32_e32 v32, v151, v173
	v_accvgpr_read_b32 v18, a34
	v_cndmask_b32_e32 v17, v184, v17, vcc
	v_cmp_lt_u32_e32 vcc, s97, v32
	v_add_u32_e32 v32, v151, v187
	v_accvgpr_read_b32 v19, a35
	v_cndmask_b32_e32 v18, v184, v18, vcc
	v_cmp_lt_u32_e32 vcc, s97, v32
	v_add_u32_e32 v32, v151, v188
	v_accvgpr_read_b32 v20, a36
	v_cndmask_b32_e32 v19, v184, v19, vcc
	v_cmp_lt_u32_e32 vcc, s97, v32
	v_add_u32_e32 v32, v151, v189
	v_accvgpr_read_b32 v21, a37
	v_cndmask_b32_e32 v20, v184, v20, vcc
	v_cmp_lt_u32_e32 vcc, s97, v32
	v_add_u32_e32 v32, v151, v190
	v_accvgpr_read_b32 v22, a38
	v_cndmask_b32_e32 v21, v184, v21, vcc
	v_cmp_lt_u32_e32 vcc, s97, v32
	v_add_u32_e32 v32, v151, v191
	s_or_b32 s80, s78, 16
	v_cndmask_b32_e32 v22, v184, v22, vcc
	v_cmp_lt_u32_e32 vcc, s97, v32
	v_subrev_u32_e32 v32, s80, v131
	v_accvgpr_read_b32 v23, a39
	v_add_u32_e32 v33, v32, v169
	v_accvgpr_read_b32 v24, a40
	v_cndmask_b32_e32 v23, v184, v23, vcc
	v_cmp_lt_u32_e32 vcc, s97, v33
	v_add_u32_e32 v33, v32, v171
	v_accvgpr_read_b32 v25, a41
	v_cndmask_b32_e32 v24, v184, v24, vcc
	v_cmp_lt_u32_e32 vcc, s97, v33
	v_add_u32_e32 v33, v32, v173
	v_accvgpr_read_b32 v26, a42
	v_cndmask_b32_e32 v25, v184, v25, vcc
	v_cmp_lt_u32_e32 vcc, s97, v33
	v_add_u32_e32 v33, v32, v187
	v_accvgpr_read_b32 v27, a43
	v_cndmask_b32_e32 v26, v184, v26, vcc
	v_cmp_lt_u32_e32 vcc, s97, v33
	v_add_u32_e32 v33, v32, v188
	v_accvgpr_read_b32 v28, a44
	v_cndmask_b32_e32 v27, v184, v27, vcc
	v_cmp_lt_u32_e32 vcc, s97, v33
	v_add_u32_e32 v33, v32, v189
	v_accvgpr_read_b32 v29, a45
	v_cndmask_b32_e32 v28, v184, v28, vcc
	v_cmp_lt_u32_e32 vcc, s97, v33
	v_add_u32_e32 v33, v32, v190
	s_or_b32 s80, s78, 32
	v_accvgpr_read_b32 v30, a46
	v_accvgpr_read_b32 v31, a47
	v_cndmask_b32_e32 v29, v184, v29, vcc
	v_cmp_lt_u32_e32 vcc, s97, v33
	v_add_u32_e32 v32, v32, v191
	v_accvgpr_write_b32 a32, v16
	v_subrev_u32_e32 v16, s80, v131
	v_cndmask_b32_e32 v30, v184, v30, vcc
	v_cmp_lt_u32_e32 vcc, s97, v32
	v_accvgpr_write_b32 a33, v17
	v_add_u32_e32 v17, v16, v169
	v_accvgpr_read_b32 v0, a48
	v_cndmask_b32_e32 v31, v184, v31, vcc
	v_cmp_lt_u32_e32 vcc, s97, v17
	v_add_u32_e32 v17, v16, v171
	v_accvgpr_read_b32 v1, a49
	v_cndmask_b32_e32 v0, v184, v0, vcc
	v_cmp_lt_u32_e32 vcc, s97, v17
	v_add_u32_e32 v17, v16, v173
	v_accvgpr_read_b32 v2, a50
	v_cndmask_b32_e32 v1, v184, v1, vcc
	v_cmp_lt_u32_e32 vcc, s97, v17
	v_add_u32_e32 v17, v16, v187
	v_accvgpr_read_b32 v3, a51
	v_cndmask_b32_e32 v2, v184, v2, vcc
	v_cmp_lt_u32_e32 vcc, s97, v17
	v_add_u32_e32 v17, v16, v188
	v_accvgpr_read_b32 v4, a52
	v_cndmask_b32_e32 v3, v184, v3, vcc
	v_cmp_lt_u32_e32 vcc, s97, v17
	v_add_u32_e32 v17, v16, v189
	v_accvgpr_read_b32 v5, a53
	v_cndmask_b32_e32 v4, v184, v4, vcc
	v_cmp_lt_u32_e32 vcc, s97, v17
	v_add_u32_e32 v17, v16, v190
	v_accvgpr_read_b32 v6, a54
	v_cndmask_b32_e32 v5, v184, v5, vcc
	v_cmp_lt_u32_e32 vcc, s97, v17
	v_add_u32_e32 v16, v16, v191
	s_or_b32 s80, s78, 48
	v_cndmask_b32_e32 v6, v184, v6, vcc
	v_cmp_lt_u32_e32 vcc, s97, v16
	v_subrev_u32_e32 v16, s80, v131
	v_accvgpr_read_b32 v7, a55
	v_add_u32_e32 v17, v16, v169
	v_accvgpr_read_b32 v8, a56
	v_cndmask_b32_e32 v7, v184, v7, vcc
	v_cmp_lt_u32_e32 vcc, s97, v17
	v_add_u32_e32 v17, v16, v171
	v_accvgpr_read_b32 v9, a57
	v_cndmask_b32_e32 v8, v184, v8, vcc
	v_cmp_lt_u32_e32 vcc, s97, v17
	v_add_u32_e32 v17, v16, v173
	v_accvgpr_read_b32 v10, a58
	v_cndmask_b32_e32 v9, v184, v9, vcc
	v_cmp_lt_u32_e32 vcc, s97, v17
	v_add_u32_e32 v17, v16, v187
	v_accvgpr_read_b32 v11, a59
	v_cndmask_b32_e32 v10, v184, v10, vcc
	v_cmp_lt_u32_e32 vcc, s97, v17
	v_add_u32_e32 v17, v16, v188
	v_accvgpr_read_b32 v12, a60
	v_cndmask_b32_e32 v11, v184, v11, vcc
	v_cmp_lt_u32_e32 vcc, s97, v17
	v_add_u32_e32 v17, v16, v189
	v_accvgpr_read_b32 v13, a61
	v_cndmask_b32_e32 v12, v184, v12, vcc
	v_cmp_lt_u32_e32 vcc, s97, v17
	v_add_u32_e32 v17, v16, v190
	v_accvgpr_read_b32 v14, a62
	v_cndmask_b32_e32 v13, v184, v13, vcc
	v_cmp_lt_u32_e32 vcc, s97, v17
	v_add_u32_e32 v16, v16, v191
	v_accvgpr_read_b32 v15, a63
	v_cndmask_b32_e32 v14, v184, v14, vcc
	v_cmp_lt_u32_e32 vcc, s97, v16
	v_accvgpr_write_b32 a34, v18
	v_accvgpr_write_b32 a35, v19
	v_cndmask_b32_e32 v15, v184, v15, vcc
	v_accvgpr_write_b32 a36, v20
	v_accvgpr_write_b32 a37, v21
	v_accvgpr_write_b32 a38, v22
	v_accvgpr_write_b32 a39, v23
	v_accvgpr_write_b32 a40, v24
	v_accvgpr_write_b32 a41, v25
	v_accvgpr_write_b32 a42, v26
	v_accvgpr_write_b32 a43, v27
	v_accvgpr_write_b32 a44, v28
	v_accvgpr_write_b32 a45, v29
	v_accvgpr_write_b32 a46, v30
	v_accvgpr_write_b32 a47, v31
	v_accvgpr_write_b32 a48, v0
	v_accvgpr_write_b32 a49, v1
	v_accvgpr_write_b32 a50, v2
	v_accvgpr_write_b32 a51, v3
	v_accvgpr_write_b32 a52, v4
	v_accvgpr_write_b32 a53, v5
	v_accvgpr_write_b32 a54, v6
	v_accvgpr_write_b32 a55, v7
	v_accvgpr_write_b32 a56, v8
	v_accvgpr_write_b32 a57, v9
	v_accvgpr_write_b32 a58, v10
	v_accvgpr_write_b32 a59, v11
	v_accvgpr_write_b32 a60, v12
	v_accvgpr_write_b32 a61, v13
	v_accvgpr_write_b32 a62, v14
	v_accvgpr_write_b32 a63, v15

.LBB0_1630:
	v_exp_f32_e32 v48, v48
	v_exp_f32_e32 v49, v49
	v_exp_f32_e32 v50, v50
	v_exp_f32_e32 v51, v51
	v_exp_f32_e32 v52, v52
	v_exp_f32_e32 v53, v53
	v_exp_f32_e32 v54, v54
	v_exp_f32_e32 v55, v55
	v_exp_f32_e32 v16, v16
	v_exp_f32_e32 v17, v17
	v_exp_f32_e32 v18, v18
	v_exp_f32_e32 v19, v19
	v_exp_f32_e32 v20, v20
	v_exp_f32_e32 v21, v21
	v_exp_f32_e32 v22, v22
	v_exp_f32_e32 v23, v23
	v_lshl_add_u32 v165, s75, 1, v135
	ds_read_b128 a[80:83], v165 offset:18432
	ds_read_b128 a[84:87], v165 offset:18464
	ds_read_b128 a[88:91], v165 offset:18496
	ds_read_b128 a[92:95], v165 offset:18528
	v_cvt_pk_bf16_f32 v98, v48, v49
	v_cvt_pk_bf16_f32 v99, v50, v51
	v_cvt_pk_bf16_f32 v100, v52, v53
	v_cvt_pk_bf16_f32 v101, v54, v55
	v_cvt_pk_bf16_f32 v110, v16, v17
	v_cvt_pk_bf16_f32 v111, v18, v19
	v_cvt_pk_bf16_f32 v112, v20, v21
	v_cvt_pk_bf16_f32 v113, v22, v23
	v_accvgpr_write_b32 a16, v150
	v_accvgpr_write_b32 a17, v128
	v_accvgpr_write_b32 a18, v132
	v_accvgpr_write_b32 a19, v183
	v_accvgpr_write_b32 a20, v182
	v_accvgpr_write_b32 a21, v179
	v_accvgpr_write_b32 a22, v178
	v_accvgpr_write_b32 a23, v181
	v_accvgpr_write_b32 a24, v180
	v_accvgpr_write_b32 a25, v254
	v_accvgpr_write_b32 a26, v253
	v_accvgpr_write_b32 a27, v252
	v_accvgpr_write_b32 a28, v251
	v_accvgpr_write_b32 a29, v250
	v_accvgpr_write_b32 a30, v249
	v_accvgpr_write_b32 a31, v248
	v_accvgpr_write_b32 a0, v247
	v_accvgpr_write_b32 a1, v246
	v_accvgpr_write_b32 a2, v245
	v_accvgpr_write_b32 a3, v244
	v_accvgpr_write_b32 a4, v243
	v_accvgpr_write_b32 a5, v242
	v_accvgpr_write_b32 a6, v241
	v_accvgpr_write_b32 a7, v240
	v_accvgpr_write_b32 a8, v239
	v_accvgpr_write_b32 a9, v238
	v_accvgpr_write_b32 a10, v237
	v_accvgpr_write_b32 a11, v236
	v_accvgpr_write_b32 a12, v235
	v_accvgpr_write_b32 a13, v234
	v_accvgpr_write_b32 a14, v233
	v_accvgpr_write_b32 a15, v232
	s_waitcnt lgkmcnt(3)
	v_mfma_f32_32x32x16_bf16 a[16:31], a[80:83], v[110:113], a[16:31]
	v_exp_f32_e32 v56, v56
	v_exp_f32_e32 v57, v57
	v_exp_f32_e32 v58, v58
	v_exp_f32_e32 v59, v59
	v_exp_f32_e32 v60, v60
	v_exp_f32_e32 v61, v61
	v_exp_f32_e32 v62, v62
	v_mfma_f32_32x32x16_bf16 a[0:15], a[80:83], v[98:101], a[0:15]
	ds_read_b128 a[80:83], v165 offset:23040
	v_exp_f32_e32 v63, v63
	v_exp_f32_e32 v24, v24
	v_exp_f32_e32 v25, v25
	v_exp_f32_e32 v26, v26
	v_exp_f32_e32 v27, v27
	v_exp_f32_e32 v28, v28
	v_exp_f32_e32 v29, v29
	v_exp_f32_e32 v30, v30
	v_exp_f32_e32 v31, v31
	v_cvt_pk_bf16_f32 v102, v56, v57
	v_cvt_pk_bf16_f32 v103, v58, v59
	v_cvt_pk_bf16_f32 v104, v60, v61
	v_cvt_pk_bf16_f32 v105, v62, v63
	v_cvt_pk_bf16_f32 v114, v24, v25
	v_cvt_pk_bf16_f32 v115, v26, v27
	v_cvt_pk_bf16_f32 v116, v28, v29
	v_cvt_pk_bf16_f32 v117, v30, v31
	s_waitcnt lgkmcnt(3)
	v_mfma_f32_32x32x16_bf16 a[16:31], a[84:87], v[114:117], a[16:31]
	v_exp_f32_e32 v32, v32
	v_exp_f32_e32 v33, v33
	v_exp_f32_e32 v34, v34
	v_exp_f32_e32 v35, v35
	v_exp_f32_e32 v36, v36
	v_exp_f32_e32 v37, v37
	v_exp_f32_e32 v38, v38
	v_mfma_f32_32x32x16_bf16 a[0:15], a[84:87], v[102:105], a[0:15]
	ds_read_b128 a[84:87], v165 offset:23072
	v_exp_f32_e32 v39, v39
	v_exp_f32_e32 v0, v0
	v_exp_f32_e32 v1, v1
	v_exp_f32_e32 v2, v2
	v_exp_f32_e32 v3, v3
	v_exp_f32_e32 v4, v4
	v_exp_f32_e32 v5, v5
	v_exp_f32_e32 v6, v6
	v_exp_f32_e32 v7, v7
	v_cvt_pk_bf16_f32 v106, v32, v33
	v_cvt_pk_bf16_f32 v107, v34, v35
	v_cvt_pk_bf16_f32 v118, v0, v1
	v_cvt_pk_bf16_f32 v119, v2, v3
	v_cvt_pk_bf16_f32 v120, v4, v5
	v_cvt_pk_bf16_f32 v121, v6, v7
	v_cvt_pk_bf16_f32 v108, v36, v37
	v_cvt_pk_bf16_f32 v109, v38, v39
	s_waitcnt lgkmcnt(3)
	v_mfma_f32_32x32x16_bf16 a[16:31], a[88:91], v[118:121], a[16:31]
	v_exp_f32_e32 v40, v40
	v_exp_f32_e32 v41, v41
	v_exp_f32_e32 v42, v42
	v_exp_f32_e32 v43, v43
	v_exp_f32_e32 v44, v44
	v_exp_f32_e32 v8, v8
	v_exp_f32_e32 v9, v9
	v_mfma_f32_32x32x16_bf16 a[0:15], a[88:91], v[106:109], a[0:15]
	ds_read_b128 a[88:91], v165 offset:23104
	v_exp_f32_e32 v10, v10
	v_exp_f32_e32 v11, v11
	v_exp_f32_e32 v12, v12
	v_exp_f32_e32 v13, v13
	v_exp_f32_e32 v14, v14
	v_exp_f32_e32 v15, v15
	v_exp_f32_e32 v45, v45
	v_exp_f32_e32 v46, v46
	v_exp_f32_e32 v47, v47
	v_cvt_pk_bf16_f32 v178, v8, v9
	v_cvt_pk_bf16_f32 v179, v10, v11
	v_cvt_pk_bf16_f32 v180, v12, v13
	v_cvt_pk_bf16_f32 v181, v14, v15
	v_cvt_pk_bf16_f32 v236, v40, v41
	v_cvt_pk_bf16_f32 v237, v42, v43
	v_cvt_pk_bf16_f32 v238, v44, v45
	v_cvt_pk_bf16_f32 v239, v46, v47
	s_waitcnt lgkmcnt(3)
	v_mfma_f32_32x32x16_bf16 a[16:31], a[92:95], v[178:181], a[16:31]
	v_accvgpr_write_b32 a48, v231
	v_accvgpr_write_b32 a49, v230
	v_accvgpr_write_b32 a50, v229
	v_accvgpr_write_b32 a51, v228
	v_accvgpr_write_b32 a52, v227
	v_accvgpr_write_b32 a53, v226
	v_accvgpr_write_b32 a54, v225
	v_mfma_f32_32x32x16_bf16 a[0:15], a[92:95], v[236:239], a[0:15]
	ds_read_b128 a[92:95], v165 offset:23136
	v_accvgpr_write_b32 a55, v224
	v_accvgpr_write_b32 a56, v223
	v_accvgpr_write_b32 a57, v222
	v_accvgpr_write_b32 a58, v221
	v_accvgpr_write_b32 a59, v220
	v_accvgpr_write_b32 a60, v219
	v_accvgpr_write_b32 a61, v218
	v_accvgpr_write_b32 a62, v217
	v_accvgpr_write_b32 a63, v216
	v_accvgpr_write_b32 a32, v215
	v_accvgpr_write_b32 a33, v214
	v_accvgpr_write_b32 a34, v213
	v_accvgpr_write_b32 a35, v212
	v_accvgpr_write_b32 a36, v211
	v_accvgpr_write_b32 a37, v210
	v_accvgpr_write_b32 a38, v209
	v_accvgpr_write_b32 a39, v208
	v_accvgpr_write_b32 a40, v207
	v_accvgpr_write_b32 a41, v206
	v_accvgpr_write_b32 a42, v205
	v_accvgpr_write_b32 a43, v204
	v_accvgpr_write_b32 a44, v203
	v_accvgpr_write_b32 a45, v202
	v_accvgpr_write_b32 a46, v201
	v_accvgpr_write_b32 a47, v200
	s_waitcnt lgkmcnt(3)
	v_mfma_f32_32x32x16_bf16 a[48:63], a[80:83], v[110:113], a[48:63]
	s_and_b64 vcc, exec, s[10:11]
	s_mov_b64 s[10:11], -1
	v_mfma_f32_32x32x16_bf16 a[32:47], a[80:83], v[98:101], a[32:47]
	s_waitcnt lgkmcnt(2)
	v_mfma_f32_32x32x16_bf16 a[48:63], a[84:87], v[114:117], a[48:63]
	v_mfma_f32_32x32x16_bf16 a[32:47], a[84:87], v[102:105], a[32:47]
	s_waitcnt lgkmcnt(1)
	v_mfma_f32_32x32x16_bf16 a[48:63], a[88:91], v[118:121], a[48:63]
	v_mfma_f32_32x32x16_bf16 a[32:47], a[88:91], v[106:109], a[32:47]
	s_waitcnt lgkmcnt(0)
	v_mfma_f32_32x32x16_bf16 a[48:63], a[92:95], v[178:181], a[48:63]
	v_mfma_f32_32x32x16_bf16 a[32:47], a[92:95], v[236:239], a[32:47]
	s_cbranch_vccnz .LBB0_1632
	s_mov_b64 s[10:11], 0
	s_waitcnt vmcnt(1)
	ds_write_b128 v151, a[124:127] offset:18432
	s_waitcnt vmcnt(0)
	ds_write_b128 v163, a[128:131] offset:18432

.LBB0_1643:
	s_or_b64 exec, exec, s[60:61]
	s_waitcnt lgkmcnt(0)
	s_barrier
	ds_read_b128 a[32:35], v137 offset:43520
	ds_read_b128 a[36:39], v137 offset:43552
	ds_read_b128 a[40:43], v149
	ds_read_b128 a[44:47], v149 offset:4608
	ds_read_b128 v[52:55], v149 offset:32
	s_waitcnt lgkmcnt(2)
	v_mfma_f32_32x32x16_bf16 a[16:31], a[32:35], a[40:43], 0
	ds_read_b128 a[40:43], v149 offset:4640
	s_lshl_b32 s2, s66, 13
	s_mov_b32 s66, 1
	s_mov_b64 s[60:61], 0
	s_waitcnt lgkmcnt(2)
	v_mfma_f32_32x32x16_bf16 a[0:15], a[32:35], a[44:47], 0
	ds_read_b128 a[32:35], v137 offset:43584
	ds_read_b128 a[44:47], v149 offset:64
	s_waitcnt lgkmcnt(3)
	v_mfma_f32_32x32x16_bf16 a[16:31], a[36:39], v[52:55], a[16:31]
	s_waitcnt lgkmcnt(2)
	v_mfma_f32_32x32x16_bf16 a[0:15], a[36:39], a[40:43], a[0:15]
	ds_read_b128 a[36:39], v149 offset:4672
	ds_read_b128 a[40:43], v137 offset:43616
	s_waitcnt lgkmcnt(2)
	v_mfma_f32_32x32x16_bf16 a[16:31], a[32:35], a[44:47], a[16:31]
	ds_read_b128 a[44:47], v149 offset:96
	s_waitcnt lgkmcnt(2)
	v_mfma_f32_32x32x16_bf16 a[0:15], a[32:35], a[36:39], a[0:15]
	ds_read_b128 a[32:35], v149 offset:4704
	s_waitcnt lgkmcnt(1)
	v_mfma_f32_32x32x16_bf16 a[16:31], a[40:43], a[44:47], a[16:31]
	s_waitcnt lgkmcnt(0)
	v_mfma_f32_32x32x16_bf16 a[0:15], a[40:43], a[32:35], a[0:15]
	v_lshl_add_u64 v[36:37], s[2:3], 2, v[32:33]
	s_movk_i32 s2, 0x1000
	v_add_co_u32_e32 v38, vcc, s2, v36
	s_movk_i32 s2, 0x2000
	s_nop 0
	v_addc_co_u32_e32 v39, vcc, 0, v37, vcc
	v_add_co_u32_e32 v40, vcc, s2, v36
	s_movk_i32 s2, 0x3000
	s_nop 0
	v_addc_co_u32_e32 v41, vcc, 0, v37, vcc
	v_add_co_u32_e32 v42, vcc, s2, v36
	global_store_dword v[36:37], a16, off
	global_store_dword v[36:37], a17, off offset:512
	global_store_dword v[36:37], a18, off offset:1024
	global_store_dword v[36:37], a19, off offset:1536
	v_addc_co_u32_e32 v43, vcc, 0, v37, vcc
	s_and_b64 vcc, exec, s[10:11]
	global_store_dword v[40:41], a20, off offset:-4096
	global_store_dword v[38:39], a21, off offset:512
	global_store_dword v[38:39], a22, off offset:1024
	global_store_dword v[38:39], a23, off offset:1536
	global_store_dword v[40:41], a24, off
	global_store_dword v[40:41], a25, off offset:512
	global_store_dword v[40:41], a26, off offset:1024
	global_store_dword v[40:41], a27, off offset:1536
	global_store_dword v[42:43], a28, off
	global_store_dword v[42:43], a29, off offset:512
	global_store_dword v[42:43], a30, off offset:1024
	global_store_dword v[42:43], a31, off offset:1536
	global_store_dword v[36:37], a0, off offset:128
	global_store_dword v[36:37], a1, off offset:640
	global_store_dword v[36:37], a2, off offset:1152
	global_store_dword v[36:37], a3, off offset:1664
	global_store_dword v[38:39], a4, off offset:128
	global_store_dword v[38:39], a5, off offset:640
	global_store_dword v[38:39], a6, off offset:1152
	global_store_dword v[38:39], a7, off offset:1664
	global_store_dword v[40:41], a8, off offset:128
	global_store_dword v[40:41], a9, off offset:640
	global_store_dword v[40:41], a10, off offset:1152
	global_store_dword v[40:41], a11, off offset:1664
	global_store_dword v[42:43], a12, off offset:128
	global_store_dword v[42:43], a13, off offset:640
	global_store_dword v[42:43], a14, off offset:1152
	global_store_dword v[42:43], a15, off offset:1664
	s_barrier
	s_cbranch_vccz .LBB0_1639

.LBB0_1779:
	s_or_b64 exec, exec, s[80:81]
	s_waitcnt lgkmcnt(0)
	s_barrier
	global_load_ushort v6, v[188:189], off
	global_load_ushort v7, v[190:191], off
	global_load_ushort v8, v[192:193], off
	global_load_ushort v9, v[194:195], off
	global_load_ushort v10, v[198:199], off
	global_load_ushort v11, v[206:207], off
	global_load_ushort v12, v[222:223], off
	global_load_ushort v13, v[224:225], off
	global_load_ushort v14, v[226:227], off
	global_load_ushort v15, v[232:233], off
	global_load_ushort v16, v[236:237], off
	v_accvgpr_read_b32 v206, a54
	v_accvgpr_read_b32 v104, a55
	v_accvgpr_read_b32 v105, a56
	v_accvgpr_read_b32 v108, a57
	ds_read_b32 v17, v206 offset:36096
	ds_read2_b32 v[0:1], v104 offset0:64 offset1:129
	ds_read2_b32 v[2:3], v105 offset0:66 offset1:131
	ds_read2_b32 v[4:5], v108 offset0:68 offset1:133
	global_load_ushort v18, v[228:229], off
	global_load_ushort v19, v[230:231], off
	global_load_ushort v20, v[234:235], off
	global_load_ushort v21, v[238:239], off
	global_load_ushort v22, v[240:241], off
	global_load_ushort v23, v[242:243], off
	global_load_ushort v24, v[244:245], off
	global_load_ushort v25, v[246:247], off
	global_load_ushort v26, v[248:249], off
	s_waitcnt lgkmcnt(3)
	v_mul_f32_e32 v28, 0x3fb8aa3b, v17
	s_waitcnt lgkmcnt(2)
	v_mul_f32_e32 v29, 0x3fb8aa3b, v0
	v_mul_f32_e32 v0, 0xbfb8aa3b, v0
	v_mul_f32_e32 v30, 0x3fb8aa3b, v1
	s_waitcnt lgkmcnt(1)
	v_mul_f32_e32 v31, 0x3fb8aa3b, v2
	v_mul_f32_e32 v17, 0xbfb8aa3b, v17
	v_mul_f32_e32 v1, 0xbfb8aa3b, v1
	v_mul_f32_e32 v2, 0xbfb8aa3b, v2
	v_exp_f32_e32 v28, v28
	v_exp_f32_e32 v0, v0
	v_exp_f32_e32 v30, v30
	v_exp_f32_e32 v31, v31
	v_exp_f32_e32 v17, v17
	v_exp_f32_e32 v29, v29
	v_exp_f32_e32 v1, v1
	v_exp_f32_e32 v2, v2
	v_accvgpr_read_b32 v27, a81
	v_accvgpr_read_b32 v106, a48
	v_accvgpr_read_b32 v226, a49
	ds_read_b32 v27, v27 offset:39736
	v_mul_f32_e32 v32, 0x3fb8aa3b, v3
	v_mul_f32_e32 v3, 0xbfb8aa3b, v3
	v_exp_f32_e32 v3, v3
	v_exp_f32_e32 v32, v32
	v_accvgpr_read_b32 v228, a50
	v_accvgpr_read_b32 v109, a58
	v_accvgpr_read_b32 v110, a59
	v_accvgpr_read_b32 v111, a60
	v_accvgpr_read_b32 v112, a61
	s_add_u32 s76, s90, s76
	s_addc_u32 s77, s91, s77
	v_mov_b32_e32 v119, v65
	v_mov_b32_e32 v121, v65
	v_mov_b32_e32 v123, v65
	v_mov_b32_e32 v125, v65
	v_mov_b32_e32 v127, v65
	v_mov_b32_e32 v149, v65
	v_mov_b32_e32 v151, v65
	v_mov_b32_e32 v153, v65
	v_mov_b32_e32 v155, v65
	v_mov_b32_e32 v157, v65
	v_mov_b32_e32 v159, v65
	v_mov_b32_e32 v161, v65
	v_mov_b32_e32 v163, v65
	v_mov_b32_e32 v165, v65
	v_mov_b32_e32 v167, v65
	v_mov_b32_e32 v169, v65
	v_mov_b32_e32 v171, v65
	v_mov_b32_e32 v173, v65
	v_mov_b32_e32 v175, v65
	v_mov_b32_e32 v177, v65
	v_mov_b32_e32 v179, v65
	v_mov_b32_e32 v181, v65
	v_mov_b32_e32 v183, v65
	v_mov_b32_e32 v185, v65
	v_mov_b32_e32 v187, v65
	s_lshl_b32 s88, s4, 1
	v_mov_b32_e32 v115, v65
	s_mov_b64 s[4:5], 0x186fa500
	s_add_i32 s72, s84, s72
	s_waitcnt vmcnt(19)
	v_lshlrev_b32_e32 v6, 16, v6
	s_waitcnt vmcnt(18)
	v_lshlrev_b32_e32 v7, 16, v7
	s_waitcnt vmcnt(17)
	v_lshlrev_b32_e32 v8, 16, v8
	s_waitcnt vmcnt(16)
	v_lshlrev_b32_e32 v9, 16, v9
	s_waitcnt vmcnt(15)
	v_lshlrev_b32_e32 v10, 16, v10
	s_waitcnt vmcnt(14)
	v_lshlrev_b32_e32 v11, 16, v11
	s_waitcnt vmcnt(13)
	v_lshlrev_b32_e32 v12, 16, v12
	s_waitcnt vmcnt(12)
	v_lshlrev_b32_e32 v13, 16, v13
	v_mul_f32_e32 v6, v28, v6
	v_mul_f32_e32 v0, v0, v9
	v_mul_f32_e32 v9, v30, v10
	v_mul_f32_e32 v10, v31, v12
	v_mul_f32_e32 v7, v17, v7
	v_mul_f32_e32 v8, v29, v8
	v_mul_f32_e32 v1, v1, v11
	v_mul_f32_e32 v2, v2, v13
	v_cvt_pk_bf16_f32 v6, v6, s0
	v_cvt_pk_bf16_f32 v9, v9, s0
	v_cvt_pk_bf16_f32 v10, v10, s0
	v_cvt_pk_bf16_f32 v7, v7, s0
	v_cvt_pk_bf16_f32 v8, v8, s0
	v_cvt_pk_bf16_f32 v0, v0, s0
	v_cvt_pk_bf16_f32 v1, v1, s0
	v_cvt_pk_bf16_f32 v2, v2, s0
	ds_write_b16 v135, v6 offset:52736
	ds_write_b16 v135, v7 offset:61952
	ds_write_b16 v254, v8 offset:52736
	ds_write_b16 v254, v0 offset:61952
	ds_write_b16 v106, v9 offset:52736
	ds_write_b16 v106, v1 offset:61952
	ds_write_b16 v226, v10 offset:52736
	ds_write_b16 v226, v2 offset:61952
	global_load_ushort v2, v[200:201], off
	global_load_ushort v6, v[208:209], off
	global_load_ushort v7, v[210:211], off
	global_load_ushort v10, v[214:215], off
	s_waitcnt lgkmcnt(9)
	v_mul_f32_e32 v1, 0x3fb8aa3b, v4
	s_waitcnt vmcnt(14)
	v_lshlrev_b32_e32 v0, 16, v15
	v_exp_f32_e32 v1, v1
	v_mul_f32_e32 v0, v3, v0
	v_cvt_pk_bf16_f32 v0, v0, s0
	global_load_ushort v3, v[202:203], off
	global_load_ushort v15, v[252:253], off
	ds_write_b16 v228, v0 offset:61952
	s_waitcnt vmcnt(15)
	v_lshlrev_b32_e32 v0, 16, v16
	v_lshlrev_b32_e32 v14, 16, v14
	v_mul_f32_e32 v0, v1, v0
	v_mul_f32_e32 v1, 0xbfb8aa3b, v4
	v_mul_f32_e32 v11, v32, v14
	v_exp_f32_e32 v1, v1
	v_cvt_pk_bf16_f32 v11, v11, s0
	global_load_ushort v4, v[204:205], off
	ds_write_b16 v228, v11 offset:52736
	v_cvt_pk_bf16_f32 v0, v0, s0
	global_load_ushort v11, v[218:219], off
	v_accvgpr_read_b32 v202, a51
	ds_write_b16 v202, v0 offset:52736
	s_waitcnt vmcnt(16)
	v_lshlrev_b32_e32 v0, 16, v18
	v_mul_f32_e32 v0, v1, v0
	v_mul_f32_e32 v1, 0x3fb8aa3b, v5
	v_exp_f32_e32 v1, v1
	v_cvt_pk_bf16_f32 v0, v0, s0
	ds_write_b16 v202, v0 offset:61952
	s_waitcnt vmcnt(15)
	v_lshlrev_b32_e32 v0, 16, v19
	v_mul_f32_e32 v0, v1, v0
	v_cvt_pk_bf16_f32 v0, v0, s0
	v_mul_f32_e32 v1, 0xbfb8aa3b, v5
	v_accvgpr_read_b32 v203, a52
	v_exp_f32_e32 v5, v1
	ds_write_b16 v203, v0 offset:52736
	ds_read2_b32 v[0:1], v109 offset0:70 offset1:135
	s_waitcnt vmcnt(14)
	v_lshlrev_b32_e32 v8, 16, v20
	v_mul_f32_e32 v5, v5, v8
	global_load_ushort v8, v[212:213], off
	v_cvt_pk_bf16_f32 v5, v5, s0
	s_waitcnt lgkmcnt(0)
	v_mul_f32_e32 v9, 0x3fb8aa3b, v0
	v_exp_f32_e32 v9, v9
	ds_write_b16 v203, v5 offset:61952
	s_waitcnt vmcnt(14)
	v_lshlrev_b32_e32 v5, 16, v21
	v_mul_f32_e32 v0, 0xbfb8aa3b, v0
	v_mul_f32_e32 v5, v9, v5
	v_cvt_pk_bf16_f32 v5, v5, s0
	v_exp_f32_e32 v0, v0
	v_accvgpr_read_b32 v204, a53
	ds_write_b16 v204, v5 offset:52736
	global_load_ushort v5, v[216:217], off
	s_waitcnt vmcnt(14)
	v_lshlrev_b32_e32 v9, 16, v22
	v_mul_f32_e32 v0, v0, v9
	v_mul_f32_e32 v9, 0x3fb8aa3b, v1
	v_exp_f32_e32 v9, v9
	v_cvt_pk_bf16_f32 v0, v0, s0
	ds_write_b16 v204, v0 offset:61952
	s_waitcnt vmcnt(13)
	v_lshlrev_b32_e32 v0, 16, v23
	v_mul_f32_e32 v0, v9, v0
	v_mul_f32_e32 v1, 0xbfb8aa3b, v1
	global_load_ushort v9, v[220:221], off
	v_exp_f32_e32 v12, v1
	s_waitcnt vmcnt(13)
	v_lshlrev_b32_e32 v13, 16, v24
	v_cvt_pk_bf16_f32 v0, v0, s0
	ds_write_b16 v73, v0 offset:52736
	v_mul_f32_e32 v12, v12, v13
	global_load_ushort v13, v[250:251], off
	ds_read2_b32 v[0:1], v110 offset0:72 offset1:137
	v_cvt_pk_bf16_f32 v12, v12, s0
	ds_write_b16 v73, v12 offset:61952
	s_waitcnt vmcnt(13)
	v_lshlrev_b32_e32 v12, 16, v25
	s_add_i32 s86, s86, s85
	s_waitcnt lgkmcnt(1)
	v_mul_f32_e32 v14, 0x3fb8aa3b, v0
	v_exp_f32_e32 v14, v14
	v_mul_f32_e32 v0, 0xbfb8aa3b, v0
	v_exp_f32_e32 v0, v0
	s_cmpk_gt_i32 s72, 0x5ff
	v_mul_f32_e32 v12, v14, v12
	v_cvt_pk_bf16_f32 v12, v12, s0
	ds_write_b16 v128, v12 offset:52736
	s_waitcnt vmcnt(12)
	v_lshlrev_b32_e32 v12, 16, v26
	v_mul_f32_e32 v0, v0, v12
	v_mul_f32_e32 v12, 0x3fb8aa3b, v1
	v_exp_f32_e32 v12, v12
	v_cvt_pk_bf16_f32 v0, v0, s0
	ds_write_b16 v128, v0 offset:61952
	s_waitcnt vmcnt(11)
	v_lshlrev_b32_e32 v0, 16, v2
	v_mul_f32_e32 v2, v12, v0
	v_mul_f32_e32 v0, 0xbfb8aa3b, v1
	v_exp_f32_e32 v12, v0
	ds_read2_b32 v[0:1], v111 offset0:74 offset1:139
	v_cvt_pk_bf16_f32 v2, v2, s0
	ds_write_b16 v107, v2 offset:52736
	s_waitcnt vmcnt(7)
	v_lshlrev_b32_e32 v2, 16, v3
	v_mul_f32_e32 v2, v12, v2
	s_waitcnt lgkmcnt(1)
	v_mul_f32_e32 v3, 0x3fb8aa3b, v0
	v_exp_f32_e32 v3, v3
	v_cvt_pk_bf16_f32 v2, v2, s0
	v_mul_f32_e32 v0, 0xbfb8aa3b, v0
	ds_write_b16 v107, v2 offset:61952
	s_waitcnt vmcnt(5)
	v_lshlrev_b32_e32 v2, 16, v4
	v_exp_f32_e32 v0, v0
	v_mul_f32_e32 v2, v3, v2
	v_cvt_pk_bf16_f32 v2, v2, s0
	ds_write_b16 v78, v2 offset:52736
	v_lshlrev_b32_e32 v2, 16, v6
	v_mul_f32_e32 v0, v0, v2
	v_mul_f32_e32 v2, 0x3fb8aa3b, v1
	v_exp_f32_e32 v2, v2
	v_cvt_pk_bf16_f32 v0, v0, s0
	ds_write_b16 v78, v0 offset:61952
	v_lshlrev_b32_e32 v0, 16, v7
	v_mul_f32_e32 v2, v2, v0
	v_mul_f32_e32 v0, 0xbfb8aa3b, v1
	v_exp_f32_e32 v3, v0
	ds_read2_b32 v[0:1], v112 offset0:76 offset1:141
	v_cvt_pk_bf16_f32 v2, v2, s0
	ds_write_b16 v79, v2 offset:52736
	s_waitcnt vmcnt(3)
	v_lshlrev_b32_e32 v2, 16, v8
	v_mul_f32_e32 v2, v3, v2
	s_waitcnt lgkmcnt(1)
	v_mul_f32_e32 v3, 0x3fb8aa3b, v0
	v_exp_f32_e32 v3, v3
	v_cvt_pk_bf16_f32 v2, v2, s0
	v_mul_f32_e32 v0, 0xbfb8aa3b, v0
	ds_write_b16 v79, v2 offset:61952
	v_lshlrev_b32_e32 v2, 16, v10
	v_exp_f32_e32 v0, v0
	v_mul_f32_e32 v2, v3, v2
	v_cvt_pk_bf16_f32 v2, v2, s0
	ds_write_b16 v129, v2 offset:52736
	s_waitcnt vmcnt(2)
	v_lshlrev_b32_e32 v2, 16, v5
	v_mul_f32_e32 v0, v0, v2
	v_mul_f32_e32 v2, 0x3fb8aa3b, v1
	v_exp_f32_e32 v2, v2
	v_cvt_pk_bf16_f32 v0, v0, s0
	v_mul_f32_e32 v1, 0xbfb8aa3b, v1
	ds_write_b16 v129, v0 offset:61952
	v_lshlrev_b32_e32 v0, 16, v11
	v_exp_f32_e32 v1, v1
	v_mul_f32_e32 v0, v2, v0
	v_cvt_pk_bf16_f32 v0, v0, s0
	ds_write_b16 v68, v0 offset:52736
	s_waitcnt vmcnt(1)
	v_lshlrev_b32_e32 v0, 16, v9
	v_mul_f32_e32 v0, v1, v0
	v_mul_f32_e32 v1, 0x3fb8aa3b, v27
	v_exp_f32_e32 v1, v1
	v_cvt_pk_bf16_f32 v0, v0, s0
	ds_write_b16 v68, v0 offset:61952
	s_waitcnt vmcnt(0)
	v_lshlrev_b32_e32 v0, 16, v13
	v_mul_f32_e32 v0, v1, v0
	v_mul_f32_e32 v1, 0xbfb8aa3b, v27
	v_exp_f32_e32 v1, v1
	v_cvt_pk_bf16_f32 v0, v0, s0
	ds_write_b16 v69, v0 offset:52736
	v_lshlrev_b32_e32 v0, 16, v15
	v_mul_f32_e32 v0, v1, v0
	v_cvt_pk_bf16_f32 v0, v0, s0
	ds_write_b16 v69, v0 offset:61952
	s_waitcnt lgkmcnt(0)
	s_barrier
	ds_read_b128 a[152:155], v132 offset:52736
	ds_read_b128 a[156:159], v133 offset:61952
	ds_read_b128 a[160:163], v132 offset:52768
	ds_read_b128 a[164:167], v133 offset:61984
	s_waitcnt lgkmcnt(2)
	v_mfma_f32_32x32x16_bf16 a[48:63], a[152:155], a[156:159], 0
	ds_read_b128 a[152:155], v132 offset:52800
	ds_read_b128 a[156:159], v133 offset:62016
	v_accvgpr_read_b32 v139, a77
	s_waitcnt lgkmcnt(2)
	v_mfma_f32_32x32x16_bf16 a[48:63], a[160:163], a[164:167], a[48:63]
	ds_read_b128 a[160:163], v132 offset:52832
	ds_read_b128 a[164:167], v133 offset:62048
	s_waitcnt lgkmcnt(2)
	v_mfma_f32_32x32x16_bf16 a[48:63], a[152:155], a[156:159], a[48:63]
	ds_read_b128 a[152:155], v82 offset:52736
	ds_read_b128 a[156:159], v82 offset:52768
	v_accvgpr_read_b32 v0, a64
	v_accvgpr_read_b32 v1, a65
	v_lshl_add_u64 v[0:1], v[0:1], 2, s[76:77]
	v_lshl_add_u64 v[0:1], v[0:1], 0, v[64:65]
	s_mov_b64 s[76:77], 0x2c802100
	v_lshl_add_u64 v[20:21], v[0:1], 0, s[76:77]
	v_lshl_add_u64 v[0:1], v[20:21], 0, v[118:119]
	global_load_dword v4, v[0:1], off
	global_load_dword v5, v[0:1], off offset:512
	global_load_dword v6, v[0:1], off offset:1024
	global_load_dword v7, v[0:1], off offset:1536
	global_load_dword v16, v[0:1], off offset:2048
	global_load_dword v17, v[0:1], off offset:2560
	global_load_dword v18, v[0:1], off offset:3072
	global_load_dword v19, v[0:1], off offset:3584
	s_waitcnt lgkmcnt(2)
	v_mfma_f32_32x32x16_bf16 a[48:63], a[160:163], a[164:167], a[48:63]
	ds_read_b128 a[160:163], v82 offset:57344
	ds_read_b128 a[164:167], v82 offset:57376
	v_lshl_add_u64 v[22:23], v[20:21], 0, v[152:153]
	v_lshl_add_u64 v[24:25], v[20:21], 0, v[154:155]
	v_readlane_b32 s76, v255, 18
	v_readlane_b32 s77, v255, 19
	s_waitcnt vmcnt(6)
	v_cvt_pk_bf16_f32 v4, v4, v5
	s_waitcnt vmcnt(4)
	v_cvt_pk_bf16_f32 v5, v6, v7
	s_waitcnt vmcnt(2)
	v_cvt_pk_bf16_f32 v6, v16, v17
	v_lshl_add_u64 v[16:17], v[20:21], 0, v[148:149]
	s_waitcnt vmcnt(0)
	v_cvt_pk_bf16_f32 v7, v18, v19
	v_lshl_add_u64 v[18:19], v[20:21], 0, v[150:151]
	s_waitcnt lgkmcnt(3)
	v_mfma_f32_32x32x16_bf16 a[16:31], a[152:155], v[4:7], a[16:31]
	ds_read_b128 a[152:155], v82 offset:52800
	s_waitcnt lgkmcnt(2)
	v_mfma_f32_32x32x16_bf16 a[0:15], a[160:163], v[4:7], a[0:15]
	ds_read_b128 a[160:163], v82 offset:57408
	v_lshl_add_u64 v[0:1], v[20:21], 0, v[120:121]
	v_lshl_add_u64 v[2:3], v[20:21], 0, v[122:123]
	v_lshl_add_u64 v[4:5], v[20:21], 0, v[124:125]
	v_lshl_add_u64 v[6:7], v[20:21], 0, v[126:127]
	global_load_dword v0, v[0:1], off
	s_nop 0
	global_load_dword v1, v[2:3], off
	s_nop 0
	global_load_dword v2, v[4:5], off
	global_load_dword v3, v[6:7], off
	s_nop 0
	global_load_dword v4, v[16:17], off
	global_load_dword v5, v[18:19], off
	global_load_dword v6, v[22:23], off
	global_load_dword v7, v[24:25], off
	v_lshl_add_u64 v[16:17], v[20:21], 0, v[164:165]
	v_lshl_add_u64 v[18:19], v[20:21], 0, v[166:167]
	v_lshl_add_u64 v[22:23], v[20:21], 0, v[168:169]
	v_lshl_add_u64 v[24:25], v[20:21], 0, v[170:171]
	s_waitcnt vmcnt(6)
	v_cvt_pk_bf16_f32 v0, v0, v1
	s_waitcnt vmcnt(4)
	v_cvt_pk_bf16_f32 v1, v2, v3
	s_waitcnt vmcnt(2)
	v_cvt_pk_bf16_f32 v2, v4, v5
	v_lshl_add_u64 v[4:5], v[20:21], 0, v[156:157]
	s_waitcnt vmcnt(0)
	v_cvt_pk_bf16_f32 v3, v6, v7
	v_lshl_add_u64 v[6:7], v[20:21], 0, v[158:159]
	s_nop 0
	s_waitcnt lgkmcnt(4)
	v_mfma_f32_32x32x16_bf16 a[16:31], a[156:159], v[0:3], a[16:31]
	v_lshl_add_u64 v[8:9], v[20:21], 0, v[160:161]
	v_lshl_add_u64 v[10:11], v[20:21], 0, v[162:163]
	global_load_dword v4, v[4:5], off
	s_nop 0
	global_load_dword v5, v[6:7], off
	s_nop 0
	global_load_dword v6, v[8:9], off
	global_load_dword v7, v[10:11], off
	s_nop 0
	global_load_dword v8, v[16:17], off
	global_load_dword v9, v[18:19], off
	global_load_dword v10, v[22:23], off
	global_load_dword v11, v[24:25], off
	v_lshl_add_u64 v[22:23], v[20:21], 0, v[184:185]
	s_waitcnt vmcnt(6)
	v_cvt_pk_bf16_f32 v4, v4, v5
	s_waitcnt lgkmcnt(2)
	v_mfma_f32_32x32x16_bf16 a[0:15], a[164:167], v[0:3], a[0:15]
	s_waitcnt vmcnt(4)
	v_cvt_pk_bf16_f32 v5, v6, v7
	s_waitcnt vmcnt(2)
	v_cvt_pk_bf16_f32 v6, v8, v9
	v_lshl_add_u64 v[12:13], v[20:21], 0, v[180:181]
	s_waitcnt vmcnt(0)
	v_cvt_pk_bf16_f32 v7, v10, v11
	ds_read_b128 v[8:11], v82 offset:52832
	v_lshl_add_u64 v[14:15], v[20:21], 0, v[182:183]
	s_waitcnt lgkmcnt(2)
	v_mfma_f32_32x32x16_bf16 a[16:31], a[152:155], v[4:7], a[16:31]
	ds_read_b128 v[16:19], v82 offset:57440
	s_waitcnt lgkmcnt(2)
	v_mfma_f32_32x32x16_bf16 a[0:15], a[160:163], v[4:7], a[0:15]
	v_lshl_add_u64 v[0:1], v[20:21], 0, v[172:173]
	v_lshl_add_u64 v[2:3], v[20:21], 0, v[174:175]
	v_lshl_add_u64 v[4:5], v[20:21], 0, v[176:177]
	v_lshl_add_u64 v[6:7], v[20:21], 0, v[178:179]
	v_lshl_add_u64 v[20:21], v[20:21], 0, v[186:187]
	global_load_dword v0, v[0:1], off
	s_nop 0
	global_load_dword v1, v[2:3], off
	s_nop 0
	global_load_dword v2, v[4:5], off
	global_load_dword v3, v[6:7], off
	s_nop 0
	global_load_dword v4, v[12:13], off
	global_load_dword v5, v[14:15], off
	global_load_dword v6, v[22:23], off
	global_load_dword v7, v[20:21], off
	s_waitcnt lgkmcnt(0)
	s_barrier
	s_waitcnt vmcnt(6)
	v_cvt_pk_bf16_f32 v20, v0, v1
	s_waitcnt vmcnt(4)
	v_cvt_pk_bf16_f32 v21, v2, v3
	s_waitcnt vmcnt(2)
	v_cvt_pk_bf16_f32 v22, v4, v5
	s_waitcnt vmcnt(0)
	v_cvt_pk_bf16_f32 v23, v6, v7
	s_nop 1
	v_mfma_f32_32x32x16_bf16 a[16:31], v[8:11], v[20:23], a[16:31]
	v_accvgpr_read_b32 v0, a32
	v_cndmask_b32_e64 v0, v0, 0, s[8:9]
	v_accvgpr_read_b32 v1, a33
	v_accvgpr_read_b32 v2, a34
	v_accvgpr_read_b32 v3, a35
	v_accvgpr_read_b32 v4, a36
	v_accvgpr_read_b32 v5, a37
	v_mfma_f32_32x32x16_bf16 a[0:15], v[16:19], v[20:23], a[0:15]
	v_accvgpr_read_b32 v16, a48
	v_cndmask_b32_e64 v16, v16, 0, s[76:77]
	v_add_f32_e32 v0, v0, v16
	v_readlane_b32 s76, v255, 20
	v_cvt_pk_bf16_f32 v0, v0, s0
	v_readlane_b32 s77, v255, 21
	ds_write_b16 v83, v0 offset:18432
	v_accvgpr_read_b32 v6, a38
	v_cndmask_b32_e64 v0, v1, 0, s[76:77]
	v_accvgpr_read_b32 v1, a49
	v_cndmask_b32_e64 v1, 0, v1, s[8:9]
	v_add_f32_e32 v0, v0, v1
	v_readlane_b32 s76, v255, 22
	v_cvt_pk_bf16_f32 v0, v0, s0
	v_readlane_b32 s77, v255, 23
	ds_write_b16 v83, v0 offset:18576
	v_accvgpr_read_b32 v1, a50
	v_cndmask_b32_e64 v0, v2, 0, s[76:77]
	v_readlane_b32 s76, v255, 16
	v_readlane_b32 s77, v255, 17
	v_accvgpr_read_b32 v7, a39
	v_accvgpr_read_b32 v8, a40
	v_cndmask_b32_e64 v1, v1, 0, s[76:77]
	v_add_f32_e32 v0, v0, v1
	v_readlane_b32 s76, v255, 26
	v_cvt_pk_bf16_f32 v0, v0, s0
	v_readlane_b32 s77, v255, 27
	v_accvgpr_read_b32 v1, a51
	ds_write_b16 v83, v0 offset:18720
	v_cndmask_b32_e64 v0, v3, 0, s[76:77]
	v_cndmask_b32_e64 v1, v1, 0, s[20:21]
	v_add_f32_e32 v0, v0, v1
	v_cvt_pk_bf16_f32 v0, v0, s0
	v_accvgpr_read_b32 v1, a52
	ds_write_b16 v83, v0 offset:18864
	v_cndmask_b32_e64 v0, v4, 0, s[22:23]
	v_cndmask_b32_e64 v1, v1, 0, s[24:25]
	v_add_f32_e32 v0, v0, v1
	v_cvt_pk_bf16_f32 v0, v0, s0
	v_accvgpr_read_b32 v1, a53
	ds_write_b16 v83, v0 offset:19584
	v_cndmask_b32_e64 v0, v5, 0, s[26:27]
	v_cndmask_b32_e64 v1, v1, 0, s[28:29]
	v_add_f32_e32 v0, v0, v1
	v_cvt_pk_bf16_f32 v0, v0, s0
	v_accvgpr_read_b32 v1, a54
	ds_write_b16 v83, v0 offset:19728
	v_cndmask_b32_e64 v0, v6, 0, s[30:31]
	v_cndmask_b32_e64 v1, v1, 0, s[34:35]
	v_add_f32_e32 v0, v0, v1
	v_cvt_pk_bf16_f32 v0, v0, s0
	v_accvgpr_read_b32 v1, a55
	ds_write_b16 v83, v0 offset:19872
	v_cndmask_b32_e64 v0, v7, 0, s[36:37]
	v_cndmask_b32_e64 v1, v1, 0, s[38:39]
	v_add_f32_e32 v0, v0, v1
	v_cvt_pk_bf16_f32 v0, v0, s0
	v_accvgpr_read_b32 v1, a56
	ds_write_b16 v83, v0 offset:20016
	v_cndmask_b32_e64 v0, v8, 0, s[40:41]
	v_cndmask_b32_e64 v1, v1, 0, s[42:43]
	v_add_f32_e32 v0, v0, v1
	v_accvgpr_read_b32 v9, a41
	v_cvt_pk_bf16_f32 v0, v0, s0
	v_accvgpr_read_b32 v1, a57
	ds_write_b16 v83, v0 offset:20736
	v_cndmask_b32_e64 v0, v9, 0, s[44:45]
	v_cndmask_b32_e64 v1, v1, 0, s[46:47]
	v_add_f32_e32 v0, v0, v1
	v_accvgpr_read_b32 v10, a42
	v_cvt_pk_bf16_f32 v0, v0, s0
	v_accvgpr_read_b32 v1, a58
	ds_write_b16 v83, v0 offset:20880
	v_cndmask_b32_e64 v0, v10, 0, s[48:49]
	v_cndmask_b32_e64 v1, v1, 0, s[50:51]
	v_add_f32_e32 v0, v0, v1
	v_accvgpr_read_b32 v11, a43
	v_cvt_pk_bf16_f32 v0, v0, s0
	v_accvgpr_read_b32 v1, a59
	ds_write_b16 v83, v0 offset:21024
	v_cndmask_b32_e64 v0, v11, 0, s[52:53]
	v_cndmask_b32_e64 v1, v1, 0, s[54:55]
	v_add_f32_e32 v0, v0, v1
	v_accvgpr_read_b32 v12, a44
	v_cvt_pk_bf16_f32 v0, v0, s0
	v_accvgpr_read_b32 v1, a60
	ds_write_b16 v83, v0 offset:21168
	v_cndmask_b32_e64 v0, v12, 0, s[56:57]
	v_cndmask_b32_e64 v1, v1, 0, s[58:59]
	v_add_f32_e32 v0, v0, v1
	v_accvgpr_read_b32 v13, a45
	v_cvt_pk_bf16_f32 v0, v0, s0
	v_accvgpr_read_b32 v1, a61
	ds_write_b16 v83, v0 offset:21888
	v_cndmask_b32_e64 v0, v13, 0, s[60:61]
	v_cndmask_b32_e64 v1, v1, 0, s[62:63]
	v_add_f32_e32 v0, v0, v1
	v_accvgpr_read_b32 v14, a46
	v_cvt_pk_bf16_f32 v0, v0, s0
	v_accvgpr_read_b32 v1, a62
	ds_write_b16 v83, v0 offset:22032
	v_cndmask_b32_e64 v0, v14, 0, s[64:65]
	v_cndmask_b32_e64 v1, v1, 0, s[66:67]
	v_add_f32_e32 v0, v0, v1
	v_accvgpr_read_b32 v15, a47
	v_cvt_pk_bf16_f32 v0, v0, s0
	v_accvgpr_read_b32 v1, a63
	ds_write_b16 v83, v0 offset:22176
	v_cndmask_b32_e64 v0, v15, 0, s[68:69]
	v_cndmask_b32_e64 v1, v1, 0, s[70:71]
	v_add_f32_e32 v0, v0, v1
	v_cvt_pk_bf16_f32 v0, v0, s0
	ds_write_b16 v83, v0 offset:22320
	s_waitcnt lgkmcnt(0)
	s_barrier
	ds_read_b128 a[32:35], v82 offset:18432
	ds_read_b128 a[36:39], v70
	ds_read_b128 a[40:43], v70 offset:32
	ds_read_b128 a[44:47], v82 offset:18464
	s_waitcnt lgkmcnt(2)
	v_mfma_f32_32x32x16_bf16 a[16:31], a[32:35], a[36:39], a[16:31]
	ds_read_b128 a[32:35], v82 offset:23040
	s_waitcnt lgkmcnt(0)
	v_mfma_f32_32x32x16_bf16 a[0:15], a[32:35], a[36:39], a[0:15]
	ds_read_b128 a[32:35], v82 offset:23072
	ds_read_b128 a[36:39], v82 offset:18496
	s_waitcnt lgkmcnt(3)
	v_mfma_f32_32x32x16_bf16 a[16:31], a[44:47], a[40:43], a[16:31]
	ds_read_b128 a[44:47], v70 offset:64
	s_waitcnt lgkmcnt(2)
	v_mfma_f32_32x32x16_bf16 a[0:15], a[32:35], a[40:43], a[0:15]
	ds_read_b128 a[32:35], v70 offset:96
	ds_read_b128 a[40:43], v82 offset:18528
	s_waitcnt lgkmcnt(2)
	v_mfma_f32_32x32x16_bf16 a[16:31], a[36:39], a[44:47], a[16:31]
	ds_read_b128 a[36:39], v82 offset:23104
	s_waitcnt lgkmcnt(0)
	v_mfma_f32_32x32x16_bf16 a[0:15], a[36:39], a[44:47], a[0:15]
	ds_read_b128 a[36:39], v82 offset:23136
	v_accvgpr_read_b32 v0, a66
	s_waitcnt lgkmcnt(2)
	v_mfma_f32_32x32x16_bf16 a[16:31], a[40:43], a[32:35], a[16:31]
	v_add_u32_e32 v12, 0x8d00, v86
	s_waitcnt lgkmcnt(0)
	v_mfma_f32_32x32x16_bf16 a[0:15], a[36:39], a[32:35], a[0:15]
	s_nop 8
	ds_write_b32 v71, a16 offset:36096
	ds_write_b32 v71, a17 offset:36612
	ds_write_b32 v71, a18 offset:37128
	ds_write_b32 v71, a19 offset:37644
	ds_write_b32 v71, a20 offset:40224
	ds_write_b32 v71, a21 offset:40740
	ds_write_b32 v71, a22 offset:41256
	ds_write_b32 v71, a23 offset:41772
	ds_write_b32 v71, a24 offset:44352
	ds_write_b32 v71, a25 offset:44868
	ds_write_b32 v71, a26 offset:45384
	ds_write_b32 v71, a27 offset:45900
	ds_write_b32 v71, a28 offset:48480
	ds_write_b32 v71, a29 offset:48996
	ds_write_b32 v71, a30 offset:49512
	ds_write_b32 v71, a31 offset:50028
	ds_write_b32 v71, a0 offset:52608
	ds_write_b32 v71, a1 offset:53124
	ds_write_b32 v71, a2 offset:53640
	ds_write_b32 v71, a3 offset:54156
	ds_write_b32 v71, a4 offset:56736
	ds_write_b32 v71, a5 offset:57252
	ds_write_b32 v71, a6 offset:57768
	ds_write_b32 v71, a7 offset:58284
	ds_write_b32 v71, a8 offset:60864
	ds_write_b32 v71, a9 offset:61380
	ds_write_b32 v71, a10 offset:61896
	ds_write_b32 v71, a11 offset:62412
	ds_write_b32 v71, a12 offset:64992
	ds_write_b32 v71, a13 offset:65508
	ds_write_b32 v0, a14 offset:29928
	ds_write_b32 v0, a15 offset:30444
	v_accvgpr_read_b32 v0, a213
	v_add_u32_e32 v0, s74, v0
	v_ashrrev_i32_e32 v1, 31, v0
	v_lshlrev_b64 v[2:3], 10, v[0:1]
	v_lshl_add_u64 v[2:3], s[2:3], 0, v[2:3]
	v_lshl_add_u64 v[2:3], v[2:3], 0, s[88:89]
	v_lshl_add_u64 v[4:5], v[2:3], 0, v[114:115]
	s_waitcnt lgkmcnt(0)
	s_barrier
	global_load_dwordx4 v[58:61], v[4:5], off
	v_lshlrev_b64 v[0:1], 11, v[0:1]
	v_lshl_add_u64 v[0:1], s[90:91], 0, v[0:1]
	v_add_u32_e32 v2, 0x8d70, v86
	v_add_u32_e32 v3, 0x8d78, v86
	v_lshl_add_u64 v[0:1], v[0:1], 0, s[88:89]
	v_add_u32_e32 v8, 0x8d18, v86
	ds_read2_b32 v[24:25], v2 offset1:1
	ds_read2_b32 v[22:23], v3 offset1:1
	global_load_dwordx4 v[16:19], v[4:5], off offset:16
	v_lshl_add_u64 v[26:27], v[0:1], 0, v[114:115]
	global_load_dwordx4 v[0:3], v[4:5], off offset:48
	s_nop 0
	global_load_dwordx4 v[4:7], v[4:5], off offset:32
	ds_read2_b32 v[28:29], v8 offset1:1
	v_lshl_add_u64 v[20:21], v[26:27], 0, s[4:5]
	v_add_u32_e32 v10, 0x8d10, v86
	v_add_u32_e32 v11, 0x8d08, v86
	ds_read2_b32 v[34:35], v10 offset1:1
	ds_read2_b32 v[36:37], v11 offset1:1
	ds_read2_b32 v[38:39], v12 offset1:1
	s_waitcnt lgkmcnt(3)
	v_pk_mul_f32 v[44:45], v[28:29], v[28:29]
	v_pk_mul_f32 v[32:33], v[24:25], v[24:25]
	s_waitcnt lgkmcnt(2)
	v_pk_mul_f32 v[48:49], v[34:35], v[34:35]
	v_pk_mul_f32 v[30:31], v[22:23], v[22:23]
	s_waitcnt vmcnt(3)
	v_lshlrev_b32_e32 v46, 16, v60
	v_and_b32_e32 v42, 0xffff0000, v60
	v_mul_f32_e32 v8, 0xbfb8aa3b, v46
	v_mul_f32_e32 v9, 0xbfb8aa3b, v42
	v_exp_f32_e32 v8, v8
	v_exp_f32_e32 v9, v9
	v_lshlrev_b32_e32 v53, 16, v59
	v_and_b32_e32 v56, 0xffff0000, v59
	v_and_b32_e32 v60, 0xffff0000, v58
	v_pk_add_f32 v[40:41], v[8:9], 1.0 op_sel_hi:[1,0]
	global_load_dwordx4 v[8:11], v[76:77], off offset:528
	global_load_dwordx4 v[12:15], v[76:77], off offset:512
	v_div_scale_f32 v43, s[4:5], v41, v41, v42
	v_rcp_f32_e32 v47, v43
	s_waitcnt vmcnt(4)
	v_lshlrev_b32_e32 v100, 16, v19
	v_and_b32_e32 v101, 0xffff0000, v19
	v_fma_f32 v50, -v43, v47, 1.0
	v_fmac_f32_e32 v47, v50, v47
	v_div_scale_f32 v50, vcc, v42, v41, v42
	v_mul_f32_e32 v51, v50, v47
	v_fma_f32 v52, -v43, v51, v50
	v_fmac_f32_e32 v51, v52, v47
	v_fma_f32 v43, -v43, v51, v50
	v_div_scale_f32 v50, s[4:5], v40, v40, v46
	v_rcp_f32_e32 v52, v50
	v_div_fmas_f32 v43, v43, v47, v51
	v_div_fixup_f32 v41, v43, v41, v42
	v_mul_f32_e32 v43, 0xbfb8aa3b, v56
	v_fma_f32 v42, -v50, v52, 1.0
	v_fmac_f32_e32 v52, v42, v52
	v_mul_f32_e32 v42, 0xbfb8aa3b, v53
	v_exp_f32_e32 v42, v42
	v_exp_f32_e32 v43, v43
	v_div_scale_f32 v47, vcc, v46, v40, v46
	v_mul_f32_e32 v51, v47, v52
	v_fma_f32 v54, -v50, v51, v47
	v_fmac_f32_e32 v51, v54, v52
	v_pk_add_f32 v[42:43], v[42:43], 1.0 op_sel_hi:[1,0]
	v_fma_f32 v47, -v50, v51, v47
	v_div_scale_f32 v50, s[4:5], v43, v43, v56
	v_rcp_f32_e32 v57, v50
	v_div_fmas_f32 v47, v47, v52, v51
	v_div_fixup_f32 v40, v47, v40, v46
	s_waitcnt lgkmcnt(1)
	v_pk_mul_f32 v[54:55], v[36:37], v[36:37]
	v_fma_f32 v46, -v50, v57, 1.0
	v_fmac_f32_e32 v57, v46, v57
	v_div_scale_f32 v46, vcc, v56, v43, v56
	v_mul_f32_e32 v47, v46, v57
	v_fma_f32 v51, -v50, v47, v46
	v_fmac_f32_e32 v47, v51, v57
	v_fma_f32 v46, -v50, v47, v46
	v_div_scale_f32 v50, s[4:5], v42, v42, v53
	v_rcp_f32_e32 v51, v50
	v_div_fmas_f32 v46, v46, v57, v47
	v_div_fixup_f32 v43, v46, v43, v56
	v_lshlrev_b32_e32 v57, 16, v58
	v_fma_f32 v46, -v50, v51, 1.0
	v_fmac_f32_e32 v51, v46, v51
	v_mul_f32_e32 v46, 0xbfb8aa3b, v57
	v_mul_f32_e32 v47, 0xbfb8aa3b, v60
	v_exp_f32_e32 v46, v46
	v_exp_f32_e32 v47, v47
	v_div_scale_f32 v52, vcc, v53, v42, v53
	v_mul_f32_e32 v56, v52, v51
	v_fma_f32 v58, -v50, v56, v52
	v_fmac_f32_e32 v56, v58, v51
	v_pk_add_f32 v[46:47], v[46:47], 1.0 op_sel_hi:[1,0]
	v_fma_f32 v50, -v50, v56, v52
	v_div_scale_f32 v52, s[4:5], v47, v47, v60
	v_rcp_f32_e32 v62, v52
	v_div_fmas_f32 v50, v50, v51, v56
	v_div_fixup_f32 v42, v50, v42, v53
	s_waitcnt lgkmcnt(0)
	v_pk_mul_f32 v[58:59], v[38:39], v[38:39]
	v_fma_f32 v50, -v52, v62, 1.0
	v_fmac_f32_e32 v62, v50, v62
	v_div_scale_f32 v50, vcc, v60, v47, v60
	v_mul_f32_e32 v51, v50, v62
	v_fma_f32 v53, -v52, v51, v50
	v_fmac_f32_e32 v51, v53, v62
	v_fma_f32 v50, -v52, v51, v50
	v_div_scale_f32 v52, s[4:5], v46, v46, v57
	v_rcp_f32_e32 v56, v52
	v_div_fmas_f32 v50, v50, v62, v51
	v_lshlrev_b32_e32 v62, 16, v61
	v_and_b32_e32 v61, 0xffff0000, v61
	v_div_fixup_f32 v53, v50, v47, v60
	v_mul_f32_e32 v50, 0xbfb8aa3b, v62
	v_mul_f32_e32 v51, 0xbfb8aa3b, v61
	v_exp_f32_e32 v50, v50
	v_exp_f32_e32 v51, v51
	v_fma_f32 v47, -v52, v56, 1.0
	v_fmac_f32_e32 v56, v47, v56
	v_div_scale_f32 v47, vcc, v57, v46, v57
	v_mul_f32_e32 v60, v47, v56
	v_fma_f32 v63, -v52, v60, v47
	v_pk_add_f32 v[50:51], v[50:51], 1.0 op_sel_hi:[1,0]
	v_fmac_f32_e32 v60, v63, v56
	v_div_scale_f32 v63, s[4:5], v51, v51, v61
	v_rcp_f32_e32 v67, v63
	v_fma_f32 v47, -v52, v60, v47
	v_div_fmas_f32 v47, v47, v56, v60
	v_div_fixup_f32 v52, v47, v46, v57
	v_fma_f32 v46, -v63, v67, 1.0
	v_fmac_f32_e32 v67, v46, v67
	v_div_scale_f32 v46, vcc, v61, v51, v61
	v_mul_f32_e32 v47, v46, v67
	v_fma_f32 v56, -v63, v47, v46
	v_fmac_f32_e32 v47, v56, v67
	v_div_scale_f32 v56, s[4:5], v50, v50, v62
	v_rcp_f32_e32 v60, v56
	v_fma_f32 v46, -v63, v47, v46
	v_div_fmas_f32 v46, v46, v67, v47
	v_div_fixup_f32 v57, v46, v51, v61
	v_fma_f32 v46, -v56, v60, 1.0
	v_fmac_f32_e32 v60, v46, v60
	v_div_scale_f32 v46, vcc, v62, v50, v62
	v_mul_f32_e32 v47, v46, v60
	v_fma_f32 v51, -v56, v47, v46
	v_fmac_f32_e32 v47, v51, v60
	v_fma_f32 v46, -v56, v47, v46
	v_lshlrev_b32_e32 v67, 16, v18
	v_div_fmas_f32 v46, v46, v60, v47
	v_and_b32_e32 v18, 0xffff0000, v18
	v_mul_f32_e32 v47, 0xbfb8aa3b, v67
	v_exp_f32_e32 v60, v47
	v_mul_f32_e32 v47, 0xbfb8aa3b, v18
	v_exp_f32_e32 v61, v47
	v_div_fixup_f32 v56, v46, v50, v62
	v_add_u32_e32 v46, 0x8d38, v86
	v_add_u32_e32 v50, 0x8d30, v86
	v_pk_add_f32 v[74:75], v[60:61], 1.0 op_sel_hi:[1,0]
	v_add_u32_e32 v60, 0x8d28, v86
	v_div_scale_f32 v80, s[4:5], v75, v75, v18
	v_rcp_f32_e32 v81, v80
	v_add_u32_e32 v62, 0x8d20, v86
	v_add_f32_e32 v58, v58, v59
	ds_read2_b32 v[46:47], v46 offset1:1
	ds_read2_b32 v[50:51], v50 offset1:1
	v_fma_f32 v85, -v80, v81, 1.0
	v_fmac_f32_e32 v81, v85, v81
	v_div_scale_f32 v85, vcc, v18, v75, v18
	v_mul_f32_e32 v90, v85, v81
	v_fma_f32 v91, -v80, v90, v85
	v_fmac_f32_e32 v90, v91, v81
	v_fma_f32 v80, -v80, v90, v85
	v_div_scale_f32 v85, s[4:5], v74, v74, v67
	v_div_fmas_f32 v80, v80, v81, v90
	v_rcp_f32_e32 v92, v85
	v_div_fixup_f32 v141, v80, v75, v18
	v_lshlrev_b32_e32 v80, 16, v17
	v_and_b32_e32 v17, 0xffff0000, v17
	v_mul_f32_e32 v81, 0xbfb8aa3b, v80
	v_exp_f32_e32 v90, v81
	v_mul_f32_e32 v81, 0xbfb8aa3b, v17
	v_exp_f32_e32 v91, v81
	v_fma_f32 v18, -v85, v92, 1.0
	v_fmac_f32_e32 v92, v18, v92
	v_div_scale_f32 v18, vcc, v67, v74, v67
	v_mul_f32_e32 v75, v18, v92
	v_fma_f32 v81, -v85, v75, v18
	v_pk_add_f32 v[90:91], v[90:91], 1.0 op_sel_hi:[1,0]
	v_fmac_f32_e32 v75, v81, v92
	v_div_scale_f32 v81, s[4:5], v91, v91, v17
	v_fma_f32 v18, -v85, v75, v18
	v_rcp_f32_e32 v85, v81
	v_div_fmas_f32 v18, v18, v92, v75
	v_div_fixup_f32 v140, v18, v74, v67
	ds_read2_b32 v[60:61], v60 offset1:1
	ds_read2_b32 v[62:63], v62 offset1:1
	v_fma_f32 v18, -v81, v85, 1.0
	v_fmac_f32_e32 v85, v18, v85
	v_div_scale_f32 v18, vcc, v17, v91, v17
	v_mul_f32_e32 v67, v18, v85
	v_fma_f32 v74, -v81, v67, v18
	v_fmac_f32_e32 v67, v74, v85
	v_div_scale_f32 v74, s[4:5], v90, v90, v80
	v_rcp_f32_e32 v75, v74
	v_fma_f32 v18, -v81, v67, v18
	v_div_fmas_f32 v18, v18, v85, v67
	v_div_fixup_f32 v143, v18, v91, v17
	v_fma_f32 v17, -v74, v75, 1.0
	v_lshlrev_b32_e32 v81, 16, v16
	v_and_b32_e32 v85, 0xffff0000, v16
	v_fmac_f32_e32 v75, v17, v75
	v_mul_f32_e32 v16, 0xbfb8aa3b, v81
	v_mul_f32_e32 v17, 0xbfb8aa3b, v85
	v_exp_f32_e32 v16, v16
	v_exp_f32_e32 v17, v17
	v_div_scale_f32 v18, vcc, v80, v90, v80
	v_mul_f32_e32 v67, v18, v75
	v_pk_add_f32 v[144:145], v[16:17], 1.0 op_sel_hi:[1,0]
	v_fma_f32 v91, -v74, v67, v18
	v_div_scale_f32 v16, s[4:5], v145, v145, v85
	v_rcp_f32_e32 v17, v16
	v_fmac_f32_e32 v67, v91, v75
	v_fma_f32 v18, -v74, v67, v18
	v_div_fmas_f32 v18, v18, v75, v67
	v_div_fixup_f32 v142, v18, v90, v80
	v_fma_f32 v18, -v16, v17, 1.0
	v_fmac_f32_e32 v17, v18, v17
	v_div_scale_f32 v18, vcc, v85, v145, v85
	v_mul_f32_e32 v67, v18, v17
	v_fma_f32 v74, -v16, v67, v18
	v_fmac_f32_e32 v67, v74, v17
	v_fma_f32 v16, -v16, v67, v18
	v_div_scale_f32 v18, s[4:5], v144, v144, v81
	v_rcp_f32_e32 v80, v18
	v_div_fmas_f32 v16, v16, v17, v67
	v_add_f32_e32 v54, v58, v54
	v_div_fixup_f32 v145, v16, v145, v85
	v_fma_f32 v16, -v18, v80, 1.0
	v_add_f32_e32 v54, v54, v55
	v_fmac_f32_e32 v80, v16, v80
	v_mul_f32_e32 v16, 0xbfb8aa3b, v100
	v_mul_f32_e32 v17, 0xbfb8aa3b, v101
	v_add_f32_e32 v48, v54, v48
	v_div_scale_f32 v67, vcc, v81, v144, v81
	v_exp_f32_e32 v16, v16
	v_exp_f32_e32 v17, v17
	v_add_f32_e32 v48, v48, v49
	v_mul_f32_e32 v85, v67, v80
	v_add_f32_e32 v44, v48, v44
	s_waitcnt lgkmcnt(0)
	v_pk_mul_f32 v[136:137], v[62:63], v[62:63]
	v_fma_f32 v19, -v18, v85, v67
	v_add_f32_e32 v44, v44, v45
	v_fmac_f32_e32 v85, v19, v80
	v_add_f32_e32 v44, v44, v136
	v_pk_mul_f32 v[200:201], v[60:61], v[60:61]
	v_fma_f32 v67, -v18, v85, v67
	v_pk_add_f32 v[198:199], v[16:17], 1.0 op_sel_hi:[1,0]
	v_add_u32_e32 v16, 0x8d58, v86
	v_add_u32_e32 v18, 0x8d50, v86
	v_add_f32_e32 v44, v44, v137
	ds_read2_b32 v[16:17], v16 offset1:1
	v_add_u32_e32 v74, 0x8d48, v86
	v_add_u32_e32 v75, 0x8d40, v86
	ds_read2_b32 v[18:19], v18 offset1:1
	ds_read2_b32 v[146:147], v74 offset1:1
	ds_read2_b32 v[188:189], v75 offset1:1
	v_add_f32_e32 v44, v44, v200
	v_pk_mul_f32 v[194:195], v[50:51], v[50:51]
	v_add_f32_e32 v44, v44, v201
	v_add_f32_e32 v44, v44, v194
	v_pk_mul_f32 v[192:193], v[46:47], v[46:47]
	v_add_f32_e32 v44, v44, v195
	v_add_f32_e32 v44, v44, v192
	s_waitcnt lgkmcnt(0)
	v_pk_mul_f32 v[94:95], v[188:189], v[188:189]
	v_add_f32_e32 v44, v44, v193
	v_add_f32_e32 v44, v44, v94
	v_add_u32_e32 v90, 0x8d68, v86
	v_pk_mul_f32 v[92:93], v[146:147], v[146:147]
	v_add_f32_e32 v44, v44, v95
	v_add_u32_e32 v91, 0x8d60, v86
	ds_read2_b32 v[190:191], v90 offset1:1
	ds_read2_b32 v[196:197], v91 offset1:1
	v_add_f32_e32 v44, v44, v92
	v_pk_mul_f32 v[90:91], v[18:19], v[18:19]
	v_add_f32_e32 v44, v44, v93
	v_add_f32_e32 v44, v44, v90
	v_pk_mul_f32 v[74:75], v[16:17], v[16:17]
	v_add_f32_e32 v44, v44, v91
	v_add_f32_e32 v44, v44, v74
	s_waitcnt lgkmcnt(0)
	v_pk_mul_f32 v[98:99], v[196:197], v[196:197]
	v_add_f32_e32 v44, v44, v75
	v_add_f32_e32 v44, v44, v98
	v_pk_mul_f32 v[96:97], v[190:191], v[190:191]
	v_add_f32_e32 v44, v44, v99
	v_add_f32_e32 v44, v44, v96
	v_add_f32_e32 v44, v44, v97
	v_add_f32_e32 v32, v44, v32
	v_add_f32_e32 v32, v32, v33
	v_add_f32_e32 v30, v32, v30
	v_add_f32_e32 v30, v30, v31
	v_accvgpr_read_b32 v31, a149
	ds_bpermute_b32 v31, v31, v30
	v_div_scale_f32 v102, s[4:5], v199, v199, v101
	v_rcp_f32_e32 v103, v102
	s_mov_b32 s4, 0x800000
	s_waitcnt lgkmcnt(0)
	v_add_f32_e32 v30, v30, v31
	v_accvgpr_read_b32 v31, a150
	ds_bpermute_b32 v31, v31, v30
	v_div_fmas_f32 v32, v67, v80, v85
	v_div_fixup_f32 v144, v32, v144, v81
	v_fma_f32 v32, -v102, v103, 1.0
	v_fmac_f32_e32 v103, v32, v103
	s_waitcnt lgkmcnt(0)
	v_add_f32_e32 v30, v30, v31
	v_mov_b32_e32 v31, 0x358637bd
	v_fmamk_f32 v30, v30, 0x3c000000, v31
	v_mul_f32_e32 v31, 0x4b800000, v30
	v_cmp_gt_f32_e64 s[74:75], s4, v30
	v_div_scale_f32 v32, vcc, v101, v199, v101
	s_nop 0
	v_cndmask_b32_e64 v30, v30, v31, s[74:75]
	v_rsq_f32_e32 v30, v30
	v_mul_f32_e32 v44, v32, v103
	v_fma_f32 v31, -v102, v44, v32
	v_fmac_f32_e32 v44, v31, v103
	v_fma_f32 v31, -v102, v44, v32
	v_mul_f32_e32 v32, 0x45800000, v30
	v_cndmask_b32_e64 v30, v30, v32, s[74:75]
	v_pk_mul_f32 v[32:33], v[38:39], v[30:31] op_sel_hi:[1,0]
	s_mov_b32 s4, 0x186fa000
	s_waitcnt vmcnt(0)
	v_pk_mul_f32 v[12:13], v[12:13], v[32:33]
	v_pk_mul_f32 v[32:33], v[36:37], v[30:31] op_sel_hi:[1,0]
	v_pk_mul_f32 v[12:13], v[52:53], v[12:13]
	v_pk_mul_f32 v[14:15], v[14:15], v[32:33]
	v_cvt_pk_bf16_f32 v12, v12, v13
	v_pk_mul_f32 v[14:15], v[42:43], v[14:15]
	v_lshlrev_b32_e32 v38, 16, v5
	v_cvt_pk_bf16_f32 v13, v14, v15
	v_pk_mul_f32 v[14:15], v[34:35], v[30:31] op_sel_hi:[1,0]
	v_lshlrev_b32_e32 v34, 16, v6
	v_pk_mul_f32 v[8:9], v[8:9], v[14:15]
	v_and_b32_e32 v6, 0xffff0000, v6
	v_pk_mul_f32 v[8:9], v[40:41], v[8:9]
	v_and_b32_e32 v5, 0xffff0000, v5
	v_cvt_pk_bf16_f32 v14, v8, v9
	v_pk_mul_f32 v[8:9], v[28:29], v[30:31] op_sel_hi:[1,0]
	v_mul_f32_e32 v29, 0xbfb8aa3b, v6
	v_pk_mul_f32 v[8:9], v[10:11], v[8:9]
	v_exp_f32_e32 v29, v29
	v_pk_mul_f32 v[8:9], v[56:57], v[8:9]
	s_nop 0
	v_cvt_pk_bf16_f32 v15, v8, v9
	v_add_co_u32_e64 v8, s[74:75], s4, v26
	v_div_scale_f32 v26, s[4:5], v198, v198, v100
	s_nop 0
	v_addc_co_u32_e64 v9, s[74:75], 0, v27, s[74:75]
	global_store_dwordx4 v[8:9], v[12:15], off offset:1280
	global_load_dwordx4 v[8:11], v[76:77], off offset:560
	s_nop 0
	global_load_dwordx4 v[12:15], v[76:77], off offset:544
	v_rcp_f32_e32 v32, v26
	v_div_fmas_f32 v27, v31, v103, v44
	v_div_scale_f32 v31, vcc, v100, v198, v100
	v_fma_f32 v28, -v26, v32, 1.0
	v_fmac_f32_e32 v32, v28, v32
	v_mul_f32_e32 v28, 0xbfb8aa3b, v34
	v_exp_f32_e32 v28, v28
	v_mul_f32_e32 v33, v31, v32
	v_fma_f32 v35, -v26, v33, v31
	v_fmac_f32_e32 v33, v35, v32
	v_pk_add_f32 v[28:29], v[28:29], 1.0 op_sel_hi:[1,0]
	v_fma_f32 v26, -v26, v33, v31
	v_div_scale_f32 v31, s[4:5], v29, v29, v6
	v_rcp_f32_e32 v35, v31
	v_div_fmas_f32 v26, v26, v32, v33
	v_div_fixup_f32 v27, v27, v199, v101
	v_div_fixup_f32 v26, v26, v198, v100
	v_fma_f32 v32, -v31, v35, 1.0
	v_fmac_f32_e32 v35, v32, v35
	v_div_scale_f32 v32, vcc, v6, v29, v6
	v_mul_f32_e32 v33, v32, v35
	v_fma_f32 v36, -v31, v33, v32
	v_fmac_f32_e32 v33, v36, v35
	v_div_scale_f32 v36, s[4:5], v28, v28, v34
	v_rcp_f32_e32 v37, v36
	v_fma_f32 v31, -v31, v33, v32
	v_div_fmas_f32 v31, v31, v35, v33
	v_mul_f32_e32 v32, 0xbfb8aa3b, v38
	v_mul_f32_e32 v33, 0xbfb8aa3b, v5
	v_exp_f32_e32 v32, v32
	v_exp_f32_e32 v33, v33
	v_div_fixup_f32 v29, v31, v29, v6
	v_fma_f32 v6, -v36, v37, 1.0
	v_fmac_f32_e32 v37, v6, v37
	v_div_scale_f32 v6, vcc, v34, v28, v34
	v_mul_f32_e32 v31, v6, v37
	v_fma_f32 v35, -v36, v31, v6
	v_pk_add_f32 v[32:33], v[32:33], 1.0 op_sel_hi:[1,0]
	v_fmac_f32_e32 v31, v35, v37
	v_div_scale_f32 v35, s[4:5], v33, v33, v5
	v_fma_f32 v6, -v36, v31, v6
	v_rcp_f32_e32 v36, v35
	v_div_fmas_f32 v6, v6, v37, v31
	v_div_fixup_f32 v28, v6, v28, v34
	v_div_scale_f32 v37, s[4:5], v32, v32, v38
	v_fma_f32 v6, -v35, v36, 1.0
	v_fmac_f32_e32 v36, v6, v36
	v_div_scale_f32 v6, vcc, v5, v33, v5
	v_mul_f32_e32 v31, v6, v36
	v_fma_f32 v34, -v35, v31, v6
	v_fmac_f32_e32 v31, v34, v36
	v_fma_f32 v6, -v35, v31, v6
	v_pk_mul_f32 v[34:35], v[62:63], v[30:31] op_sel_hi:[1,0]
	v_rcp_f32_e32 v39, v37
	v_div_fmas_f32 v6, v6, v36, v31
	v_div_fixup_f32 v33, v6, v33, v5
	v_div_scale_f32 v6, vcc, v38, v32, v38
	v_fma_f32 v5, -v37, v39, 1.0
	v_fmac_f32_e32 v39, v5, v39
	s_waitcnt vmcnt(0)
	v_pk_mul_f32 v[12:13], v[34:35], v[12:13]
	v_pk_mul_f32 v[34:35], v[60:61], v[30:31] op_sel_hi:[1,0]
	v_pk_mul_f32 v[12:13], v[12:13], v[144:145]
	v_pk_mul_f32 v[14:15], v[34:35], v[14:15]
	v_cvt_pk_bf16_f32 v12, v12, v13
	v_pk_mul_f32 v[14:15], v[14:15], v[142:143]
	s_nop 0
	v_cvt_pk_bf16_f32 v13, v14, v15
	v_pk_mul_f32 v[14:15], v[50:51], v[30:31] op_sel_hi:[1,0]
	s_nop 0
	v_pk_mul_f32 v[8:9], v[14:15], v[8:9]
	s_nop 0
	v_pk_mul_f32 v[8:9], v[8:9], v[140:141]
	s_nop 0
	v_cvt_pk_bf16_f32 v14, v8, v9
	v_pk_mul_f32 v[8:9], v[46:47], v[30:31] op_sel_hi:[1,0]
	v_and_b32_e32 v31, 0xffff0000, v4
	v_pk_mul_f32 v[8:9], v[8:9], v[10:11]
	v_mul_f32_e32 v5, 0xbfb8aa3b, v31
	v_pk_mul_f32 v[8:9], v[26:27], v[8:9]
	v_lshlrev_b32_e32 v27, 16, v4
	v_cvt_pk_bf16_f32 v15, v8, v9
	global_store_dwordx4 v[20:21], v[12:15], off offset:16
	global_load_dwordx4 v[8:11], v[76:77], off offset:592
	s_nop 0
	global_load_dwordx4 v[12:15], v[76:77], off offset:576
	v_mul_f32_e32 v4, 0xbfb8aa3b, v27
	v_exp_f32_e32 v4, v4
	v_exp_f32_e32 v5, v5
	v_mul_f32_e32 v26, v6, v39
	v_fma_f32 v34, -v37, v26, v6
	v_fmac_f32_e32 v26, v34, v39
	v_pk_add_f32 v[4:5], v[4:5], 1.0 op_sel_hi:[1,0]
	v_fma_f32 v6, -v37, v26, v6
	v_div_scale_f32 v34, s[4:5], v5, v5, v31
	v_rcp_f32_e32 v35, v34
	v_div_fmas_f32 v6, v6, v39, v26
	v_div_fixup_f32 v32, v6, v32, v38
	v_and_b32_e32 v37, 0xffff0000, v7
	v_fma_f32 v6, -v34, v35, 1.0
	v_fmac_f32_e32 v35, v6, v35
	v_div_scale_f32 v6, vcc, v31, v5, v31
	v_mul_f32_e32 v26, v6, v35
	v_fma_f32 v36, -v34, v26, v6
	v_fmac_f32_e32 v26, v36, v35
	v_fma_f32 v6, -v34, v26, v6
	v_div_scale_f32 v34, s[4:5], v4, v4, v27
	v_rcp_f32_e32 v36, v34
	v_div_fmas_f32 v6, v6, v35, v26
	v_div_fixup_f32 v5, v6, v5, v31
	v_lshlrev_b32_e32 v35, 16, v7
	v_fma_f32 v6, -v34, v36, 1.0
	v_fmac_f32_e32 v36, v6, v36
	v_mul_f32_e32 v6, 0xbfb8aa3b, v35
	v_mul_f32_e32 v7, 0xbfb8aa3b, v37
	v_exp_f32_e32 v6, v6
	v_exp_f32_e32 v7, v7
	v_div_scale_f32 v26, vcc, v27, v4, v27
	v_mul_f32_e32 v31, v26, v36
	v_fma_f32 v38, -v34, v31, v26
	v_fmac_f32_e32 v31, v38, v36
	v_pk_add_f32 v[6:7], v[6:7], 1.0 op_sel_hi:[1,0]
	v_fma_f32 v26, -v34, v31, v26
	v_div_scale_f32 v34, s[4:5], v7, v7, v37
	v_rcp_f32_e32 v38, v34
	v_div_fmas_f32 v26, v26, v36, v31
	v_div_fixup_f32 v4, v26, v4, v27
	v_fma_f32 v26, -v34, v38, 1.0
	v_fmac_f32_e32 v38, v26, v38
	v_div_scale_f32 v26, vcc, v37, v7, v37
	v_mul_f32_e32 v27, v26, v38
	v_fma_f32 v31, -v34, v27, v26
	v_fmac_f32_e32 v27, v31, v38
	v_div_scale_f32 v31, s[4:5], v6, v6, v35
	v_fma_f32 v26, -v34, v27, v26
	v_rcp_f32_e32 v34, v31
	v_div_fmas_f32 v26, v26, v38, v27
	v_div_fixup_f32 v27, v26, v7, v37
	v_fma_f32 v7, -v31, v34, 1.0
	v_fmac_f32_e32 v34, v7, v34
	v_div_scale_f32 v7, vcc, v35, v6, v35
	v_mul_f32_e32 v26, v7, v34
	v_fma_f32 v36, -v31, v26, v7
	v_fmac_f32_e32 v26, v36, v34
	v_fma_f32 v7, -v31, v26, v7
	v_div_fmas_f32 v7, v7, v34, v26
	v_div_fixup_f32 v26, v7, v6, v35
	v_pk_mul_f32 v[6:7], v[188:189], v[30:31] op_sel_hi:[1,0]
	s_waitcnt vmcnt(0)
	v_pk_mul_f32 v[6:7], v[6:7], v[12:13]
	s_nop 0
	v_pk_mul_f32 v[4:5], v[6:7], v[4:5]
	v_pk_mul_f32 v[6:7], v[146:147], v[30:31] op_sel_hi:[1,0]
	v_cvt_pk_bf16_f32 v4, v4, v5
	v_pk_mul_f32 v[6:7], v[6:7], v[14:15]
	v_lshlrev_b32_e32 v14, 16, v0
	v_pk_mul_f32 v[6:7], v[6:7], v[32:33]
	v_and_b32_e32 v0, 0xffff0000, v0
	v_cvt_pk_bf16_f32 v5, v6, v7
	v_pk_mul_f32 v[6:7], v[18:19], v[30:31] op_sel_hi:[1,0]
	s_nop 0
	v_pk_mul_f32 v[6:7], v[6:7], v[8:9]
	v_pk_mul_f32 v[8:9], v[16:17], v[30:31] op_sel_hi:[1,0]
	v_pk_mul_f32 v[6:7], v[6:7], v[28:29]
	v_pk_mul_f32 v[8:9], v[8:9], v[10:11]
	v_cvt_pk_bf16_f32 v6, v6, v7
	v_pk_mul_f32 v[8:9], v[26:27], v[8:9]
	s_nop 0
	v_cvt_pk_bf16_f32 v7, v8, v9
	global_store_dwordx4 v[20:21], v[4:7], off offset:32
	global_load_dwordx4 v[4:7], v[76:77], off offset:608
	v_mul_f32_e32 v8, 0xbfb8aa3b, v14
	v_mul_f32_e32 v9, 0xbfb8aa3b, v0
	v_exp_f32_e32 v8, v8
	v_exp_f32_e32 v9, v9
	s_nop 0
	v_pk_add_f32 v[12:13], v[8:9], 1.0 op_sel_hi:[1,0]
	global_load_dwordx4 v[8:11], v[76:77], off offset:624
	v_div_scale_f32 v15, s[4:5], v13, v13, v0
	v_rcp_f32_e32 v16, v15
	s_nop 0
	v_fma_f32 v17, -v15, v16, 1.0
	v_fmac_f32_e32 v16, v17, v16
	v_div_scale_f32 v17, vcc, v0, v13, v0
	v_mul_f32_e32 v18, v17, v16
	v_fma_f32 v19, -v15, v18, v17
	v_fmac_f32_e32 v18, v19, v16
	v_fma_f32 v15, -v15, v18, v17
	v_div_scale_f32 v17, s[4:5], v12, v12, v14
	v_rcp_f32_e32 v19, v17
	v_div_fmas_f32 v15, v15, v16, v18
	v_div_fixup_f32 v13, v15, v13, v0
	v_fma_f32 v0, -v17, v19, 1.0
	v_fmac_f32_e32 v19, v0, v19
	v_div_scale_f32 v0, vcc, v14, v12, v14
	v_mul_f32_e32 v15, v0, v19
	v_fma_f32 v16, -v17, v15, v0
	v_fmac_f32_e32 v15, v16, v19
	v_fma_f32 v0, -v17, v15, v0
	v_div_fmas_f32 v0, v0, v19, v15
	v_lshlrev_b32_e32 v16, 16, v1
	v_and_b32_e32 v17, 0xffff0000, v1
	v_div_fixup_f32 v12, v0, v12, v14
	v_mul_f32_e32 v0, 0xbfb8aa3b, v16
	v_mul_f32_e32 v1, 0xbfb8aa3b, v17
	v_exp_f32_e32 v0, v0
	v_exp_f32_e32 v1, v1
	v_pk_mul_f32 v[14:15], v[196:197], v[30:31] op_sel_hi:[1,0]
	s_waitcnt vmcnt(1)
	v_pk_mul_f32 v[4:5], v[14:15], v[4:5]
	s_nop 0
	v_pk_mul_f32 v[4:5], v[4:5], v[12:13]
	v_pk_add_f32 v[12:13], v[0:1], 1.0 op_sel_hi:[1,0]
	v_cvt_pk_bf16_f32 v0, v4, v5
	v_div_scale_f32 v1, s[4:5], v13, v13, v17
	v_rcp_f32_e32 v14, v1
	v_pk_mul_f32 v[4:5], v[190:191], v[30:31] op_sel_hi:[1,0]
	s_nop 0
	v_pk_mul_f32 v[4:5], v[4:5], v[6:7]
	v_fma_f32 v6, -v1, v14, 1.0
	v_fmac_f32_e32 v14, v6, v14
	v_div_scale_f32 v6, vcc, v17, v13, v17
	v_mul_f32_e32 v7, v6, v14
	v_fma_f32 v15, -v1, v7, v6
	v_fmac_f32_e32 v7, v15, v14
	v_fma_f32 v1, -v1, v7, v6
	v_div_scale_f32 v6, s[4:5], v12, v12, v16
	v_rcp_f32_e32 v18, v6
	v_div_fmas_f32 v1, v1, v14, v7
	v_div_fixup_f32 v7, v1, v13, v17
	v_lshlrev_b32_e32 v17, 16, v2
	v_fma_f32 v1, -v6, v18, 1.0
	v_fmac_f32_e32 v18, v1, v18
	v_div_scale_f32 v1, vcc, v16, v12, v16
	v_mul_f32_e32 v13, v1, v18
	v_fma_f32 v14, -v6, v13, v1
	v_fmac_f32_e32 v13, v14, v18
	v_fma_f32 v1, -v6, v13, v1
	v_and_b32_e32 v2, 0xffff0000, v2
	v_mul_f32_e32 v6, 0xbfb8aa3b, v17
	v_exp_f32_e32 v14, v6
	v_mul_f32_e32 v6, 0xbfb8aa3b, v2
	v_exp_f32_e32 v15, v6
	v_div_fmas_f32 v1, v1, v18, v13
	v_div_fixup_f32 v6, v1, v12, v16
	v_pk_mul_f32 v[4:5], v[4:5], v[6:7]
	v_pk_add_f32 v[6:7], v[14:15], 1.0 op_sel_hi:[1,0]
	v_cvt_pk_bf16_f32 v1, v4, v5
	v_div_scale_f32 v12, s[4:5], v7, v7, v2
	v_rcp_f32_e32 v13, v12
	v_pk_mul_f32 v[4:5], v[24:25], v[30:31] op_sel_hi:[1,0]
	s_waitcnt vmcnt(0)
	v_pk_mul_f32 v[4:5], v[4:5], v[8:9]
	v_fma_f32 v8, -v12, v13, 1.0
	v_fmac_f32_e32 v13, v8, v13
	v_div_scale_f32 v8, vcc, v2, v7, v2
	v_mul_f32_e32 v9, v8, v13
	v_fma_f32 v14, -v12, v9, v8
	v_fmac_f32_e32 v9, v14, v13
	v_fma_f32 v8, -v12, v9, v8
	v_div_scale_f32 v12, s[4:5], v6, v6, v17
	v_rcp_f32_e32 v14, v12
	v_div_fmas_f32 v8, v8, v13, v9
	v_div_fixup_f32 v7, v8, v7, v2
	v_and_b32_e32 v13, 0xffff0000, v3
	v_fma_f32 v2, -v12, v14, 1.0
	v_fmac_f32_e32 v14, v2, v14
	v_div_scale_f32 v2, vcc, v17, v6, v17
	v_mul_f32_e32 v8, v2, v14
	v_fma_f32 v9, -v12, v8, v2
	v_fmac_f32_e32 v8, v9, v14
	v_fma_f32 v9, -v12, v8, v2
	v_lshlrev_b32_e32 v12, 16, v3
	v_mul_f32_e32 v2, 0xbfb8aa3b, v12
	v_mul_f32_e32 v3, 0xbfb8aa3b, v13
	v_exp_f32_e32 v2, v2
	v_exp_f32_e32 v3, v3
	v_div_fmas_f32 v8, v9, v14, v8
	v_div_fixup_f32 v6, v8, v6, v17
	v_pk_mul_f32 v[4:5], v[4:5], v[6:7]
	v_pk_add_f32 v[6:7], v[2:3], 1.0 op_sel_hi:[1,0]
	v_cvt_pk_bf16_f32 v2, v4, v5
	v_div_scale_f32 v3, s[4:5], v7, v7, v13
	v_rcp_f32_e32 v8, v3
	v_pk_mul_f32 v[4:5], v[22:23], v[30:31] op_sel_hi:[1,0]
	v_fma_f32 v9, -v3, v8, 1.0
	v_fmac_f32_e32 v8, v9, v8
	v_div_scale_f32 v9, vcc, v13, v7, v13
	v_pk_mul_f32 v[4:5], v[4:5], v[10:11]
	v_mul_f32_e32 v10, v9, v8
	v_fma_f32 v11, -v3, v10, v9
	v_fmac_f32_e32 v10, v11, v8
	v_fma_f32 v3, -v3, v10, v9
	v_div_scale_f32 v9, s[4:5], v6, v6, v12
	v_rcp_f32_e32 v11, v9
	v_div_fmas_f32 v3, v3, v8, v10
	v_div_fixup_f32 v7, v3, v7, v13
	v_fma_f32 v3, -v9, v11, 1.0
	v_fmac_f32_e32 v11, v3, v11
	v_div_scale_f32 v3, vcc, v12, v6, v12
	v_mul_f32_e32 v8, v3, v11
	v_fma_f32 v10, -v9, v8, v3
	v_fmac_f32_e32 v8, v10, v11
	v_fma_f32 v3, -v9, v8, v3
	v_div_fmas_f32 v3, v3, v11, v8
	v_div_fixup_f32 v6, v3, v6, v12
	v_pk_mul_f32 v[4:5], v[6:7], v[4:5]
	s_nop 0
	v_cvt_pk_bf16_f32 v3, v4, v5
	global_store_dwordx4 v[20:21], v[0:3], off offset:48
	s_barrier
	s_cbranch_scc1 .LBB0_1790

.LBB0_2270:
	s_lshl_b64 s[58:59], s[4:5], 10
	s_lshl_b64 s[64:65], s[4:5], 11
	v_mov_b32_e32 v243, v149
	s_lshl_b32 s4, s68, 7
	v_lshl_add_u64 v[0:1], s[62:63], 0, v[242:243]
	v_mov_b32_e32 v245, v149
	v_mov_b32_e32 v247, v149
	s_add_u32 s70, s62, s4
	v_lshl_add_u64 v[0:1], v[0:1], 0, v[244:245]
	v_lshl_add_u64 v[2:3], s[62:63], 0, v[246:247]
	s_addc_u32 s71, s63, 0
	v_lshl_add_u64 v[2:3], v[2:3], 0, v[244:245]
	global_load_dwordx4 v[32:35], v[0:1], off
	global_load_dwordx4 v[36:39], v[2:3], off
	v_lshl_add_u64 v[0:1], s[70:71], 0, v[242:243]
	v_lshl_add_u64 v[0:1], v[0:1], 0, v[244:245]
	v_lshl_add_u64 v[2:3], s[70:71], 0, v[246:247]
	v_lshl_add_u64 v[2:3], v[2:3], 0, v[244:245]
	global_load_dwordx4 v[40:43], v[0:1], off
	global_load_dwordx4 v[44:47], v[2:3], off
	v_accvgpr_read_b32 v0, a209
	v_mul_u32_u24_e32 v0, s68, v0
	v_lshlrev_b32_e32 v64, 1, v0
	v_mov_b32_e32 v65, v149
	v_mul_u32_u24_e32 v2, s68, v152
	v_lshl_add_u64 v[0:1], s[60:61], 0, v[64:65]
	v_lshlrev_b32_e32 v66, 1, v2
	v_mov_b32_e32 v67, v149
	v_lshl_add_u64 v[0:1], v[0:1], 0, v[244:245]
	v_lshl_add_u64 v[2:3], s[60:61], 0, v[66:67]
	v_lshl_add_u64 v[2:3], v[2:3], 0, v[244:245]
	global_load_dwordx4 v[48:51], v[0:1], off
	global_load_dwordx4 v[52:55], v[2:3], off
	v_mul_u32_u24_e32 v0, s68, v153
	v_lshlrev_b32_e32 v68, 1, v0
	v_mov_b32_e32 v69, v149
	v_mul_u32_u24_e32 v2, s68, v160
	v_lshl_add_u64 v[0:1], s[60:61], 0, v[68:69]
	v_lshlrev_b32_e32 v70, 1, v2
	v_mov_b32_e32 v71, v149
	v_lshl_add_u64 v[0:1], v[0:1], 0, v[244:245]
	v_lshl_add_u64 v[2:3], s[60:61], 0, v[70:71]
	v_lshl_add_u64 v[2:3], v[2:3], 0, v[244:245]
	global_load_dwordx4 v[56:59], v[0:1], off
	global_load_dwordx4 v[60:63], v[2:3], off
	v_mov_b32_e32 v251, v149
	v_lshl_add_u64 v[0:1], v[164:165], 0, s[64:65]
	v_lshl_add_u64 v[2:3], v[0:1], 0, v[148:149]
	v_lshl_add_u64 v[0:1], v[0:1], 0, v[250:251]
	global_load_dwordx4 v[28:31], v[2:3], off
	global_load_dwordx4 v[24:27], v[2:3], off offset:32
	global_load_dwordx4 v[20:23], v[2:3], off offset:64
	global_load_dwordx4 v[16:19], v[2:3], off offset:96
	global_load_dwordx4 v[12:15], v[0:1], off
	global_load_dwordx4 v[8:11], v[0:1], off offset:32
	global_load_dwordx4 v[4:7], v[0:1], off offset:64
	s_nop 0
	global_load_dwordx4 v[0:3], v[0:1], off offset:96
	v_lshl_add_u64 v[82:83], s[62:63], 0, v[146:147]
	v_lshl_add_u64 v[84:85], s[62:63], 0, v[166:167]
	v_lshl_add_u64 v[86:87], v[82:83], 0, s[4:5]
	v_lshl_add_u64 v[88:89], v[84:85], 0, s[4:5]
	s_add_i32 s4, s67, 1
	s_add_u32 s60, s60, 0x80
	v_mov_b32_e32 v80, 0
	s_addc_u32 s61, s61, 0
	v_accvgpr_write_b32 a31, 0
	v_accvgpr_write_b32 a30, 0
	v_accvgpr_write_b32 a29, 0
	v_accvgpr_write_b32 a28, 0
	v_accvgpr_write_b32 a27, 0
	v_accvgpr_write_b32 a26, 0
	v_accvgpr_write_b32 a25, 0
	v_accvgpr_write_b32 a24, 0
	v_accvgpr_write_b32 a23, 0
	v_accvgpr_write_b32 a22, 0
	v_lshl_add_u64 v[90:91], s[60:61], 0, v[64:65]
	v_lshl_add_u64 v[92:93], s[60:61], 0, v[66:67]
	v_lshl_add_u64 v[94:95], s[60:61], 0, v[68:69]
	v_lshl_add_u64 v[96:97], s[60:61], 0, v[70:71]
	v_accvgpr_write_b32 a21, 0
	v_accvgpr_write_b32 a20, 0
	v_accvgpr_write_b32 a19, 0
	v_accvgpr_write_b32 a18, 0
	v_accvgpr_write_b32 a17, 0
	v_accvgpr_write_b32 a16, 0
	v_accvgpr_write_b32 a111, 0
	v_accvgpr_write_b32 a110, 0
	v_accvgpr_write_b32 a109, 0
	v_accvgpr_write_b32 a108, 0
	v_accvgpr_write_b32 a107, 0
	v_accvgpr_write_b32 a106, 0
	v_accvgpr_write_b32 a105, 0
	v_accvgpr_write_b32 a104, 0
	v_accvgpr_write_b32 a103, 0
	v_accvgpr_write_b32 a102, 0
	v_accvgpr_write_b32 a101, 0
	v_accvgpr_write_b32 a100, 0
	v_accvgpr_write_b32 a99, 0
	v_accvgpr_write_b32 a98, 0
	v_accvgpr_write_b32 a97, 0
	v_accvgpr_write_b32 a96, 0
	v_accvgpr_write_b32 a143, 0
	v_accvgpr_write_b32 a142, 0
	v_accvgpr_write_b32 a141, 0
	v_accvgpr_write_b32 a140, 0
	v_accvgpr_write_b32 a139, 0
	v_accvgpr_write_b32 a138, 0
	v_accvgpr_write_b32 a137, 0
	v_accvgpr_write_b32 a136, 0
	v_accvgpr_write_b32 a135, 0
	v_accvgpr_write_b32 a134, 0
	v_accvgpr_write_b32 a133, 0
	v_accvgpr_write_b32 a132, 0
	v_accvgpr_write_b32 a131, 0
	v_accvgpr_write_b32 a130, 0
	v_accvgpr_write_b32 a129, 0
	v_accvgpr_write_b32 a128, 0
	v_accvgpr_write_b32 a63, 0
	v_accvgpr_write_b32 a62, 0
	v_accvgpr_write_b32 a61, 0
	v_accvgpr_write_b32 a60, 0
	v_accvgpr_write_b32 a59, 0
	v_accvgpr_write_b32 a58, 0
	v_accvgpr_write_b32 a57, 0
	v_accvgpr_write_b32 a56, 0
	v_accvgpr_write_b32 a55, 0
	v_accvgpr_write_b32 a54, 0
	v_accvgpr_write_b32 a53, 0
	v_accvgpr_write_b32 a52, 0
	v_accvgpr_write_b32 a51, 0
	v_accvgpr_write_b32 a50, 0
	v_accvgpr_write_b32 a49, 0
	v_accvgpr_write_b32 a48, 0
	v_accvgpr_write_b32 a95, 0
	v_accvgpr_write_b32 a94, 0
	v_accvgpr_write_b32 a93, 0
	v_accvgpr_write_b32 a92, 0
	v_accvgpr_write_b32 a91, 0
	v_accvgpr_write_b32 a90, 0
	v_accvgpr_write_b32 a89, 0
	v_accvgpr_write_b32 a88, 0
	v_accvgpr_write_b32 a87, 0
	v_accvgpr_write_b32 a86, 0
	v_accvgpr_write_b32 a85, 0
	v_accvgpr_write_b32 a84, 0
	v_accvgpr_write_b32 a83, 0
	v_accvgpr_write_b32 a82, 0
	v_accvgpr_write_b32 a81, 0
	v_accvgpr_write_b32 a80, 0
	v_accvgpr_write_b32 a47, 0
	v_accvgpr_write_b32 a46, 0
	v_accvgpr_write_b32 a45, 0
	v_accvgpr_write_b32 a44, 0
	v_accvgpr_write_b32 a43, 0
	v_accvgpr_write_b32 a42, 0
	v_accvgpr_write_b32 a41, 0
	v_accvgpr_write_b32 a40, 0
	v_accvgpr_write_b32 a39, 0
	v_accvgpr_write_b32 a38, 0
	v_accvgpr_write_b32 a37, 0
	v_accvgpr_write_b32 a36, 0
	v_accvgpr_write_b32 a35, 0
	v_accvgpr_write_b32 a34, 0
	v_accvgpr_write_b32 a33, 0
	v_accvgpr_write_b32 a32, 0
	v_accvgpr_write_b32 a127, 0
	v_accvgpr_write_b32 a126, 0
	v_accvgpr_write_b32 a125, 0
	v_accvgpr_write_b32 a124, 0
	v_accvgpr_write_b32 a123, 0
	v_accvgpr_write_b32 a122, 0
	v_accvgpr_write_b32 a121, 0
	v_accvgpr_write_b32 a120, 0
	v_accvgpr_write_b32 a119, 0
	v_accvgpr_write_b32 a118, 0
	v_accvgpr_write_b32 a117, 0
	v_accvgpr_write_b32 a116, 0
	v_accvgpr_write_b32 a115, 0
	v_accvgpr_write_b32 a114, 0
	v_accvgpr_write_b32 a113, 0
	v_accvgpr_write_b32 a112, 0
	v_accvgpr_write_b32 a79, 0
	v_accvgpr_write_b32 a78, 0
	v_accvgpr_write_b32 a77, 0
	v_accvgpr_write_b32 a76, 0
	v_accvgpr_write_b32 a75, 0
	v_accvgpr_write_b32 a74, 0
	v_accvgpr_write_b32 a73, 0
	v_accvgpr_write_b32 a72, 0
	v_accvgpr_write_b32 a71, 0
	v_accvgpr_write_b32 a70, 0
	v_accvgpr_write_b32 a69, 0
	v_accvgpr_write_b32 a68, 0
	v_accvgpr_write_b32 a67, 0
	v_accvgpr_write_b32 a66, 0
	v_accvgpr_write_b32 a65, 0
	v_accvgpr_write_b32 a64, 0
	s_mov_b32 s60, 0
	v_mov_b32_e32 v81, v80
	s_waitcnt vmcnt(15)
	ds_write_b128 v129, v[32:35]
	s_waitcnt vmcnt(14)
	ds_write_b128 v135, v[36:39]
	s_waitcnt vmcnt(13)
	ds_write_b128 v129, v[40:43] offset:9216
	s_waitcnt vmcnt(12)
	ds_write_b128 v135, v[44:47] offset:9216
	s_waitcnt vmcnt(11)
	ds_write_b128 v129, v[48:51] offset:36864
	s_waitcnt vmcnt(10)
	ds_write_b128 v135, v[52:55] offset:36864
	s_waitcnt vmcnt(9)
	ds_write_b128 v161, v[56:59] offset:36864
	s_waitcnt vmcnt(8)
	ds_write_b128 v162, v[60:63] offset:36864
	v_accvgpr_write_b32 a160, 0
	v_mov_b32_e32 v48, 0
	v_accvgpr_write_b32 a161, 0
	v_mov_b32_e32 v49, 0
	v_accvgpr_write_b32 a162, 0
	v_mov_b32_e32 v50, 0
	v_accvgpr_write_b32 a163, 0
	v_mov_b32_e32 v51, 0
	v_accvgpr_write_b32 a164, 0
	v_mov_b32_e32 v52, 0
	v_accvgpr_write_b32 a165, 0
	v_mov_b32_e32 v53, 0
	v_accvgpr_write_b32 a166, 0
	v_mov_b32_e32 v54, 0
	v_accvgpr_write_b32 a167, 0
	v_mov_b32_e32 v55, 0
	v_accvgpr_write_b32 a168, 0
	v_mov_b32_e32 v56, 0
	v_accvgpr_write_b32 a169, 0
	v_mov_b32_e32 v57, 0
	v_accvgpr_write_b32 a170, 0
	v_mov_b32_e32 v58, 0
	v_accvgpr_write_b32 a171, 0
	v_mov_b32_e32 v59, 0
	v_accvgpr_write_b32 a172, 0
	v_mov_b32_e32 v60, 0
	v_accvgpr_write_b32 a173, 0
	v_mov_b32_e32 v61, 0
	v_accvgpr_write_b32 a174, 0
	v_mov_b32_e32 v62, 0
	v_accvgpr_write_b32 a175, 0
	v_mov_b32_e32 v63, 0
	v_accvgpr_write_b32 a176, 0
	v_mov_b32_e32 v116, 0
	v_accvgpr_write_b32 a177, 0
	v_mov_b32_e32 v117, 0
	v_accvgpr_write_b32 a178, 0
	v_mov_b32_e32 v118, 0
	v_accvgpr_write_b32 a179, 0
	v_mov_b32_e32 v119, 0
	v_accvgpr_write_b32 a180, 0
	v_mov_b32_e32 v120, 0
	v_accvgpr_write_b32 a181, 0
	v_mov_b32_e32 v121, 0
	v_accvgpr_write_b32 a182, 0
	v_mov_b32_e32 v122, 0
	v_accvgpr_write_b32 a183, 0
	v_mov_b32_e32 v123, 0
	v_accvgpr_write_b32 a184, 0
	v_mov_b32_e32 v124, 0
	v_accvgpr_write_b32 a185, 0
	v_mov_b32_e32 v125, 0
	v_accvgpr_write_b32 a186, 0
	v_mov_b32_e32 v126, 0
	v_accvgpr_write_b32 a187, 0
	v_mov_b32_e32 v127, 0
	v_accvgpr_write_b32 a188, 0
	v_mov_b32_e32 v130, 0
	v_accvgpr_write_b32 a189, 0
	v_mov_b32_e32 v131, 0
	v_accvgpr_write_b32 a190, 0
	v_mov_b32_e32 v132, 0
	v_accvgpr_write_b32 a191, 0
	v_mov_b32_e32 v133, 0
	v_mov_b32_e32 v200, 0
	v_mov_b32_e32 v201, 0
	v_mov_b32_e32 v202, 0
	v_mov_b32_e32 v203, 0
	v_mov_b32_e32 v204, 0
	v_mov_b32_e32 v205, 0
	v_mov_b32_e32 v206, 0
	v_mov_b32_e32 v207, 0
	v_mov_b32_e32 v208, 0
	v_mov_b32_e32 v209, 0
	v_mov_b32_e32 v210, 0
	v_mov_b32_e32 v211, 0
	v_mov_b32_e32 v212, 0
	v_mov_b32_e32 v213, 0
	v_mov_b32_e32 v214, 0
	v_mov_b32_e32 v215, 0
	v_mov_b32_e32 v136, 0
	v_mov_b32_e32 v137, 0
	v_mov_b32_e32 v100, 0
	v_mov_b32_e32 v101, 0
	v_mov_b32_e32 v102, 0
	v_mov_b32_e32 v103, 0
	v_mov_b32_e32 v104, 0
	v_mov_b32_e32 v105, 0
	v_mov_b32_e32 v106, 0
	v_mov_b32_e32 v107, 0
	v_mov_b32_e32 v108, 0
	v_mov_b32_e32 v109, 0
	v_mov_b32_e32 v110, 0
	v_mov_b32_e32 v111, 0
	v_mov_b32_e32 v112, 0
	v_mov_b32_e32 v113, 0
	v_mov_b32_e32 v114, 0
	v_mov_b32_e32 v115, 0
	v_mov_b32_e32 v144, 0
	v_mov_b32_e32 v145, 0
	v_accvgpr_read_b32 v32, a0
	v_accvgpr_read_b32 v33, a0
	v_accvgpr_read_b32 v34, a0
	v_accvgpr_read_b32 v35, a0
	v_accvgpr_read_b32 v36, a0
	v_accvgpr_read_b32 v37, a0
	v_accvgpr_read_b32 v38, a0
	v_accvgpr_read_b32 v39, a0
	v_accvgpr_read_b32 v40, a0
	v_accvgpr_read_b32 v41, a0
	v_accvgpr_read_b32 v42, a0
	v_accvgpr_read_b32 v43, a0
	v_accvgpr_read_b32 v44, a0
	v_accvgpr_read_b32 v45, a0
	v_accvgpr_read_b32 v46, a0
	v_accvgpr_read_b32 v47, a0
	v_mbcnt_lo_u32_b32 v235, -1, 0
	v_mbcnt_hi_u32_b32 v235, -1, v235
	v_lshlrev_b32_e32 v235, 4, v235
	v_add_u32_e32 v235, 0xd800, v235
	s_waitcnt lgkmcnt(0)
	ds_write_b128 v235, a[160:163]
	ds_write_b128 v235, a[160:163] offset:1024
	ds_write_b128 v235, a[160:163] offset:2048
	ds_write_b128 v235, a[160:163] offset:3072
	ds_write_b128 v235, a[160:163] offset:4096
	ds_write_b128 v235, a[160:163] offset:5120
	ds_write_b128 v235, a[160:163] offset:6144
	ds_write_b128 v235, a[160:163] offset:7168
	ds_write_b128 v235, a[160:163] offset:8192
	s_waitcnt lgkmcnt(0)
	ds_write_b128 v235, a[160:163] offset:9216
	ds_write_b128 v235, a[160:163] offset:10240
	ds_write_b128 v235, a[160:163] offset:11264
	ds_write_b128 v235, a[160:163] offset:12288
	ds_write_b128 v235, a[160:163] offset:13312
	ds_write_b128 v235, a[160:163] offset:14336
	ds_write_b128 v235, a[160:163] offset:15360
	ds_write_b128 v235, a[160:163] offset:16384
	ds_write_b128 v235, a[160:163] offset:17408
.LBB0_2271:
	s_and_b32 s61, s60, 1
	s_xor_b32 s62, s61, 1
	s_mulk_i32 s61, 0x4800
	s_mulk_i32 s62, 0x4800
	v_add_u32_e32 v233, s61, v128
	v_add_u32_e32 v234, s62, v150
	s_waitcnt vmcnt(0) lgkmcnt(0)
	s_barrier
	ds_read_b128 a[144:147], v233
	ds_read_b128 a[148:151], v233 offset:32
	ds_read_b128 a[152:155], v233 offset:64
	ds_read_b128 a[156:159], v233 offset:96
	s_waitcnt lgkmcnt(3)
	v_mfma_f32_32x32x16_bf16 v[184:199], a[144:147], v[28:31], v[32:47]
	v_pk_add_f32 v[136:137], v[136:137], v[200:201]
	v_pk_add_f32 v[136:137], v[136:137], v[202:203]
	v_pk_add_f32 v[136:137], v[136:137], v[204:205]
	v_pk_add_f32 v[136:137], v[136:137], v[206:207]
	v_pk_add_f32 v[136:137], v[136:137], v[208:209]
	v_pk_add_f32 v[136:137], v[136:137], v[210:211]
	s_cmp_eq_u32 s60, 0
	s_cselect_b32 s32, 0x9000, s61
	v_mfma_f32_32x32x16_bf16 v[168:183], a[144:147], v[12:15], v[32:47]
	v_pk_add_f32 v[136:137], v[136:137], v[212:213]
	v_pk_add_f32 v[136:137], v[136:137], v[214:215]
	v_cvt_pk_bf16_f32 v56, v200, v201
	v_cvt_pk_bf16_f32 v57, v202, v203
	v_cvt_pk_bf16_f32 v58, v204, v205
	v_add3_u32 v220, s32, v151, v134
	ds_read_b128 a[144:147], v233 offset:4608
	s_waitcnt lgkmcnt(3)
	v_mfma_f32_32x32x16_bf16 v[184:199], a[148:151], v[24:27], v[184:199]
	v_cvt_pk_bf16_f32 v59, v206, v207
	v_cvt_pk_bf16_f32 v60, v208, v209
	v_cvt_pk_bf16_f32 v61, v210, v211
	v_cvt_pk_bf16_f32 v62, v212, v213
	v_cvt_pk_bf16_f32 v63, v214, v215
	v_add3_u32 v221, s32, v156, v134
	v_mfma_f32_32x32x16_bf16 v[168:183], a[148:151], v[8:11], v[168:183]
	v_add_f32_e32 v235, v136, v137
	v_add_f32_e32 v81, v81, v235
	v_pk_add_f32 v[144:145], v[144:145], v[100:101]
	v_pk_add_f32 v[144:145], v[144:145], v[102:103]
	v_pk_add_f32 v[144:145], v[144:145], v[104:105]
	v_add3_u32 v222, s32, v157, v134
	ds_read_b128 a[148:151], v233 offset:4640
	s_waitcnt lgkmcnt(3)
	v_mfma_f32_32x32x16_bf16 v[184:199], a[152:155], v[20:23], v[184:199]
	v_pk_add_f32 v[144:145], v[144:145], v[106:107]
	v_pk_add_f32 v[144:145], v[144:145], v[108:109]
	v_pk_add_f32 v[144:145], v[144:145], v[110:111]
	v_pk_add_f32 v[144:145], v[144:145], v[112:113]
	v_pk_add_f32 v[144:145], v[144:145], v[114:115]
	v_add3_u32 v232, s32, v158, v134
	v_mfma_f32_32x32x16_bf16 v[168:183], a[152:155], v[4:7], v[168:183]
	v_cvt_pk_bf16_f32 v124, v100, v101
	v_cvt_pk_bf16_f32 v125, v102, v103
	v_cvt_pk_bf16_f32 v126, v104, v105
	v_cvt_pk_bf16_f32 v127, v106, v107
	v_cvt_pk_bf16_f32 v130, v108, v109
	ds_write_b128 v220, v[140:143] offset:36864
	ds_read_b128 a[152:155], v233 offset:4672
	s_waitcnt lgkmcnt(4)
	v_mfma_f32_32x32x16_bf16 v[184:199], a[156:159], v[16:19], v[184:199]
	v_cvt_pk_bf16_f32 v131, v110, v111
	v_cvt_pk_bf16_f32 v132, v112, v113
	v_cvt_pk_bf16_f32 v133, v114, v115
	v_add_f32_e32 v235, v144, v145
	v_add_f32_e32 v80, v80, v235
	ds_write_b128 v221, v[216:219] offset:36864
	v_mfma_f32_32x32x16_bf16 v[168:183], a[156:159], v[0:3], v[168:183]
	ds_write_b128 v222, v[224:227] offset:36864
	ds_read_b128 a[156:159], v233 offset:4704
	s_waitcnt lgkmcnt(6)
	v_mfma_f32_32x32x16_bf16 v[200:215], a[144:147], v[28:31], v[32:47]
	ds_write_b128 v232, v[228:231] offset:36864
	v_lshl_add_u64 v[98:99], v[82:83], 0, v[154:155]
	global_load_dwordx4 v[64:67], v[98:99], off
	v_lshl_add_u64 v[98:99], v[84:85], 0, v[154:155]
	global_load_dwordx4 v[68:71], v[98:99], off
	v_lshl_add_u64 v[98:99], v[86:87], 0, v[154:155]
	v_mfma_f32_32x32x16_bf16 v[100:115], a[144:147], v[12:15], v[32:47]
	global_load_dwordx4 v[72:75], v[98:99], off
	v_lshl_add_u64 v[98:99], v[88:89], 0, v[154:155]
	global_load_dwordx4 v[76:79], v[98:99], off
	v_accvgpr_write_b32 a160, v48
	v_accvgpr_write_b32 a161, v49
	v_accvgpr_write_b32 a162, v50
	s_waitcnt lgkmcnt(6)
	v_mfma_f32_32x32x16_bf16 v[200:215], a[148:151], v[24:27], v[200:215]
	v_accvgpr_write_b32 a163, v51
	v_accvgpr_write_b32 a164, v52
	v_accvgpr_write_b32 a165, v53
	v_accvgpr_write_b32 a166, v54
	v_accvgpr_write_b32 a167, v55
	v_mfma_f32_32x32x16_bf16 v[100:115], a[148:151], v[8:11], v[100:115]
	v_accvgpr_write_b32 a176, v116
	v_accvgpr_write_b32 a177, v117
	v_accvgpr_write_b32 a178, v118
	v_accvgpr_write_b32 a179, v119
	v_accvgpr_write_b32 a180, v120
	v_accvgpr_write_b32 a181, v121
	s_waitcnt lgkmcnt(4)
	v_mfma_f32_32x32x16_bf16 v[200:215], a[152:155], v[20:23], v[200:215]
	v_accvgpr_write_b32 a182, v122
	v_accvgpr_write_b32 a183, v123
	v_lshl_add_u64 v[82:83], v[82:83], 0, s[54:55]
	v_lshl_add_u64 v[84:85], v[84:85], 0, s[54:55]
	v_lshl_add_u64 v[86:87], v[86:87], 0, s[54:55]
	v_lshl_add_u64 v[88:89], v[88:89], 0, s[54:55]
	v_mfma_f32_32x32x16_bf16 v[100:115], a[152:155], v[4:7], v[100:115]
	v_accvgpr_write_b32 a168, v56
	v_accvgpr_write_b32 a169, v57
	v_accvgpr_write_b32 a170, v58
	v_accvgpr_write_b32 a171, v59
	v_accvgpr_write_b32 a172, v60
	s_waitcnt lgkmcnt(1)
	v_mfma_f32_32x32x16_bf16 v[200:215], a[156:159], v[16:19], v[200:215]
	v_accvgpr_write_b32 a173, v61
	v_accvgpr_write_b32 a174, v62
	v_accvgpr_write_b32 a175, v63
	v_accvgpr_write_b32 a184, v124
	v_accvgpr_write_b32 a185, v125
	v_accvgpr_write_b32 a186, v126
	v_mfma_f32_32x32x16_bf16 v[100:115], a[156:159], v[0:3], v[100:115]
	v_accvgpr_write_b32 a187, v127
	v_accvgpr_write_b32 a188, v130
	v_accvgpr_write_b32 a189, v131
	v_accvgpr_write_b32 a190, v132
	v_accvgpr_write_b32 a191, v133
	ds_read_b128 a[144:147], v234 offset:36864
	ds_read_b128 a[148:151], v234 offset:36896
	ds_read_b128 a[152:155], v234 offset:36928
	ds_read_b128 a[156:159], v234 offset:36960
	s_waitcnt lgkmcnt(3)
	v_mfma_f32_32x32x16_bf16 a[128:143], a[144:147], a[160:163], a[128:143]
	v_exp_f32_e32 v184, v184
	v_exp_f32_e32 v185, v185
	v_exp_f32_e32 v186, v186
	v_mfma_f32_32x32x16_bf16 a[112:127], a[144:147], a[176:179], a[112:127]
	v_exp_f32_e32 v187, v187
	v_exp_f32_e32 v188, v188
	v_exp_f32_e32 v189, v189
	ds_read_b128 a[144:147], v234 offset:41472
	s_waitcnt lgkmcnt(3)
	v_mfma_f32_32x32x16_bf16 a[128:143], a[148:151], a[164:167], a[128:143]
	v_exp_f32_e32 v190, v190
	v_exp_f32_e32 v191, v191
	v_exp_f32_e32 v192, v192
	v_mfma_f32_32x32x16_bf16 a[112:127], a[148:151], a[180:183], a[112:127]
	v_exp_f32_e32 v193, v193
	v_exp_f32_e32 v194, v194
	v_exp_f32_e32 v195, v195
	ds_read_b128 a[148:151], v234 offset:41504
	s_waitcnt lgkmcnt(3)
	v_mfma_f32_32x32x16_bf16 a[128:143], a[152:155], a[168:171], a[128:143]
	v_exp_f32_e32 v196, v196
	v_exp_f32_e32 v197, v197
	v_exp_f32_e32 v198, v198
	v_mfma_f32_32x32x16_bf16 a[112:127], a[152:155], a[184:187], a[112:127]
	v_exp_f32_e32 v199, v199
	v_pk_add_f32 v[136:137], v[184:185], v[186:187]
	v_pk_add_f32 v[136:137], v[136:137], v[188:189]
	ds_read_b128 a[152:155], v234 offset:41536
	s_waitcnt lgkmcnt(3)
	v_mfma_f32_32x32x16_bf16 a[128:143], a[156:159], a[172:175], a[128:143]
	v_pk_add_f32 v[136:137], v[136:137], v[190:191]
	v_pk_add_f32 v[136:137], v[136:137], v[192:193]
	v_pk_add_f32 v[136:137], v[136:137], v[194:195]
	v_mfma_f32_32x32x16_bf16 a[112:127], a[156:159], a[188:191], a[112:127]
	v_pk_add_f32 v[136:137], v[136:137], v[196:197]
	v_pk_add_f32 v[136:137], v[136:137], v[198:199]
	v_cvt_pk_bf16_f32 v48, v184, v185
	v_cvt_pk_bf16_f32 v49, v186, v187
	ds_read_b128 a[156:159], v234 offset:41568
	s_waitcnt lgkmcnt(3)
	v_mfma_f32_32x32x16_bf16 a[48:63], a[144:147], a[160:163], a[48:63]
	v_cvt_pk_bf16_f32 v50, v188, v189
	v_cvt_pk_bf16_f32 v51, v190, v191
	v_cvt_pk_bf16_f32 v52, v192, v193
	v_cvt_pk_bf16_f32 v53, v194, v195
	v_cvt_pk_bf16_f32 v54, v196, v197
	v_cvt_pk_bf16_f32 v55, v198, v199
	v_mfma_f32_32x32x16_bf16 a[64:79], a[144:147], a[176:179], a[64:79]
	v_add3_u32 v220, s62, v151, v134
	v_add3_u32 v221, s62, v156, v134
	s_waitcnt vmcnt(3)
	ds_write_b128 v220, v[64:67]
	s_waitcnt vmcnt(2)
	ds_write_b128 v221, v[68:71]
	s_waitcnt vmcnt(1)
	ds_read_b128 a[144:147], v234 offset:46080
	s_waitcnt lgkmcnt(5)
	v_mfma_f32_32x32x16_bf16 a[48:63], a[148:151], a[164:167], a[48:63]
	ds_write_b128 v220, v[72:75] offset:9216
	s_waitcnt vmcnt(0)
	ds_write_b128 v221, v[76:79] offset:9216
	v_lshl_add_u64 v[98:99], v[90:91], 0, v[154:155]
	global_load_dwordx4 v[140:143], v[98:99], off
	v_mfma_f32_32x32x16_bf16 a[64:79], a[148:151], a[180:183], a[64:79]
	v_lshl_add_u64 v[98:99], v[92:93], 0, v[154:155]
	global_load_dwordx4 v[216:219], v[98:99], off
	v_lshl_add_u64 v[98:99], v[94:95], 0, v[154:155]
	global_load_dwordx4 v[224:227], v[98:99], off
	v_lshl_add_u64 v[98:99], v[96:97], 0, v[154:155]
	global_load_dwordx4 v[228:231], v[98:99], off
	ds_read_b128 a[148:151], v234 offset:46112
	s_waitcnt lgkmcnt(7)
	v_mfma_f32_32x32x16_bf16 a[48:63], a[152:155], a[168:171], a[48:63]
	v_lshl_add_u64 v[90:91], v[90:91], 0, s[56:57]
	v_lshl_add_u64 v[92:93], v[92:93], 0, s[56:57]
	v_lshl_add_u64 v[94:95], v[94:95], 0, s[56:57]
	v_lshl_add_u64 v[96:97], v[96:97], 0, s[56:57]
	v_exp_f32_e32 v168, v168
	v_mfma_f32_32x32x16_bf16 a[64:79], a[152:155], a[184:187], a[64:79]
	v_exp_f32_e32 v169, v169
	v_exp_f32_e32 v170, v170
	v_exp_f32_e32 v171, v171
	ds_read_b128 a[152:155], v234 offset:46144
	s_waitcnt lgkmcnt(7)
	v_mfma_f32_32x32x16_bf16 a[48:63], a[156:159], a[172:175], a[48:63]
	v_exp_f32_e32 v172, v172
	v_exp_f32_e32 v173, v173
	v_exp_f32_e32 v174, v174
	v_mfma_f32_32x32x16_bf16 a[64:79], a[156:159], a[188:191], a[64:79]
	v_exp_f32_e32 v175, v175
	v_exp_f32_e32 v176, v176
	v_exp_f32_e32 v177, v177
	ds_read_b128 a[156:159], v234 offset:46176
	s_waitcnt lgkmcnt(5)
	v_mfma_f32_32x32x16_bf16 a[80:95], a[144:147], a[160:163], a[80:95]
	v_exp_f32_e32 v178, v178
	v_exp_f32_e32 v179, v179
	v_exp_f32_e32 v180, v180
	v_mfma_f32_32x32x16_bf16 a[96:111], a[144:147], a[176:179], a[96:111]
	v_exp_f32_e32 v181, v181
	v_exp_f32_e32 v182, v182
	v_exp_f32_e32 v183, v183
	ds_read_b128 a[144:147], v234 offset:50688
	s_waitcnt lgkmcnt(3)
	v_mfma_f32_32x32x16_bf16 a[80:95], a[148:151], a[164:167], a[80:95]
	v_pk_add_f32 v[144:145], v[168:169], v[170:171]
	v_pk_add_f32 v[144:145], v[144:145], v[172:173]
	v_pk_add_f32 v[144:145], v[144:145], v[174:175]
	v_mfma_f32_32x32x16_bf16 a[96:111], a[148:151], a[180:183], a[96:111]
	v_pk_add_f32 v[144:145], v[144:145], v[176:177]
	v_pk_add_f32 v[144:145], v[144:145], v[178:179]
	v_pk_add_f32 v[144:145], v[144:145], v[180:181]
	ds_read_b128 a[148:151], v234 offset:50720
	s_waitcnt lgkmcnt(3)
	v_mfma_f32_32x32x16_bf16 a[80:95], a[152:155], a[168:171], a[80:95]
	v_pk_add_f32 v[144:145], v[144:145], v[182:183]
	v_cvt_pk_bf16_f32 v116, v168, v169
	v_cvt_pk_bf16_f32 v117, v170, v171
	v_cvt_pk_bf16_f32 v118, v172, v173
	v_cvt_pk_bf16_f32 v119, v174, v175
	v_cvt_pk_bf16_f32 v120, v176, v177
	v_mfma_f32_32x32x16_bf16 a[96:111], a[152:155], a[184:187], a[96:111]
	v_cvt_pk_bf16_f32 v121, v178, v179
	v_cvt_pk_bf16_f32 v122, v180, v181
	v_cvt_pk_bf16_f32 v123, v182, v183
	v_exp_f32_e32 v200, v200
	ds_read_b128 a[152:155], v234 offset:50752
	s_waitcnt lgkmcnt(3)
	v_mfma_f32_32x32x16_bf16 a[80:95], a[156:159], a[172:175], a[80:95]
	v_exp_f32_e32 v201, v201
	v_exp_f32_e32 v202, v202
	v_exp_f32_e32 v203, v203
	v_mfma_f32_32x32x16_bf16 a[96:111], a[156:159], a[188:191], a[96:111]
	v_exp_f32_e32 v204, v204
	v_exp_f32_e32 v205, v205
	v_exp_f32_e32 v206, v206
	ds_read_b128 a[156:159], v234 offset:50784
	s_waitcnt lgkmcnt(3)
	v_mfma_f32_32x32x16_bf16 a[32:47], a[144:147], a[160:163], a[32:47]
	v_exp_f32_e32 v207, v207
	v_exp_f32_e32 v208, v208
	v_exp_f32_e32 v209, v209
	v_mfma_f32_32x32x16_bf16 a[16:31], a[144:147], a[176:179], a[16:31]
	v_exp_f32_e32 v210, v210
	v_exp_f32_e32 v211, v211
	v_exp_f32_e32 v212, v212
	s_waitcnt lgkmcnt(2)
	v_mfma_f32_32x32x16_bf16 a[32:47], a[148:151], a[164:167], a[32:47]
	v_exp_f32_e32 v213, v213
	v_exp_f32_e32 v214, v214
	v_exp_f32_e32 v215, v215
	v_mfma_f32_32x32x16_bf16 a[16:31], a[148:151], a[180:183], a[16:31]
	v_exp_f32_e32 v100, v100
	v_exp_f32_e32 v101, v101
	v_exp_f32_e32 v102, v102
	s_waitcnt lgkmcnt(1)
	v_mfma_f32_32x32x16_bf16 a[32:47], a[152:155], a[168:171], a[32:47]
	v_exp_f32_e32 v103, v103
	v_exp_f32_e32 v104, v104
	v_exp_f32_e32 v105, v105
	v_mfma_f32_32x32x16_bf16 a[16:31], a[152:155], a[184:187], a[16:31]
	v_exp_f32_e32 v106, v106
	v_exp_f32_e32 v107, v107
	v_exp_f32_e32 v108, v108
	s_waitcnt lgkmcnt(0)
	v_mfma_f32_32x32x16_bf16 a[32:47], a[156:159], a[172:175], a[32:47]
	v_exp_f32_e32 v109, v109
	v_exp_f32_e32 v110, v110
	v_exp_f32_e32 v111, v111
	v_mfma_f32_32x32x16_bf16 a[16:31], a[156:159], a[188:191], a[16:31]
	v_exp_f32_e32 v112, v112
	v_exp_f32_e32 v113, v113
	v_exp_f32_e32 v114, v114
	v_exp_f32_e32 v115, v115
	s_add_i32 s60, s60, 1
	s_cmp_eq_u32 s4, s60
	s_cbranch_scc0 .LBB0_2271
	s_waitcnt vmcnt(0) lgkmcnt(0)
	s_barrier
	v_add3_u32 v220, s62, v151, v134
	v_add3_u32 v221, s62, v156, v134
	v_add3_u32 v222, s62, v157, v134
	v_add3_u32 v232, s62, v158, v134
	ds_write_b128 v220, v[140:143] offset:36864
	ds_write_b128 v221, v[216:219] offset:36864
	ds_write_b128 v222, v[224:227] offset:36864
	ds_write_b128 v232, v[228:231] offset:36864
	v_add_u32_e32 v234, s61, v150
	v_pk_add_f32 v[136:137], v[136:137], v[200:201]
	v_pk_add_f32 v[136:137], v[136:137], v[202:203]
	v_pk_add_f32 v[136:137], v[136:137], v[204:205]
	v_pk_add_f32 v[136:137], v[136:137], v[206:207]
	v_pk_add_f32 v[136:137], v[136:137], v[208:209]
	v_pk_add_f32 v[136:137], v[136:137], v[210:211]
	v_pk_add_f32 v[136:137], v[136:137], v[212:213]
	v_pk_add_f32 v[136:137], v[136:137], v[214:215]
	v_cvt_pk_bf16_f32 v56, v200, v201
	v_cvt_pk_bf16_f32 v57, v202, v203
	v_cvt_pk_bf16_f32 v58, v204, v205
	v_cvt_pk_bf16_f32 v59, v206, v207
	v_cvt_pk_bf16_f32 v60, v208, v209
	v_cvt_pk_bf16_f32 v61, v210, v211
	v_cvt_pk_bf16_f32 v62, v212, v213
	v_cvt_pk_bf16_f32 v63, v214, v215
	v_add_f32_e32 v235, v136, v137
	v_add_f32_e32 v81, v81, v235
	v_pk_add_f32 v[144:145], v[144:145], v[100:101]
	v_pk_add_f32 v[144:145], v[144:145], v[102:103]
	v_pk_add_f32 v[144:145], v[144:145], v[104:105]
	v_pk_add_f32 v[144:145], v[144:145], v[106:107]
	v_pk_add_f32 v[144:145], v[144:145], v[108:109]
	v_pk_add_f32 v[144:145], v[144:145], v[110:111]
	v_pk_add_f32 v[144:145], v[144:145], v[112:113]
	v_pk_add_f32 v[144:145], v[144:145], v[114:115]
	v_cvt_pk_bf16_f32 v124, v100, v101
	v_cvt_pk_bf16_f32 v125, v102, v103
	v_cvt_pk_bf16_f32 v126, v104, v105
	v_cvt_pk_bf16_f32 v127, v106, v107
	v_cvt_pk_bf16_f32 v130, v108, v109
	v_cvt_pk_bf16_f32 v131, v110, v111
	v_cvt_pk_bf16_f32 v132, v112, v113
	v_cvt_pk_bf16_f32 v133, v114, v115
	v_add_f32_e32 v235, v144, v145
	v_add_f32_e32 v80, v80, v235
	s_nop 1
	ds_read_b128 a[144:147], v234 offset:36864
	ds_read_b128 a[148:151], v234 offset:36896
	ds_read_b128 a[152:155], v234 offset:36928
	ds_read_b128 a[156:159], v234 offset:36960
	s_waitcnt lgkmcnt(3)
	v_mfma_f32_32x32x16_bf16 a[128:143], a[144:147], v[48:51], a[128:143]
	v_mfma_f32_32x32x16_bf16 a[112:127], a[144:147], v[116:119], a[112:127]
	ds_read_b128 a[144:147], v234 offset:41472
	s_waitcnt lgkmcnt(3)
	v_mfma_f32_32x32x16_bf16 a[128:143], a[148:151], v[52:55], a[128:143]
	v_mfma_f32_32x32x16_bf16 a[112:127], a[148:151], v[120:123], a[112:127]
	ds_read_b128 a[148:151], v234 offset:41504
	s_waitcnt lgkmcnt(3)
	v_mfma_f32_32x32x16_bf16 a[128:143], a[152:155], v[56:59], a[128:143]
	v_mfma_f32_32x32x16_bf16 a[112:127], a[152:155], v[124:127], a[112:127]
	ds_read_b128 a[152:155], v234 offset:41536
	s_waitcnt lgkmcnt(3)
	v_mfma_f32_32x32x16_bf16 a[128:143], a[156:159], v[60:63], a[128:143]
	v_mfma_f32_32x32x16_bf16 a[112:127], a[156:159], v[130:133], a[112:127]
	ds_read_b128 a[156:159], v234 offset:41568
	s_waitcnt lgkmcnt(3)
	v_mfma_f32_32x32x16_bf16 a[48:63], a[144:147], v[48:51], a[48:63]
	v_mfma_f32_32x32x16_bf16 a[64:79], a[144:147], v[116:119], a[64:79]
	ds_read_b128 a[144:147], v234 offset:46080
	s_waitcnt lgkmcnt(3)
	v_mfma_f32_32x32x16_bf16 a[48:63], a[148:151], v[52:55], a[48:63]
	v_mfma_f32_32x32x16_bf16 a[64:79], a[148:151], v[120:123], a[64:79]
	ds_read_b128 a[148:151], v234 offset:46112
	s_waitcnt lgkmcnt(3)
	v_mfma_f32_32x32x16_bf16 a[48:63], a[152:155], v[56:59], a[48:63]
	v_mfma_f32_32x32x16_bf16 a[64:79], a[152:155], v[124:127], a[64:79]
	ds_read_b128 a[152:155], v234 offset:46144
	s_waitcnt lgkmcnt(3)
	v_mfma_f32_32x32x16_bf16 a[48:63], a[156:159], v[60:63], a[48:63]
	v_mfma_f32_32x32x16_bf16 a[64:79], a[156:159], v[130:133], a[64:79]
	ds_read_b128 a[156:159], v234 offset:46176
	s_waitcnt lgkmcnt(3)
	v_mfma_f32_32x32x16_bf16 a[80:95], a[144:147], v[48:51], a[80:95]
	v_mfma_f32_32x32x16_bf16 a[96:111], a[144:147], v[116:119], a[96:111]
	ds_read_b128 a[144:147], v234 offset:50688
	s_waitcnt lgkmcnt(3)
	v_mfma_f32_32x32x16_bf16 a[80:95], a[148:151], v[52:55], a[80:95]
	v_mfma_f32_32x32x16_bf16 a[96:111], a[148:151], v[120:123], a[96:111]
	ds_read_b128 a[148:151], v234 offset:50720
	s_waitcnt lgkmcnt(3)
	v_mfma_f32_32x32x16_bf16 a[80:95], a[152:155], v[56:59], a[80:95]
	v_mfma_f32_32x32x16_bf16 a[96:111], a[152:155], v[124:127], a[96:111]
	ds_read_b128 a[152:155], v234 offset:50752
	s_waitcnt lgkmcnt(3)
	v_mfma_f32_32x32x16_bf16 a[80:95], a[156:159], v[60:63], a[80:95]
	v_mfma_f32_32x32x16_bf16 a[96:111], a[156:159], v[130:133], a[96:111]
	ds_read_b128 a[156:159], v234 offset:50784
	s_waitcnt lgkmcnt(3)
	v_mfma_f32_32x32x16_bf16 a[32:47], a[144:147], v[48:51], a[32:47]
	v_mfma_f32_32x32x16_bf16 a[16:31], a[144:147], v[116:119], a[16:31]
	s_waitcnt lgkmcnt(2)
	v_mfma_f32_32x32x16_bf16 a[32:47], a[148:151], v[52:55], a[32:47]
	v_mfma_f32_32x32x16_bf16 a[16:31], a[148:151], v[120:123], a[16:31]
	s_waitcnt lgkmcnt(1)
	v_mfma_f32_32x32x16_bf16 a[32:47], a[152:155], v[56:59], a[32:47]
	v_mfma_f32_32x32x16_bf16 a[16:31], a[152:155], v[124:127], a[16:31]
	s_waitcnt lgkmcnt(0)
	v_mfma_f32_32x32x16_bf16 a[32:47], a[156:159], v[60:63], a[32:47]
	v_mfma_f32_32x32x16_bf16 a[16:31], a[156:159], v[130:133], a[16:31]
	s_bitcmp1_b32 s4, 0
	s_cselect_b32 s4, 0x4800, 0
	v_add_u32_e32 v48, s4, v128
	s_waitcnt lgkmcnt(0)
	s_barrier
	ds_read_b128 v[32:35], v48
	ds_read_b128 v[36:39], v48 offset:32
	s_waitcnt lgkmcnt(1)
	v_mfma_f32_32x32x16_bf16 a[186:201], v[32:35], v[28:31], a[0:15]
	v_add_u32_e32 v83, s4, v150
	v_mfma_f32_32x32x16_bf16 a[144:159], v[32:35], v[12:15], a[0:15]
	s_waitcnt lgkmcnt(0)
	v_mfma_f32_32x32x16_bf16 a[186:201], v[36:39], v[24:27], a[186:201]
	v_mfma_f32_32x32x16_bf16 a[144:159], v[36:39], v[8:11], a[144:159]
	ds_read_b128 v[32:35], v48 offset:64
	ds_read_b128 v[36:39], v48 offset:96
	s_waitcnt lgkmcnt(1)
	v_mfma_f32_32x32x16_bf16 a[186:201], v[32:35], v[20:23], a[186:201]
	s_waitcnt lgkmcnt(0)
	v_mfma_f32_32x32x16_bf16 a[186:201], v[36:39], v[16:19], a[186:201]
	v_mfma_f32_32x32x16_bf16 a[144:159], v[32:35], v[4:7], a[144:159]
	ds_read_b128 v[32:35], v48 offset:4608
	ds_read_b128 v[40:43], v48 offset:4640
	ds_read_b128 v[44:47], v48 offset:4672
	ds_read_b128 v[48:51], v48 offset:4704
	s_nop 6
	v_accvgpr_read_b32 v52, a186
	v_accvgpr_read_b32 v53, a187
	v_accvgpr_read_b32 v54, a188
	v_exp_f32_e32 v52, v52
	v_exp_f32_e32 v53, v53
	s_waitcnt lgkmcnt(3)
	v_mfma_f32_32x32x16_bf16 a[172:187], v[32:35], v[28:31], a[0:15]
	v_accvgpr_read_b32 v28, a189
	v_exp_f32_e32 v55, v28
	v_accvgpr_read_b32 v28, a190
	v_exp_f32_e32 v56, v28
	v_accvgpr_read_b32 v28, a191
	v_exp_f32_e32 v54, v54
	v_exp_f32_e32 v57, v28
	s_waitcnt lgkmcnt(2)
	v_mfma_f32_32x32x16_bf16 a[172:187], v[40:43], v[24:27], a[172:187]
	v_accvgpr_read_b32 v24, a192
	v_exp_f32_e32 v58, v24
	v_accvgpr_read_b32 v24, a193
	v_exp_f32_e32 v59, v24
	v_accvgpr_read_b32 v24, a194
	v_exp_f32_e32 v60, v24
	v_accvgpr_read_b32 v24, a195
	s_waitcnt lgkmcnt(1)
	v_mfma_f32_32x32x16_bf16 a[172:187], v[44:47], v[20:23], a[172:187]
	v_accvgpr_read_b32 v20, a196
	v_exp_f32_e32 v62, v20
	v_accvgpr_read_b32 v20, a197
	v_exp_f32_e32 v63, v20
	v_accvgpr_read_b32 v20, a198
	v_exp_f32_e32 v64, v20
	v_exp_f32_e32 v61, v24
	s_waitcnt lgkmcnt(0)
	v_mfma_f32_32x32x16_bf16 a[172:187], v[48:51], v[16:19], a[172:187]
	v_accvgpr_read_b32 v16, a199
	v_exp_f32_e32 v65, v16
	v_accvgpr_read_b32 v16, a200
	v_exp_f32_e32 v66, v16
	v_accvgpr_read_b32 v16, a201
	v_exp_f32_e32 v67, v16
	ds_read_b128 v[28:31], v83 offset:36928
	v_mfma_f32_32x32x16_bf16 a[144:159], v[36:39], v[0:3], a[144:159]
	s_nop 3
	v_accvgpr_read_b32 v16, a172
	v_exp_f32_e32 v36, v16
	v_accvgpr_read_b32 v16, a173
	v_exp_f32_e32 v37, v16
	v_accvgpr_read_b32 v16, a174
	v_exp_f32_e32 v38, v16
	v_accvgpr_read_b32 v16, a175
	v_mfma_f32_32x32x16_bf16 a[160:175], v[32:35], v[12:15], a[0:15]
	v_exp_f32_e32 v39, v16
	v_accvgpr_read_b32 v16, a144
	v_accvgpr_read_b32 v12, a176
	v_exp_f32_e32 v68, v12
	v_accvgpr_read_b32 v12, a177
	v_accvgpr_read_b32 v20, a157
	v_exp_f32_e32 v69, v12
	v_mfma_f32_32x32x16_bf16 a[160:175], v[40:43], v[8:11], a[160:175]
	v_accvgpr_read_b32 v12, a178
	v_exp_f32_e32 v84, v20
	v_accvgpr_read_b32 v20, a158
	v_exp_f32_e32 v70, v12
	v_accvgpr_read_b32 v12, a179
	v_exp_f32_e32 v85, v20
	v_accvgpr_read_b32 v20, a159
	v_mfma_f32_32x32x16_bf16 a[160:175], v[44:47], v[4:7], a[160:175]
	v_exp_f32_e32 v40, v12
	v_cvt_pk_bf16_f32 v12, v52, v53
	v_cvt_pk_bf16_f32 v13, v54, v55
	v_cvt_pk_bf16_f32 v14, v56, v57
	v_cvt_pk_bf16_f32 v15, v58, v59
	v_exp_f32_e32 v86, v20
	ds_read_b128 v[20:23], v83 offset:36896
	v_mfma_f32_32x32x16_bf16 a[160:175], v[48:51], v[0:3], a[160:175]
	v_exp_f32_e32 v49, v16
	v_accvgpr_read_b32 v16, a145
	v_exp_f32_e32 v50, v16
	v_accvgpr_read_b32 v16, a146
	v_exp_f32_e32 v51, v16
	v_accvgpr_read_b32 v16, a147
	v_exp_f32_e32 v71, v16
	v_accvgpr_read_b32 v16, a148
	v_exp_f32_e32 v72, v16
	v_accvgpr_read_b32 v16, a149
	v_exp_f32_e32 v73, v16
	v_accvgpr_read_b32 v16, a150
	v_exp_f32_e32 v74, v16
	v_accvgpr_read_b32 v16, a151
	v_exp_f32_e32 v75, v16
	v_accvgpr_read_b32 v16, a152
	v_exp_f32_e32 v76, v16
	v_accvgpr_read_b32 v16, a153
	v_exp_f32_e32 v77, v16
	v_accvgpr_read_b32 v16, a154
	v_exp_f32_e32 v78, v16
	v_accvgpr_read_b32 v16, a155
	v_exp_f32_e32 v79, v16
	v_accvgpr_read_b32 v16, a156
	v_exp_f32_e32 v82, v16
	ds_read_b128 v[16:19], v83 offset:36864
	v_accvgpr_read_b32 v24, a160
	v_exp_f32_e32 v87, v24
	v_accvgpr_read_b32 v24, a161
	v_exp_f32_e32 v88, v24
	v_cvt_pk_bf16_f32 v24, v49, v50
	v_cvt_pk_bf16_f32 v25, v51, v71
	v_cvt_pk_bf16_f32 v26, v72, v73
	v_cvt_pk_bf16_f32 v27, v74, v75
	s_waitcnt lgkmcnt(0)
	v_mfma_f32_32x32x16_bf16 a[144:159], v[16:19], v[12:15], a[128:143]
	v_accvgpr_read_b32 v8, a180
	v_exp_f32_e32 v41, v8
	v_accvgpr_read_b32 v8, a181
	v_exp_f32_e32 v42, v8
	v_accvgpr_read_b32 v8, a182
	v_exp_f32_e32 v43, v8
	v_cvt_pk_bf16_f32 v8, v60, v61
	v_mfma_f32_32x32x16_bf16 a[128:143], v[16:19], v[24:27], a[112:127]
	v_accvgpr_read_b32 v16, a162
	v_exp_f32_e32 v89, v16
	v_accvgpr_read_b32 v16, a163
	v_exp_f32_e32 v90, v16
	v_accvgpr_read_b32 v16, a164
	v_exp_f32_e32 v91, v16
	v_accvgpr_read_b32 v16, a165
	v_cvt_pk_bf16_f32 v9, v62, v63
	v_cvt_pk_bf16_f32 v10, v64, v65
	v_cvt_pk_bf16_f32 v11, v66, v67
	v_exp_f32_e32 v92, v16
	v_cvt_pk_bf16_f32 v16, v76, v77
	v_cvt_pk_bf16_f32 v17, v78, v79
	v_cvt_pk_bf16_f32 v18, v82, v84
	v_cvt_pk_bf16_f32 v19, v85, v86
	v_mfma_f32_32x32x16_bf16 a[144:159], v[20:23], v[8:11], a[144:159]
	v_accvgpr_read_b32 v32, a166
	v_accvgpr_read_b32 v4, a183
	v_exp_f32_e32 v93, v32
	v_exp_f32_e32 v44, v4
	v_accvgpr_read_b32 v4, a184
	v_exp_f32_e32 v45, v4
	v_accvgpr_read_b32 v4, a185
	v_mfma_f32_32x32x16_bf16 a[128:143], v[20:23], v[16:19], a[128:143]
	v_accvgpr_read_b32 v20, a167
	v_exp_f32_e32 v94, v20
	v_accvgpr_read_b32 v32, a169
	v_exp_f32_e32 v46, v4
	v_accvgpr_read_b32 v4, a186
	v_exp_f32_e32 v96, v32
	v_accvgpr_read_b32 v32, a170
	v_exp_f32_e32 v47, v4
	v_cvt_pk_bf16_f32 v4, v36, v37
	v_cvt_pk_bf16_f32 v5, v38, v39
	v_cvt_pk_bf16_f32 v6, v68, v69
	v_cvt_pk_bf16_f32 v7, v70, v40
	v_accvgpr_read_b32 v20, a168
	v_exp_f32_e32 v97, v32
	v_cvt_pk_bf16_f32 v32, v87, v88
	v_cvt_pk_bf16_f32 v33, v89, v90
	v_cvt_pk_bf16_f32 v34, v91, v92
	v_cvt_pk_bf16_f32 v35, v93, v94
	v_exp_f32_e32 v95, v20
	ds_read_b128 v[20:23], v83 offset:36960
	v_mfma_f32_32x32x16_bf16 a[144:159], v[28:31], v[4:7], a[144:159]
	v_accvgpr_read_b32 v0, a187
	v_exp_f32_e32 v48, v0
	v_cvt_pk_bf16_f32 v0, v41, v42
	v_cvt_pk_bf16_f32 v1, v43, v44
	v_cvt_pk_bf16_f32 v2, v45, v46
	v_cvt_pk_bf16_f32 v3, v47, v48
	v_cvt_pk_bf16_f32 v130, v95, v96
	v_mfma_f32_32x32x16_bf16 a[128:143], v[28:31], v[32:35], a[128:143]
	v_accvgpr_read_b32 v28, a171
	v_exp_f32_e32 v98, v28
	v_accvgpr_read_b32 v28, a172
	v_exp_f32_e32 v99, v28
	v_accvgpr_read_b32 v28, a173
	v_exp_f32_e32 v100, v28
	v_accvgpr_read_b32 v28, a174
	v_exp_f32_e32 v101, v28
	v_accvgpr_read_b32 v28, a175
	v_exp_f32_e32 v102, v28
	v_cvt_pk_bf16_f32 v131, v97, v98
	v_cvt_pk_bf16_f32 v132, v99, v100
	s_waitcnt lgkmcnt(0)
	v_mfma_f32_32x32x16_bf16 a[144:159], v[20:23], v[0:3], a[144:159]
	v_cvt_pk_bf16_f32 v133, v101, v102
	s_nop 1
	v_mfma_f32_32x32x16_bf16 a[128:143], v[20:23], v[130:133], a[128:143]
	ds_read_b128 v[20:23], v83 offset:41472
	ds_read_b128 v[28:31], v83 offset:41504
	s_nop 5
	v_accvgpr_read_b32 v112, a144
	v_accvgpr_read_b32 v113, a145
	v_accvgpr_read_b32 v114, a146
	v_accvgpr_read_b32 v115, a147
	s_waitcnt lgkmcnt(1)
	v_mfma_f32_32x32x16_bf16 a[112:127], v[20:23], v[12:15], a[48:63]
	v_accvgpr_read_b32 v116, a148
	v_accvgpr_read_b32 v117, a149
	v_accvgpr_read_b32 v118, a150
	v_accvgpr_read_b32 v119, a151
	v_accvgpr_read_b32 v120, a152
	v_accvgpr_read_b32 v121, a153
	v_accvgpr_read_b32 v122, a154
	v_mfma_f32_32x32x16_bf16 a[48:63], v[20:23], v[24:27], a[64:79]
	v_accvgpr_read_b32 v123, a155
	v_accvgpr_read_b32 v124, a156
	v_accvgpr_read_b32 v125, a157
	v_accvgpr_read_b32 v126, a158
	v_accvgpr_read_b32 v127, a159
	s_waitcnt lgkmcnt(0)
	v_mfma_f32_32x32x16_bf16 a[112:127], v[28:31], v[8:11], a[112:127]
	v_mfma_f32_32x32x16_bf16 a[48:63], v[28:31], v[16:19], a[48:63]
	ds_read_b128 v[20:23], v83 offset:41536
	ds_read_b128 v[28:31], v83 offset:41568
	s_waitcnt lgkmcnt(1)
	v_mfma_f32_32x32x16_bf16 a[112:127], v[20:23], v[4:7], a[112:127]
	v_mfma_f32_32x32x16_bf16 a[48:63], v[20:23], v[32:35], a[48:63]
	s_waitcnt lgkmcnt(0)
	v_mfma_f32_32x32x16_bf16 a[112:127], v[28:31], v[0:3], a[112:127]
	v_mfma_f32_32x32x16_bf16 a[48:63], v[28:31], v[130:133], a[48:63]
	ds_read_b128 v[20:23], v83 offset:46080
	ds_read_b128 v[28:31], v83 offset:46112
	s_waitcnt lgkmcnt(1)
	v_mfma_f32_32x32x16_bf16 a[64:79], v[20:23], v[12:15], a[80:95]
	v_mfma_f32_32x32x16_bf16 a[80:95], v[20:23], v[24:27], a[96:111]
	ds_read_b128 v[20:23], v83 offset:46144
	s_waitcnt lgkmcnt(1)
	v_mfma_f32_32x32x16_bf16 a[64:79], v[28:31], v[8:11], a[64:79]
	v_mfma_f32_32x32x16_bf16 a[80:95], v[28:31], v[16:19], a[80:95]
	v_add_f32_e32 v28, 0, v52
	v_add_f32_e32 v28, v53, v28
	v_add_f32_e32 v28, v54, v28
	v_add_f32_e32 v28, v55, v28
	v_add_f32_e32 v52, v56, v28
	v_add_f32_e32 v52, v57, v52
	v_add_f32_e32 v52, v58, v52
	v_add_f32_e32 v52, v59, v52
	v_add_f32_e32 v52, v60, v52
	v_add_f32_e32 v52, v61, v52
	v_add_f32_e32 v52, v62, v52
	v_add_f32_e32 v52, v63, v52
	ds_read_b128 v[28:31], v83 offset:46176
	s_waitcnt lgkmcnt(1)
	v_mfma_f32_32x32x16_bf16 a[64:79], v[20:23], v[4:7], a[64:79]
	v_mfma_f32_32x32x16_bf16 a[80:95], v[20:23], v[32:35], a[80:95]
	v_add_f32_e32 v20, v64, v52
	v_add_f32_e32 v20, v65, v20
	v_add_f32_e32 v20, v66, v20
	v_add_f32_e32 v20, v67, v20
	v_add_f32_e32 v20, v36, v20
	v_add_f32_e32 v20, v37, v20
	v_add_f32_e32 v20, v38, v20
	v_add_f32_e32 v20, v39, v20
	v_add_f32_e32 v20, v68, v20
	v_add_f32_e32 v20, v69, v20
	v_add_f32_e32 v20, v70, v20
	v_add_f32_e32 v20, v40, v20
	v_add_f32_e32 v36, v41, v20
	ds_read_b128 v[20:23], v83 offset:50688
	s_waitcnt lgkmcnt(1)
	v_mfma_f32_32x32x16_bf16 a[64:79], v[28:31], v[0:3], a[64:79]
	v_mfma_f32_32x32x16_bf16 a[80:95], v[28:31], v[130:133], a[80:95]
	v_add_f32_e32 v28, v42, v36
	v_add_f32_e32 v28, v43, v28
	v_add_f32_e32 v28, v44, v28
	v_add_f32_e32 v28, v45, v28
	v_add_f32_e32 v28, v46, v28
	v_add_f32_e32 v36, v47, v28
	ds_read_b128 v[28:31], v83 offset:50720
	s_waitcnt lgkmcnt(1)
	v_mfma_f32_32x32x16_bf16 a[96:111], v[20:23], v[12:15], a[32:47]
	v_add_f32_e32 v12, v48, v36
	v_add_f32_e32 v136, v81, v12
	v_add_f32_e32 v12, 0, v49
	v_add_f32_e32 v12, v50, v12
	v_add_f32_e32 v12, v51, v12
	v_add_f32_e32 v12, v71, v12
	v_add_f32_e32 v12, v72, v12
	v_add_f32_e32 v12, v73, v12
	v_add_f32_e32 v12, v74, v12
	v_add_f32_e32 v12, v75, v12
	v_add_f32_e32 v12, v76, v12
	v_add_f32_e32 v12, v77, v12
	v_add_f32_e32 v12, v78, v12
	v_add_f32_e32 v12, v79, v12
	s_waitcnt lgkmcnt(0)
	v_mfma_f32_32x32x16_bf16 a[96:111], v[28:31], v[8:11], a[96:111]
	v_add_f32_e32 v8, v82, v12
	v_add_f32_e32 v8, v84, v8
	v_add_f32_e32 v8, v85, v8
	v_add_f32_e32 v8, v86, v8
	v_add_f32_e32 v8, v87, v8
	v_add_f32_e32 v12, v88, v8
	ds_read_b128 v[8:11], v83 offset:50752
	v_mfma_f32_32x32x16_bf16 a[32:47], v[20:23], v[24:27], a[16:31]
	v_add_f32_e32 v12, v89, v12
	v_add_f32_e32 v12, v90, v12
	v_add_f32_e32 v12, v91, v12
	v_add_f32_e32 v12, v92, v12
	v_add_f32_e32 v12, v93, v12
	v_accvgpr_read_b32 v48, a128
	v_accvgpr_read_b32 v49, a129
	v_mfma_f32_32x32x16_bf16 a[32:47], v[28:31], v[16:19], a[32:47]
	v_add_f32_e32 v16, v94, v12
	ds_read_b128 v[12:15], v83 offset:50784
	v_accvgpr_read_b32 v50, a130
	v_accvgpr_read_b32 v51, a131
	v_accvgpr_read_b32 v52, a132
	v_accvgpr_read_b32 v53, a133
	v_accvgpr_read_b32 v54, a134
	s_waitcnt lgkmcnt(1)
	v_mfma_f32_32x32x16_bf16 a[96:111], v[8:11], v[4:7], a[96:111]
	v_add_f32_e32 v4, v95, v16
	v_add_f32_e32 v4, v96, v4
	v_add_f32_e32 v4, v97, v4
	v_add_f32_e32 v4, v98, v4
	v_add_f32_e32 v4, v99, v4
	v_add_f32_e32 v4, v100, v4
	v_add_f32_e32 v4, v101, v4
	v_add_f32_e32 v4, v102, v4
	v_add_f32_e32 v137, v80, v4
	ds_bpermute_b32 v4, v159, v136
	v_mfma_f32_32x32x16_bf16 a[32:47], v[8:11], v[32:35], a[32:47]
	v_accvgpr_read_b32 v96, a112
	v_accvgpr_read_b32 v32, a48
	v_accvgpr_read_b32 v95, a79
	s_waitcnt lgkmcnt(0)
	v_add_f32_e32 v136, v136, v4
	v_div_scale_f32 v140, s[60:61], v136, v136, 1.0
	v_rcp_f32_e32 v141, v140
	v_mfma_f32_32x32x16_bf16 a[32:47], v[12:15], v[130:133], a[32:47]
	ds_bpermute_b32 v131, v159, v137
	v_accvgpr_read_b32 v16, a80
	v_fma_f32 v130, -v140, v141, 1.0
	v_fmac_f32_e32 v141, v130, v141
	v_div_scale_f32 v130, vcc, 1.0, v136, 1.0
	v_mul_f32_e32 v132, v130, v141
	v_fma_f32 v133, -v140, v132, v130
	s_waitcnt lgkmcnt(0)
	v_add_f32_e32 v131, v137, v131
	v_fmac_f32_e32 v132, v133, v141
	v_div_scale_f32 v133, s[60:61], v131, v131, 1.0
	v_rcp_f32_e32 v137, v133
	v_mfma_f32_32x32x16_bf16 a[96:111], v[12:15], v[0:3], a[96:111]
	v_fma_f32 v130, -v140, v132, v130
	v_div_fmas_f32 v130, v130, v141, v132
	v_div_fixup_f32 v222, v130, v136, 1.0
	v_fma_f32 v130, -v133, v137, 1.0
	v_fmac_f32_e32 v137, v130, v137
	v_div_scale_f32 v130, vcc, 1.0, v131, 1.0
	v_mul_f32_e32 v132, v130, v137
	v_fma_f32 v136, -v133, v132, v130
	v_fmac_f32_e32 v132, v136, v137
	v_fma_f32 v130, -v133, v132, v130
	v_accvgpr_read_b32 v0, a32
	s_nop 0
	v_accvgpr_read_b32 v64, a96
	v_div_fmas_f32 v130, v130, v137, v132
	v_accvgpr_read_b32 v55, a135
	v_accvgpr_read_b32 v56, a136
	v_accvgpr_read_b32 v57, a137
	v_accvgpr_read_b32 v58, a138
	v_accvgpr_read_b32 v59, a139
	v_accvgpr_read_b32 v60, a140
	v_accvgpr_read_b32 v61, a141
	v_accvgpr_read_b32 v62, a142
	v_accvgpr_read_b32 v63, a143
	v_accvgpr_read_b32 v97, a113
	v_accvgpr_read_b32 v98, a114
	v_accvgpr_read_b32 v99, a115
	v_accvgpr_read_b32 v100, a116
	v_accvgpr_read_b32 v101, a117
	v_accvgpr_read_b32 v102, a118
	v_accvgpr_read_b32 v103, a119
	v_accvgpr_read_b32 v104, a120
	v_accvgpr_read_b32 v105, a121
	v_accvgpr_read_b32 v106, a122
	v_accvgpr_read_b32 v107, a123
	v_accvgpr_read_b32 v108, a124
	v_accvgpr_read_b32 v109, a125
	v_accvgpr_read_b32 v110, a126
	v_accvgpr_read_b32 v111, a127
	v_accvgpr_read_b32 v33, a49
	v_accvgpr_read_b32 v34, a50
	v_accvgpr_read_b32 v35, a51
	v_accvgpr_read_b32 v36, a52
	v_accvgpr_read_b32 v37, a53
	v_accvgpr_read_b32 v38, a54
	v_accvgpr_read_b32 v39, a55
	v_accvgpr_read_b32 v40, a56
	v_accvgpr_read_b32 v41, a57
	v_accvgpr_read_b32 v42, a58
	v_accvgpr_read_b32 v43, a59
	v_accvgpr_read_b32 v44, a60
	v_accvgpr_read_b32 v45, a61
	v_accvgpr_read_b32 v46, a62
	v_accvgpr_read_b32 v47, a63
	v_accvgpr_read_b32 v94, a78
	v_accvgpr_read_b32 v93, a77
	v_accvgpr_read_b32 v92, a76
	v_accvgpr_read_b32 v91, a75
	v_accvgpr_read_b32 v90, a74
	v_accvgpr_read_b32 v89, a73
	v_accvgpr_read_b32 v88, a72
	v_accvgpr_read_b32 v87, a71
	v_accvgpr_read_b32 v86, a70
	v_accvgpr_read_b32 v85, a69
	v_accvgpr_read_b32 v84, a68
	v_accvgpr_read_b32 v83, a67
	v_accvgpr_read_b32 v82, a66
	v_accvgpr_read_b32 v81, a65
	v_accvgpr_read_b32 v80, a64
	v_accvgpr_read_b32 v17, a81
	v_accvgpr_read_b32 v18, a82
	v_accvgpr_read_b32 v19, a83
	v_accvgpr_read_b32 v20, a84
	v_accvgpr_read_b32 v21, a85
	v_accvgpr_read_b32 v22, a86
	v_accvgpr_read_b32 v23, a87
	v_accvgpr_read_b32 v24, a88
	v_accvgpr_read_b32 v25, a89
	v_accvgpr_read_b32 v26, a90
	v_accvgpr_read_b32 v27, a91
	v_accvgpr_read_b32 v28, a92
	v_accvgpr_read_b32 v29, a93
	v_accvgpr_read_b32 v30, a94
	v_accvgpr_read_b32 v31, a95
	v_accvgpr_read_b32 v65, a97
	v_accvgpr_read_b32 v66, a98
	v_accvgpr_read_b32 v67, a99
	v_accvgpr_read_b32 v68, a100
	v_accvgpr_read_b32 v69, a101
	v_accvgpr_read_b32 v70, a102
	v_accvgpr_read_b32 v71, a103
	v_accvgpr_read_b32 v72, a104
	v_accvgpr_read_b32 v73, a105
	v_accvgpr_read_b32 v74, a106
	v_accvgpr_read_b32 v75, a107
	v_accvgpr_read_b32 v76, a108
	v_accvgpr_read_b32 v77, a109
	v_accvgpr_read_b32 v78, a110
	v_accvgpr_read_b32 v79, a111
	v_accvgpr_read_b32 v1, a33
	v_accvgpr_read_b32 v2, a34
	v_accvgpr_read_b32 v3, a35
	v_accvgpr_read_b32 v4, a36
	v_accvgpr_read_b32 v5, a37
	v_accvgpr_read_b32 v6, a38
	v_accvgpr_read_b32 v7, a39
	v_accvgpr_read_b32 v8, a40
	v_accvgpr_read_b32 v9, a41
	v_accvgpr_read_b32 v10, a42
	v_accvgpr_read_b32 v11, a43
	v_accvgpr_read_b32 v12, a44
	v_accvgpr_read_b32 v13, a45
	v_accvgpr_read_b32 v14, a46
	v_accvgpr_read_b32 v15, a47
	v_div_fixup_f32 v168, v130, v131, 1.0
	s_barrier
	s_and_saveexec_b64 s[60:61], s[6:7]
	s_cbranch_execz .LBB0_2274
	v_accvgpr_read_b32 v133, a216
	v_mul_f32_e32 v130, v133, v222
	v_mul_f32_e32 v131, v112, v130
	v_mul_f32_e32 v132, v113, v130
	ds_write2st64_b32 v139, v131, v132 offset1:1
	v_mul_f32_e32 v131, v114, v130
	v_mul_f32_e32 v132, v115, v130
	ds_write2st64_b32 v139, v131, v132 offset0:2 offset1:3
	v_mul_f32_e32 v131, v116, v130
	v_mul_f32_e32 v132, v117, v130
	ds_write2st64_b32 v139, v131, v132 offset0:4 offset1:5
	v_mul_f32_e32 v131, v118, v130
	v_mul_f32_e32 v132, v119, v130
	ds_write2st64_b32 v139, v131, v132 offset0:6 offset1:7
	v_mul_f32_e32 v131, v120, v130
	v_mul_f32_e32 v132, v121, v130
	ds_write2st64_b32 v139, v131, v132 offset0:8 offset1:9
	v_mul_f32_e32 v131, v122, v130
	v_mul_f32_e32 v132, v123, v130
	ds_write2st64_b32 v139, v131, v132 offset0:10 offset1:11
	v_mul_f32_e32 v131, v124, v130
	v_mul_f32_e32 v132, v125, v130
	ds_write2st64_b32 v139, v131, v132 offset0:12 offset1:13
	v_mul_f32_e32 v131, v126, v130
	v_mul_f32_e32 v132, v127, v130
	ds_write2st64_b32 v139, v131, v132 offset0:14 offset1:15
	v_mul_f32_e32 v131, v96, v130
	v_mul_f32_e32 v132, v97, v130
	ds_write2st64_b32 v139, v131, v132 offset0:16 offset1:17
	v_mul_f32_e32 v131, v98, v130
	v_mul_f32_e32 v132, v99, v130
	ds_write2st64_b32 v139, v131, v132 offset0:18 offset1:19
	v_mul_f32_e32 v131, v100, v130
	v_mul_f32_e32 v132, v101, v130
	ds_write2st64_b32 v139, v131, v132 offset0:20 offset1:21
	v_mul_f32_e32 v131, v102, v130
	v_mul_f32_e32 v132, v103, v130
	ds_write2st64_b32 v139, v131, v132 offset0:22 offset1:23
	v_mul_f32_e32 v131, v104, v130
	v_mul_f32_e32 v132, v105, v130
	ds_write2st64_b32 v139, v131, v132 offset0:24 offset1:25
	v_mul_f32_e32 v131, v106, v130
	v_mul_f32_e32 v132, v107, v130
	ds_write2st64_b32 v139, v131, v132 offset0:26 offset1:27
	v_mul_f32_e32 v131, v108, v130
	v_mul_f32_e32 v132, v109, v130
	ds_write2st64_b32 v139, v131, v132 offset0:28 offset1:29
	v_mul_f32_e32 v131, v110, v130
	v_mul_f32_e32 v132, v111, v130
	ds_write2st64_b32 v139, v131, v132 offset0:30 offset1:31
	v_mul_f32_e32 v131, v80, v130
	v_mul_f32_e32 v132, v81, v130
	ds_write2st64_b32 v139, v131, v132 offset0:32 offset1:33
	v_mul_f32_e32 v131, v82, v130
	v_mul_f32_e32 v132, v83, v130
	ds_write2st64_b32 v139, v131, v132 offset0:34 offset1:35
	v_mul_f32_e32 v131, v84, v130
	v_mul_f32_e32 v132, v85, v130
	ds_write2st64_b32 v139, v131, v132 offset0:36 offset1:37
	v_mul_f32_e32 v131, v86, v130
	v_mul_f32_e32 v132, v87, v130
	ds_write2st64_b32 v139, v131, v132 offset0:38 offset1:39
	v_mul_f32_e32 v131, v88, v130
	v_mul_f32_e32 v132, v89, v130
	ds_write2st64_b32 v139, v131, v132 offset0:40 offset1:41
	v_mul_f32_e32 v131, v90, v130
	v_mul_f32_e32 v132, v91, v130
	ds_write2st64_b32 v139, v131, v132 offset0:42 offset1:43
	v_mul_f32_e32 v131, v92, v130
	v_mul_f32_e32 v132, v93, v130
	ds_write2st64_b32 v139, v131, v132 offset0:44 offset1:45
	v_mul_f32_e32 v131, v94, v130
	v_mul_f32_e32 v132, v95, v130
	ds_write2st64_b32 v139, v131, v132 offset0:46 offset1:47
	v_mul_f32_e32 v131, v64, v130
	v_mul_f32_e32 v132, v65, v130
	ds_write2st64_b32 v139, v131, v132 offset0:48 offset1:49
	v_mul_f32_e32 v131, v66, v130
	v_mul_f32_e32 v132, v67, v130
	ds_write2st64_b32 v139, v131, v132 offset0:50 offset1:51
	v_mul_f32_e32 v131, v68, v130
	v_mul_f32_e32 v132, v69, v130
	ds_write2st64_b32 v139, v131, v132 offset0:52 offset1:53
	v_mul_f32_e32 v131, v70, v130
	v_mul_f32_e32 v132, v71, v130
	ds_write2st64_b32 v139, v131, v132 offset0:54 offset1:55
	v_mul_f32_e32 v131, v72, v130
	v_mul_f32_e32 v132, v73, v130
	ds_write2st64_b32 v139, v131, v132 offset0:56 offset1:57
	v_mul_f32_e32 v131, v74, v130
	v_mul_f32_e32 v132, v75, v130
	ds_write2st64_b32 v139, v131, v132 offset0:58 offset1:59
	v_mul_f32_e32 v131, v76, v130
	v_mul_f32_e32 v132, v77, v130
	ds_write2st64_b32 v139, v131, v132 offset0:60 offset1:61
	v_mul_f32_e32 v131, v78, v130
	v_mul_f32_e32 v130, v79, v130
	ds_write2st64_b32 v139, v131, v130 offset0:62 offset1:63
	v_mul_f32_e32 v130, v133, v168
	v_mul_f32_e32 v131, v48, v130
	v_mul_f32_e32 v132, v49, v130
	ds_write2st64_b32 v254, v131, v132 offset1:1
	v_mul_f32_e32 v131, v50, v130
	v_mul_f32_e32 v132, v51, v130
	ds_write2st64_b32 v254, v131, v132 offset0:2 offset1:3
	v_mul_f32_e32 v131, v52, v130
	v_mul_f32_e32 v132, v53, v130
	ds_write2st64_b32 v254, v131, v132 offset0:4 offset1:5
	v_mul_f32_e32 v131, v54, v130
	v_mul_f32_e32 v132, v55, v130
	ds_write2st64_b32 v254, v131, v132 offset0:6 offset1:7
	v_mul_f32_e32 v131, v56, v130
	v_mul_f32_e32 v132, v57, v130
	ds_write2st64_b32 v254, v131, v132 offset0:8 offset1:9
	v_mul_f32_e32 v131, v58, v130
	v_mul_f32_e32 v132, v59, v130
	ds_write2st64_b32 v254, v131, v132 offset0:10 offset1:11
	v_mul_f32_e32 v131, v60, v130
	v_mul_f32_e32 v132, v61, v130
	ds_write2st64_b32 v254, v131, v132 offset0:12 offset1:13
	v_mul_f32_e32 v131, v62, v130
	v_mul_f32_e32 v132, v63, v130
	ds_write2st64_b32 v254, v131, v132 offset0:14 offset1:15
	v_mul_f32_e32 v131, v32, v130
	v_mul_f32_e32 v132, v33, v130
	ds_write2st64_b32 v254, v131, v132 offset0:16 offset1:17
	v_mul_f32_e32 v131, v34, v130
	v_mul_f32_e32 v132, v35, v130
	ds_write2st64_b32 v254, v131, v132 offset0:18 offset1:19
	v_mul_f32_e32 v131, v36, v130
	v_mul_f32_e32 v132, v37, v130
	ds_write2st64_b32 v254, v131, v132 offset0:20 offset1:21
	v_mul_f32_e32 v131, v38, v130
	v_mul_f32_e32 v132, v39, v130
	ds_write2st64_b32 v254, v131, v132 offset0:22 offset1:23
	v_mul_f32_e32 v131, v40, v130
	v_mul_f32_e32 v132, v41, v130
	ds_write2st64_b32 v254, v131, v132 offset0:24 offset1:25
	v_mul_f32_e32 v131, v42, v130
	v_mul_f32_e32 v132, v43, v130
	ds_write2st64_b32 v254, v131, v132 offset0:26 offset1:27
	v_mul_f32_e32 v131, v44, v130
	v_mul_f32_e32 v132, v45, v130
	ds_write2st64_b32 v254, v131, v132 offset0:28 offset1:29
	v_mul_f32_e32 v131, v46, v130
	v_mul_f32_e32 v132, v47, v130
	ds_write2st64_b32 v254, v131, v132 offset0:30 offset1:31
	v_mul_f32_e32 v131, v16, v130
	v_mul_f32_e32 v132, v17, v130
	ds_write2st64_b32 v254, v131, v132 offset0:32 offset1:33
	v_mul_f32_e32 v131, v18, v130
	v_mul_f32_e32 v132, v19, v130
	ds_write2st64_b32 v254, v131, v132 offset0:34 offset1:35
	v_mul_f32_e32 v131, v20, v130
	v_mul_f32_e32 v132, v21, v130
	ds_write2st64_b32 v254, v131, v132 offset0:36 offset1:37
	v_mul_f32_e32 v131, v22, v130
	v_mul_f32_e32 v132, v23, v130
	ds_write2st64_b32 v254, v131, v132 offset0:38 offset1:39
	v_mul_f32_e32 v131, v24, v130
	v_mul_f32_e32 v132, v25, v130
	ds_write2st64_b32 v254, v131, v132 offset0:40 offset1:41
	v_mul_f32_e32 v131, v26, v130
	v_mul_f32_e32 v132, v27, v130
	ds_write2st64_b32 v254, v131, v132 offset0:42 offset1:43
	v_mul_f32_e32 v131, v28, v130
	v_mul_f32_e32 v132, v29, v130
	ds_write2st64_b32 v254, v131, v132 offset0:44 offset1:45
	v_mul_f32_e32 v131, v30, v130
	v_mul_f32_e32 v132, v31, v130
	ds_write2st64_b32 v254, v131, v132 offset0:46 offset1:47
	v_mul_f32_e32 v131, v0, v130
	v_mul_f32_e32 v132, v1, v130
	ds_write2st64_b32 v254, v131, v132 offset0:48 offset1:49
	v_mul_f32_e32 v131, v2, v130
	v_mul_f32_e32 v132, v3, v130
	ds_write2st64_b32 v254, v131, v132 offset0:50 offset1:51
	v_mul_f32_e32 v131, v4, v130
	v_mul_f32_e32 v132, v5, v130
	ds_write2st64_b32 v254, v131, v132 offset0:52 offset1:53
	v_mul_f32_e32 v131, v6, v130
	v_mul_f32_e32 v132, v7, v130
	ds_write2st64_b32 v254, v131, v132 offset0:54 offset1:55
	v_mul_f32_e32 v131, v8, v130
	v_mul_f32_e32 v132, v9, v130
	ds_write2st64_b32 v254, v131, v132 offset0:56 offset1:57
	v_mul_f32_e32 v131, v10, v130
	v_mul_f32_e32 v132, v11, v130
	ds_write2st64_b32 v254, v131, v132 offset0:58 offset1:59
	v_mul_f32_e32 v131, v12, v130
	v_mul_f32_e32 v132, v13, v130
	ds_write2st64_b32 v254, v131, v132 offset0:60 offset1:61
	v_mul_f32_e32 v131, v14, v130
	v_mul_f32_e32 v130, v15, v130
	ds_write2st64_b32 v254, v131, v130 offset0:62 offset1:63
